# comb16 + epilogue de-serialisation: Q/K projection epilogues issue their 8 row-statistics loads together (one round trip instead of 8); attention unit prologue waits for the tile-1 K DMA at its second
# speedup vs baseline: 1.0001x; 1.0001x over previous
;     __device__ __forceinline__ void operator()(const Acc& acc, const Unit& u, int wr, int wc, int fr, int fq) const {
;     ...
;             for (int m = 0; m < 4; ++m) { const int row = u.pm * 256 + ai * 128 + wr * 64 + m * 16 + fr; const size_t R = (size_t)u.pb * NT + row;
;                 const f32x4 sa = *(const f32x4*)(stats + R * 8 + (ISQ ? 0 : 4));
;                 float rr = rsqrtf(((sa[0] + sa[1]) + (sa[2] + sa[3])) * (ISQ ? (1.f / 256.f) : (1.f / 128.f)) + EPS); if (ISQ) rr *= QSCALE;
; #pragma unroll
;                 for (int bj = 0; bj < 2; ++bj) { const int cg_ = u.pn * 256 + bj * 128 + wc * 32; const int h = cg_ / 192, d0 = cg_ - h * 192;
;                     f32x4 a = acc[ai][bj][m][0], b = acc[ai][bj][m][1];
;                     if (d0 < 128) { a = a * rr; b = b * rr; }
;                     else { if (ISQ) { a = a * rr; b = b * rr; }
;                         f32x4 pa, pb;
; #pragma unroll
;                         for (int i = 0; i < 4; ++i) { pa[i] = __shfl_xor(a[i], 32); pb[i] = __shfl_xor(b[i], 32); }
;                         if (row < TL) { const int ti = row * 32 + ((d0 - 128) >> 5) * 16 + 8 * (fq & 1); const float sg = fq < 2 ? -1.f : 1.f;
;                             const f32x4 c0 = *(const f32x4*)(cosT + ti), c1 = *(const f32x4*)(cosT + ti + 4), s0 = *(const f32x4*)(sinT + ti) * sg, s1 = *(const f32x4*)(sinT + ti + 4) * sg;
;                             a = a * c0 + pa * s0; b = b * c1 + pb * s1; } }
.LBB0_393:
	v_mov_b32_e32 v144, v158
	s_lshl_b32 s38, s97, 8
	v_and_or_b32 v167, v144, 15, s83
	v_add_u32_e32 v146, s38, v167
	v_ashrrev_i32_e32 v147, 31, v146
	v_mad_i64_i32 v[142:143], s[4:5], s95, v164, v[146:147]
	v_lshlrev_b64 v[142:143], 5, v[142:143]
	v_lshl_add_u64 v[142:143], s[12:13], 0, v[142:143]
	v_mov_b64_e32 v[218:219], v[142:143]
	global_load_dwordx4 v[148:151], v[142:143], off
	s_mov_b32 s98, 0x1000
	s_mov_b32 s99, 0
	global_load_dwordx4 v[188:191], v[218:219], off offset:512
	global_load_dwordx4 v[192:195], v[218:219], off offset:1024
	global_load_dwordx4 v[196:199], v[218:219], off offset:1536
	v_lshl_add_u64 v[216:217], v[218:219], 0, s[98:99]
	global_load_dwordx4 v[200:203], v[216:217], off
	global_load_dwordx4 v[204:207], v[216:217], off offset:512
	global_load_dwordx4 v[208:211], v[216:217], off offset:1024
	global_load_dwordx4 v[212:215], v[216:217], off offset:1536
	s_lshl_b32 s4, s96, 8
	s_or_b32 s6, s4, s84
	s_mul_hi_i32 s4, s6, 0x2aaaaaab
	v_ashrrev_i32_e32 v143, 4, v144
	s_lshr_b32 s5, s4, 31
	s_ashr_i32 s8, s4, 5
	v_lshlrev_b32_e32 v142, 3, v143
	v_cmp_gt_i32_e32 vcc, 2, v143
	s_add_i32 s8, s8, s5
	s_mul_i32 s4, s8, 0xffffff40
	s_add_i32 s54, s4, s6
	v_cndmask_b32_e64 v144, 1.0, -1.0, vcc
	v_and_b32_e32 v166, 8, v142
	s_cmpk_gt_i32 s54, 0x7f
	v_mov_b32_e32 v145, v144
	v_cmp_gt_i32_e32 vcc, s90, v146
	v_lshl_or_b32 v168, v146, 5, v166
	s_cselect_b64 s[10:11], -1, 0
	s_cmpk_lt_i32 s54, 0x80
	s_waitcnt vmcnt(0)
	v_mov_b32_e32 v152, v149
	v_mov_b32_e32 v153, v150
	v_mov_b32_e32 v149, v151
	v_pk_add_f32 v[148:149], v[152:153], v[148:149]
	s_nop 0
	v_add_f32_e32 v143, v148, v149
	v_fmamk_f32 v143, v143, 0x3b800000, v163
	v_mul_f32_e32 v148, 0x4b800000, v143
	v_cmp_gt_f32_e64 s[4:5], s89, v143
	s_nop 1
	v_cndmask_b32_e64 v143, v143, v148, s[4:5]
	v_rsq_f32_e32 v143, v143
	s_nop 0
	v_mul_f32_e32 v148, 0x45800000, v143
	v_cndmask_b32_e64 v143, v143, v148, s[4:5]
	v_mul_f32_e32 v148, 0x3dd53b94, v143
	v_pk_mul_f32 v[128:129], v[128:129], v[148:149] op_sel_hi:[1,0]
	v_pk_mul_f32 v[126:127], v[126:127], v[148:149] op_sel_hi:[1,0]
	v_pk_mul_f32 v[124:125], v[124:125], v[148:149] op_sel_hi:[1,0]
	v_pk_mul_f32 v[122:123], v[122:123], v[148:149] op_sel_hi:[1,0]
	s_cbranch_scc1 .LBB0_397
	v_and_b32_e32 v149, 64, v165
	v_xor_b32_e32 v143, 32, v165
	v_add_u32_e32 v149, 64, v149
	v_cmp_lt_i32_e64 s[4:5], v143, v149
	s_nop 1
	v_cndmask_b32_e64 v143, v165, v143, s[4:5]
	v_lshlrev_b32_e32 v143, 2, v143
	ds_bpermute_b32 v154, v143, v126
	ds_bpermute_b32 v150, v143, v122
	ds_bpermute_b32 v155, v143, v127
	ds_bpermute_b32 v151, v143, v123
	ds_bpermute_b32 v156, v143, v128
	ds_bpermute_b32 v152, v143, v124
	ds_bpermute_b32 v157, v143, v129
	ds_bpermute_b32 v153, v143, v125
	s_and_saveexec_b64 s[4:5], vcc
	s_cbranch_execz .LBB0_396
	s_add_i32 s7, s54, 0xffffff80
	s_lshr_b32 s7, s7, 1
	v_add_u32_e32 v170, s7, v168
	v_ashrrev_i32_e32 v171, 31, v170
	v_lshlrev_b64 v[178:179], 2, v[170:171]
	v_lshl_add_u64 v[174:175], s[18:19], 0, v[178:179]
	global_load_dwordx4 v[170:173], v[174:175], off
	s_nop 0
	global_load_dwordx4 v[174:177], v[174:175], off offset:16
	v_lshl_add_u64 v[182:183], s[16:17], 0, v[178:179]
	global_load_dwordx4 v[178:181], v[182:183], off
	s_nop 0
	global_load_dwordx4 v[182:185], v[182:183], off offset:16
	v_mov_b32_e32 v186, v144
	v_mov_b32_e32 v187, v144
	s_waitcnt vmcnt(3)
	v_pk_mul_f32 v[172:173], v[186:187], v[172:173]
	v_pk_mul_f32 v[170:171], v[144:145], v[170:171]
	s_waitcnt vmcnt(2)
	v_pk_mul_f32 v[176:177], v[186:187], v[176:177]
	v_pk_mul_f32 v[174:175], v[144:145], v[174:175]
	s_waitcnt lgkmcnt(1)
	v_pk_mul_f32 v[156:157], v[172:173], v[156:157]
	v_pk_mul_f32 v[154:155], v[170:171], v[154:155]
	s_waitcnt lgkmcnt(0)
	v_pk_mul_f32 v[152:153], v[176:177], v[152:153]
	v_pk_mul_f32 v[150:151], v[174:175], v[150:151]
	s_waitcnt vmcnt(1)
	v_pk_fma_f32 v[128:129], v[128:129], v[180:181], v[156:157]
	v_pk_fma_f32 v[126:127], v[126:127], v[178:179], v[154:155]
	s_waitcnt vmcnt(0)
	v_pk_fma_f32 v[124:125], v[124:125], v[184:185], v[152:153]
	v_pk_fma_f32 v[122:123], v[122:123], v[182:183], v[150:151]

; __device__ __forceinline__ unsigned cvt_pk(float lo, float hi) { unsigned r; asm volatile("v_cvt_pk_bf16_f32 %0, %1, %2" : "=v"(r) : "v"(lo), "v"(hi)); return r; }
;     __device__ __forceinline__ void operator()(const Acc& acc, const Unit& u, int wr, int wc, int fr, int fq) const {
;     ...
;             for (int m = 0; m < 4; ++m) { const int row = u.pm * 256 + ai * 128 + wr * 64 + m * 16 + fr; const size_t R = (size_t)u.pb * NT + row;
;                 const f32x4 sa = *(const f32x4*)(stats + R * 8 + (ISQ ? 0 : 4));
;                 float rr = rsqrtf(((sa[0] + sa[1]) + (sa[2] + sa[3])) * (ISQ ? (1.f / 256.f) : (1.f / 128.f)) + EPS); if (ISQ) rr *= QSCALE;
; #pragma unroll
;                 for (int bj = 0; bj < 2; ++bj) { const int cg_ = u.pn * 256 + bj * 128 + wc * 32; const int h = cg_ / 192, d0 = cg_ - h * 192;
;                     f32x4 a = acc[ai][bj][m][0], b = acc[ai][bj][m][1];
;                     if (d0 < 128) { a = a * rr; b = b * rr; }
;                     else { if (ISQ) { a = a * rr; b = b * rr; }
;                         f32x4 pa, pb;
; #pragma unroll
;                         for (int i = 0; i < 4; ++i) { pa[i] = __shfl_xor(a[i], 32); pb[i] = __shfl_xor(b[i], 32); }
;                         if (row < TL) { const int ti = row * 32 + ((d0 - 128) >> 5) * 16 + 8 * (fq & 1); const float sg = fq < 2 ? -1.f : 1.f;
;                             const f32x4 c0 = *(const f32x4*)(cosT + ti), c1 = *(const f32x4*)(cosT + ti + 4), s0 = *(const f32x4*)(sinT + ti) * sg, s1 = *(const f32x4*)(sinT + ti + 4) * sg;
;                             a = a * c0 + pa * s0; b = b * c1 + pb * s1; } }
;                     bf16_t* dst = O + ((size_t)(u.pb * 4 + h) * NT + row) * pitch + d0 + 8 * fq;
;                     u32x4 w; w.x = cvt_pk(a[0], a[1]); w.y = cvt_pk(a[2], a[3]); w.z = cvt_pk(b[0], b[1]); w.w = cvt_pk(b[2], b[3]); *(u32x4*)dst = w; } }
.LBB0_401:
	s_mul_hi_i32 s59, s95, 0x900
	s_mul_i32 s58, s95, 0x900
	s_add_i32 s95, s6, s7
	s_waitcnt lgkmcnt(4)
	v_mad_i64_i32 v[122:123], s[4:5], s95, v164, v[146:147]
	s_waitcnt lgkmcnt(0)
	v_mov_b64_e32 v[124:125], s[22:23]
	v_mad_u64_u32 v[124:125], s[4:5], v122, s91, v[124:125]
	v_cvt_pk_bf16_f32 v118, v118, v119
	v_cvt_pk_bf16_f32 v119, v120, v121
	v_cvt_pk_bf16_f32 v120, v114, v115
	v_add3_u32 v114, s38, v167, 16
	v_mad_i32_i24 v125, v123, s91, v125
	s_ashr_i32 s57, s56, 31
	v_ashrrev_i32_e32 v115, 31, v114
	v_lshl_add_u64 v[122:123], s[56:57], 1, v[124:125]
	v_cvt_pk_bf16_f32 v121, v116, v117
	v_lshl_add_u64 v[116:117], s[58:59], 0, v[114:115]
	v_lshl_add_u64 v[122:123], v[142:143], 1, v[122:123]
	v_lshlrev_b64 v[116:117], 5, v[116:117]
	global_store_dwordx4 v[122:123], v[118:121], off
	v_lshl_add_u64 v[116:117], s[12:13], 0, v[116:117]
	v_mov_b64_e32 v[116:117], v[188:189]
	v_mov_b64_e32 v[118:119], v[190:191]
	v_cndmask_b32_e64 v122, 0, 1, s[10:11]
	v_cmp_gt_i32_e64 s[8:9], s90, v114
	v_lshl_or_b32 v126, v114, 5, v166
	v_cmp_ne_u32_e64 s[4:5], 1, v122
	s_andn2_b64 vcc, exec, s[10:11]
	s_waitcnt vmcnt(0)
	v_mov_b32_e32 v120, v117
	v_mov_b32_e32 v121, v118
	v_mov_b32_e32 v117, v119
	v_pk_add_f32 v[116:117], v[120:121], v[116:117]
	s_nop 0
	v_add_f32_e32 v116, v116, v117
	v_fmamk_f32 v116, v116, 0x3b800000, v163
	v_mul_f32_e32 v117, 0x4b800000, v116
	v_cmp_gt_f32_e64 s[6:7], s89, v116
	s_nop 1
	v_cndmask_b32_e64 v116, v116, v117, s[6:7]
	v_rsq_f32_e32 v116, v116
	s_nop 0
	v_mul_f32_e32 v117, 0x45800000, v116
	v_cndmask_b32_e64 v116, v116, v117, s[6:7]
	v_mul_f32_e32 v116, 0x3dd53b94, v116
	v_pk_mul_f32 v[112:113], v[112:113], v[116:117] op_sel_hi:[1,0]
	v_pk_mul_f32 v[110:111], v[110:111], v[116:117] op_sel_hi:[1,0]
	v_pk_mul_f32 v[108:109], v[108:109], v[116:117] op_sel_hi:[1,0]
	v_pk_mul_f32 v[106:107], v[106:107], v[116:117] op_sel_hi:[1,0]
	s_cbranch_vccnz .LBB0_405
	v_and_b32_e32 v118, 64, v165
	v_xor_b32_e32 v117, 32, v165
	v_add_u32_e32 v118, 64, v118
	v_cmp_lt_i32_e32 vcc, v117, v118
	s_nop 1
	v_cndmask_b32_e32 v117, v165, v117, vcc
	v_lshlrev_b32_e32 v117, 2, v117
	ds_bpermute_b32 v122, v117, v110
	ds_bpermute_b32 v118, v117, v106
	ds_bpermute_b32 v123, v117, v111
	ds_bpermute_b32 v119, v117, v107
	ds_bpermute_b32 v124, v117, v112
	ds_bpermute_b32 v120, v117, v108
	ds_bpermute_b32 v125, v117, v113
	ds_bpermute_b32 v121, v117, v109
	s_and_saveexec_b64 s[6:7], s[8:9]
	s_cbranch_execz .LBB0_404
	s_add_i32 s10, s54, 0xffffff80
	s_lshr_b32 s10, s10, 1
	v_add_u32_e32 v128, s10, v126
	v_ashrrev_i32_e32 v129, 31, v128
	v_lshlrev_b64 v[128:129], 2, v[128:129]
	v_lshl_add_u64 v[152:153], s[18:19], 0, v[128:129]
	global_load_dwordx4 v[148:151], v[152:153], off
	s_nop 0
	global_load_dwordx4 v[152:155], v[152:153], off offset:16
	v_lshl_add_u64 v[128:129], s[16:17], 0, v[128:129]
	global_load_dwordx4 v[168:171], v[128:129], off
	global_load_dwordx4 v[172:175], v[128:129], off offset:16
	v_mov_b32_e32 v128, v144
	v_mov_b32_e32 v129, v144
	s_waitcnt vmcnt(3)
	v_pk_mul_f32 v[150:151], v[128:129], v[150:151]
	v_pk_mul_f32 v[148:149], v[144:145], v[148:149]
	s_waitcnt vmcnt(2)
	v_pk_mul_f32 v[128:129], v[128:129], v[154:155]
	v_pk_mul_f32 v[152:153], v[144:145], v[152:153]
	s_waitcnt lgkmcnt(1)
	v_pk_mul_f32 v[124:125], v[150:151], v[124:125]
	v_pk_mul_f32 v[122:123], v[148:149], v[122:123]
	s_waitcnt lgkmcnt(0)
	v_pk_mul_f32 v[120:121], v[128:129], v[120:121]
	v_pk_mul_f32 v[118:119], v[152:153], v[118:119]
	s_waitcnt vmcnt(1)
	v_pk_fma_f32 v[112:113], v[112:113], v[170:171], v[124:125]
	v_pk_fma_f32 v[110:111], v[110:111], v[168:169], v[122:123]
	s_waitcnt vmcnt(0)
	v_pk_fma_f32 v[108:109], v[108:109], v[174:175], v[120:121]
	v_pk_fma_f32 v[106:107], v[106:107], v[172:173], v[118:119]

; __device__ __forceinline__ unsigned cvt_pk(float lo, float hi) { unsigned r; asm volatile("v_cvt_pk_bf16_f32 %0, %1, %2" : "=v"(r) : "v"(lo), "v"(hi)); return r; }
;     __device__ __forceinline__ void operator()(const Acc& acc, const Unit& u, int wr, int wc, int fr, int fq) const {
;     ...
;             for (int m = 0; m < 4; ++m) { const int row = u.pm * 256 + ai * 128 + wr * 64 + m * 16 + fr; const size_t R = (size_t)u.pb * NT + row;
;                 const f32x4 sa = *(const f32x4*)(stats + R * 8 + (ISQ ? 0 : 4));
;                 float rr = rsqrtf(((sa[0] + sa[1]) + (sa[2] + sa[3])) * (ISQ ? (1.f / 256.f) : (1.f / 128.f)) + EPS); if (ISQ) rr *= QSCALE;
; #pragma unroll
;                 for (int bj = 0; bj < 2; ++bj) { const int cg_ = u.pn * 256 + bj * 128 + wc * 32; const int h = cg_ / 192, d0 = cg_ - h * 192;
;                     f32x4 a = acc[ai][bj][m][0], b = acc[ai][bj][m][1];
;                     if (d0 < 128) { a = a * rr; b = b * rr; }
;                     else { if (ISQ) { a = a * rr; b = b * rr; }
;                         f32x4 pa, pb;
; #pragma unroll
;                         for (int i = 0; i < 4; ++i) { pa[i] = __shfl_xor(a[i], 32); pb[i] = __shfl_xor(b[i], 32); }
;                         if (row < TL) { const int ti = row * 32 + ((d0 - 128) >> 5) * 16 + 8 * (fq & 1); const float sg = fq < 2 ? -1.f : 1.f;
;                             const f32x4 c0 = *(const f32x4*)(cosT + ti), c1 = *(const f32x4*)(cosT + ti + 4), s0 = *(const f32x4*)(sinT + ti) * sg, s1 = *(const f32x4*)(sinT + ti + 4) * sg;
;                             a = a * c0 + pa * s0; b = b * c1 + pb * s1; } }
;                     bf16_t* dst = O + ((size_t)(u.pb * 4 + h) * NT + row) * pitch + d0 + 8 * fq;
;                     u32x4 w; w.x = cvt_pk(a[0], a[1]); w.y = cvt_pk(a[2], a[3]); w.z = cvt_pk(b[0], b[1]); w.w = cvt_pk(b[2], b[3]); *(u32x4*)dst = w; } }
.LBB0_409:
	s_mul_hi_i32 s67, s95, 0x900
	s_mul_i32 s66, s95, 0x900
	s_waitcnt lgkmcnt(4)
	v_lshl_add_u64 v[106:107], s[66:67], 0, v[114:115]
	s_waitcnt lgkmcnt(0)
	v_mov_b64_e32 v[108:109], s[22:23]
	v_mad_u64_u32 v[108:109], s[8:9], v106, s91, v[108:109]
	v_mov_b32_e32 v106, v109
	v_mad_u64_u32 v[106:107], s[8:9], v107, s91, v[106:107]
	v_cvt_pk_bf16_f32 v102, v102, v103
	v_cvt_pk_bf16_f32 v103, v104, v105
	v_cvt_pk_bf16_f32 v104, v98, v99
	v_add3_u32 v98, s38, v167, 32
	v_mov_b32_e32 v109, v106
	v_ashrrev_i32_e32 v99, 31, v98
	v_lshl_add_u64 v[106:107], s[56:57], 1, v[108:109]
	v_cvt_pk_bf16_f32 v105, v100, v101
	v_lshl_add_u64 v[100:101], s[58:59], 0, v[98:99]
	v_lshl_add_u64 v[106:107], v[142:143], 1, v[106:107]
	v_lshlrev_b64 v[100:101], 5, v[100:101]
	global_store_dwordx4 v[106:107], v[102:105], off
	v_lshl_add_u64 v[100:101], s[12:13], 0, v[100:101]
	v_mov_b64_e32 v[100:101], v[192:193]
	v_mov_b64_e32 v[102:103], v[194:195]
	s_and_b64 vcc, exec, s[4:5]
	v_cmp_gt_i32_e64 s[8:9], s90, v98
	v_lshl_or_b32 v110, v98, 5, v166
	s_waitcnt vmcnt(0)
	v_mov_b32_e32 v104, v101
	v_mov_b32_e32 v105, v102
	v_mov_b32_e32 v101, v103
	v_pk_add_f32 v[100:101], v[104:105], v[100:101]
	s_nop 0
	v_add_f32_e32 v100, v100, v101
	v_fmamk_f32 v100, v100, 0x3b800000, v163
	v_mul_f32_e32 v101, 0x4b800000, v100
	v_cmp_gt_f32_e64 s[10:11], s89, v100
	s_nop 1
	v_cndmask_b32_e64 v100, v100, v101, s[10:11]
	v_rsq_f32_e32 v100, v100
	s_nop 0
	v_mul_f32_e32 v101, 0x45800000, v100
	v_cndmask_b32_e64 v100, v100, v101, s[10:11]
	v_mul_f32_e32 v100, 0x3dd53b94, v100
	v_pk_mul_f32 v[96:97], v[96:97], v[100:101] op_sel_hi:[1,0]
	v_pk_mul_f32 v[94:95], v[94:95], v[100:101] op_sel_hi:[1,0]
	v_pk_mul_f32 v[92:93], v[92:93], v[100:101] op_sel_hi:[1,0]
	v_pk_mul_f32 v[90:91], v[90:91], v[100:101] op_sel_hi:[1,0]
	s_cbranch_vccnz .LBB0_413
	v_and_b32_e32 v102, 64, v165
	v_xor_b32_e32 v101, 32, v165
	v_add_u32_e32 v102, 64, v102
	v_cmp_lt_i32_e32 vcc, v101, v102
	s_nop 1
	v_cndmask_b32_e32 v101, v165, v101, vcc
	v_lshlrev_b32_e32 v101, 2, v101
	ds_bpermute_b32 v106, v101, v94
	ds_bpermute_b32 v102, v101, v90
	ds_bpermute_b32 v107, v101, v95
	ds_bpermute_b32 v103, v101, v91
	ds_bpermute_b32 v108, v101, v96
	ds_bpermute_b32 v104, v101, v92
	ds_bpermute_b32 v109, v101, v97
	ds_bpermute_b32 v105, v101, v93
	s_and_saveexec_b64 s[10:11], s[8:9]
	s_cbranch_execz .LBB0_412
	s_add_i32 s33, s54, 0xffffff80
	s_lshr_b32 s33, s33, 1
	v_add_u32_e32 v112, s33, v110
	v_ashrrev_i32_e32 v113, 31, v112
	v_lshlrev_b64 v[120:121], 2, v[112:113]
	v_lshl_add_u64 v[116:117], s[18:19], 0, v[120:121]
	global_load_dwordx4 v[112:115], v[116:117], off
	s_nop 0
	global_load_dwordx4 v[116:119], v[116:117], off offset:16
	v_lshl_add_u64 v[124:125], s[16:17], 0, v[120:121]
	global_load_dwordx4 v[120:123], v[124:125], off
	s_nop 0
	global_load_dwordx4 v[124:127], v[124:125], off offset:16
	v_mov_b32_e32 v128, v144
	v_mov_b32_e32 v129, v144
	s_waitcnt vmcnt(3)
	v_pk_mul_f32 v[114:115], v[128:129], v[114:115]
	v_pk_mul_f32 v[112:113], v[144:145], v[112:113]
	s_waitcnt vmcnt(2)
	v_pk_mul_f32 v[118:119], v[128:129], v[118:119]
	v_pk_mul_f32 v[116:117], v[144:145], v[116:117]
	s_waitcnt lgkmcnt(1)
	v_pk_mul_f32 v[108:109], v[114:115], v[108:109]
	v_pk_mul_f32 v[106:107], v[112:113], v[106:107]
	s_waitcnt lgkmcnt(0)
	v_pk_mul_f32 v[104:105], v[118:119], v[104:105]
	v_pk_mul_f32 v[102:103], v[116:117], v[102:103]
	s_waitcnt vmcnt(1)
	v_pk_fma_f32 v[96:97], v[96:97], v[122:123], v[108:109]
	v_pk_fma_f32 v[94:95], v[94:95], v[120:121], v[106:107]
	s_waitcnt vmcnt(0)
	v_pk_fma_f32 v[92:93], v[92:93], v[126:127], v[104:105]
	v_pk_fma_f32 v[90:91], v[90:91], v[124:125], v[102:103]

; __device__ __forceinline__ unsigned cvt_pk(float lo, float hi) { unsigned r; asm volatile("v_cvt_pk_bf16_f32 %0, %1, %2" : "=v"(r) : "v"(lo), "v"(hi)); return r; }
;     __device__ __forceinline__ void operator()(const Acc& acc, const Unit& u, int wr, int wc, int fr, int fq) const {
;     ...
;             for (int m = 0; m < 4; ++m) { const int row = u.pm * 256 + ai * 128 + wr * 64 + m * 16 + fr; const size_t R = (size_t)u.pb * NT + row;
;                 const f32x4 sa = *(const f32x4*)(stats + R * 8 + (ISQ ? 0 : 4));
;                 float rr = rsqrtf(((sa[0] + sa[1]) + (sa[2] + sa[3])) * (ISQ ? (1.f / 256.f) : (1.f / 128.f)) + EPS); if (ISQ) rr *= QSCALE;
; #pragma unroll
;                 for (int bj = 0; bj < 2; ++bj) { const int cg_ = u.pn * 256 + bj * 128 + wc * 32; const int h = cg_ / 192, d0 = cg_ - h * 192;
;                     f32x4 a = acc[ai][bj][m][0], b = acc[ai][bj][m][1];
;                     if (d0 < 128) { a = a * rr; b = b * rr; }
;                     else { if (ISQ) { a = a * rr; b = b * rr; }
;                         f32x4 pa, pb;
; #pragma unroll
;                         for (int i = 0; i < 4; ++i) { pa[i] = __shfl_xor(a[i], 32); pb[i] = __shfl_xor(b[i], 32); }
;                         if (row < TL) { const int ti = row * 32 + ((d0 - 128) >> 5) * 16 + 8 * (fq & 1); const float sg = fq < 2 ? -1.f : 1.f;
;                             const f32x4 c0 = *(const f32x4*)(cosT + ti), c1 = *(const f32x4*)(cosT + ti + 4), s0 = *(const f32x4*)(sinT + ti) * sg, s1 = *(const f32x4*)(sinT + ti + 4) * sg;
;                             a = a * c0 + pa * s0; b = b * c1 + pb * s1; } }
;                     bf16_t* dst = O + ((size_t)(u.pb * 4 + h) * NT + row) * pitch + d0 + 8 * fq;
;                     u32x4 w; w.x = cvt_pk(a[0], a[1]); w.y = cvt_pk(a[2], a[3]); w.z = cvt_pk(b[0], b[1]); w.w = cvt_pk(b[2], b[3]); *(u32x4*)dst = w; } }
.LBB0_417:
	s_waitcnt lgkmcnt(4)
	v_lshl_add_u64 v[90:91], s[66:67], 0, v[98:99]
	s_waitcnt lgkmcnt(0)
	v_mov_b64_e32 v[92:93], s[22:23]
	v_mad_u64_u32 v[92:93], s[8:9], v90, s91, v[92:93]
	v_mov_b32_e32 v90, v93
	v_mad_u64_u32 v[90:91], s[8:9], v91, s91, v[90:91]
	v_cvt_pk_bf16_f32 v86, v86, v87
	v_cvt_pk_bf16_f32 v87, v88, v89
	v_cvt_pk_bf16_f32 v88, v82, v83
	v_add3_u32 v82, s38, v167, 48
	v_mov_b32_e32 v93, v90
	v_ashrrev_i32_e32 v83, 31, v82
	v_lshl_add_u64 v[90:91], s[56:57], 1, v[92:93]
	v_cvt_pk_bf16_f32 v89, v84, v85
	v_lshl_add_u64 v[84:85], s[58:59], 0, v[82:83]
	v_lshl_add_u64 v[90:91], v[142:143], 1, v[90:91]
	v_lshlrev_b64 v[84:85], 5, v[84:85]
	global_store_dwordx4 v[90:91], v[86:89], off
	v_lshl_add_u64 v[84:85], s[12:13], 0, v[84:85]
	v_mov_b64_e32 v[84:85], v[196:197]
	v_mov_b64_e32 v[86:87], v[198:199]
	s_and_b64 vcc, exec, s[4:5]
	v_cmp_gt_i32_e64 s[8:9], s90, v82
	v_lshl_or_b32 v94, v82, 5, v166
	s_waitcnt vmcnt(0)
	v_mov_b32_e32 v88, v85
	v_mov_b32_e32 v89, v86
	v_mov_b32_e32 v85, v87
	v_pk_add_f32 v[84:85], v[88:89], v[84:85]
	s_nop 0
	v_add_f32_e32 v84, v84, v85
	v_fmamk_f32 v84, v84, 0x3b800000, v163
	v_mul_f32_e32 v85, 0x4b800000, v84
	v_cmp_gt_f32_e64 s[10:11], s89, v84
	s_nop 1
	v_cndmask_b32_e64 v84, v84, v85, s[10:11]
	v_rsq_f32_e32 v84, v84
	s_nop 0
	v_mul_f32_e32 v85, 0x45800000, v84
	v_cndmask_b32_e64 v84, v84, v85, s[10:11]
	v_mul_f32_e32 v84, 0x3dd53b94, v84
	v_pk_mul_f32 v[80:81], v[80:81], v[84:85] op_sel_hi:[1,0]
	v_pk_mul_f32 v[78:79], v[78:79], v[84:85] op_sel_hi:[1,0]
	v_pk_mul_f32 v[76:77], v[76:77], v[84:85] op_sel_hi:[1,0]
	v_pk_mul_f32 v[74:75], v[74:75], v[84:85] op_sel_hi:[1,0]
	s_cbranch_vccnz .LBB0_421
	v_and_b32_e32 v86, 64, v165
	v_xor_b32_e32 v85, 32, v165
	v_add_u32_e32 v86, 64, v86
	v_cmp_lt_i32_e32 vcc, v85, v86
	s_nop 1
	v_cndmask_b32_e32 v85, v165, v85, vcc
	v_lshlrev_b32_e32 v85, 2, v85
	ds_bpermute_b32 v90, v85, v78
	ds_bpermute_b32 v86, v85, v74
	ds_bpermute_b32 v91, v85, v79
	ds_bpermute_b32 v87, v85, v75
	ds_bpermute_b32 v92, v85, v80
	ds_bpermute_b32 v88, v85, v76
	ds_bpermute_b32 v93, v85, v81
	ds_bpermute_b32 v89, v85, v77
	s_and_saveexec_b64 s[10:11], s[8:9]
	s_cbranch_execz .LBB0_420
	s_add_i32 s33, s54, 0xffffff80
	s_lshr_b32 s33, s33, 1
	v_add_u32_e32 v96, s33, v94
	v_ashrrev_i32_e32 v97, 31, v96
	v_lshlrev_b64 v[104:105], 2, v[96:97]
	v_lshl_add_u64 v[100:101], s[18:19], 0, v[104:105]
	global_load_dwordx4 v[96:99], v[100:101], off
	s_nop 0
	global_load_dwordx4 v[100:103], v[100:101], off offset:16
	v_lshl_add_u64 v[108:109], s[16:17], 0, v[104:105]
	global_load_dwordx4 v[104:107], v[108:109], off
	s_nop 0
	global_load_dwordx4 v[108:111], v[108:109], off offset:16
	v_mov_b32_e32 v112, v144
	v_mov_b32_e32 v113, v144
	s_waitcnt vmcnt(3)
	v_pk_mul_f32 v[98:99], v[112:113], v[98:99]
	v_pk_mul_f32 v[96:97], v[144:145], v[96:97]
	s_waitcnt vmcnt(2)
	v_pk_mul_f32 v[102:103], v[112:113], v[102:103]
	v_pk_mul_f32 v[100:101], v[144:145], v[100:101]
	s_waitcnt lgkmcnt(1)
	v_pk_mul_f32 v[92:93], v[98:99], v[92:93]
	v_pk_mul_f32 v[90:91], v[96:97], v[90:91]
	s_waitcnt lgkmcnt(0)
	v_pk_mul_f32 v[88:89], v[102:103], v[88:89]
	v_pk_mul_f32 v[86:87], v[100:101], v[86:87]
	s_waitcnt vmcnt(1)
	v_pk_fma_f32 v[80:81], v[80:81], v[106:107], v[92:93]
	v_pk_fma_f32 v[78:79], v[78:79], v[104:105], v[90:91]
	s_waitcnt vmcnt(0)
	v_pk_fma_f32 v[76:77], v[76:77], v[110:111], v[88:89]
	v_pk_fma_f32 v[74:75], v[74:75], v[108:109], v[86:87]

; __device__ __forceinline__ unsigned cvt_pk(float lo, float hi) { unsigned r; asm volatile("v_cvt_pk_bf16_f32 %0, %1, %2" : "=v"(r) : "v"(lo), "v"(hi)); return r; }
;     __device__ __forceinline__ void operator()(const Acc& acc, const Unit& u, int wr, int wc, int fr, int fq) const {
;     ...
;             for (int m = 0; m < 4; ++m) { const int row = u.pm * 256 + ai * 128 + wr * 64 + m * 16 + fr; const size_t R = (size_t)u.pb * NT + row;
;                 const f32x4 sa = *(const f32x4*)(stats + R * 8 + (ISQ ? 0 : 4));
;                 float rr = rsqrtf(((sa[0] + sa[1]) + (sa[2] + sa[3])) * (ISQ ? (1.f / 256.f) : (1.f / 128.f)) + EPS); if (ISQ) rr *= QSCALE;
; #pragma unroll
;                 for (int bj = 0; bj < 2; ++bj) { const int cg_ = u.pn * 256 + bj * 128 + wc * 32; const int h = cg_ / 192, d0 = cg_ - h * 192;
;                     f32x4 a = acc[ai][bj][m][0], b = acc[ai][bj][m][1];
;                     if (d0 < 128) { a = a * rr; b = b * rr; }
;                     else { if (ISQ) { a = a * rr; b = b * rr; }
;                         f32x4 pa, pb;
; #pragma unroll
;                         for (int i = 0; i < 4; ++i) { pa[i] = __shfl_xor(a[i], 32); pb[i] = __shfl_xor(b[i], 32); }
;                         if (row < TL) { const int ti = row * 32 + ((d0 - 128) >> 5) * 16 + 8 * (fq & 1); const float sg = fq < 2 ? -1.f : 1.f;
;                             const f32x4 c0 = *(const f32x4*)(cosT + ti), c1 = *(const f32x4*)(cosT + ti + 4), s0 = *(const f32x4*)(sinT + ti) * sg, s1 = *(const f32x4*)(sinT + ti + 4) * sg;
;                             a = a * c0 + pa * s0; b = b * c1 + pb * s1; } }
;                     bf16_t* dst = O + ((size_t)(u.pb * 4 + h) * NT + row) * pitch + d0 + 8 * fq;
;                     u32x4 w; w.x = cvt_pk(a[0], a[1]); w.y = cvt_pk(a[2], a[3]); w.z = cvt_pk(b[0], b[1]); w.w = cvt_pk(b[2], b[3]); *(u32x4*)dst = w; } }
.LBB0_425:
	s_waitcnt lgkmcnt(4)
	v_lshl_add_u64 v[74:75], s[66:67], 0, v[82:83]
	s_waitcnt lgkmcnt(0)
	v_mov_b64_e32 v[76:77], s[22:23]
	v_mad_u64_u32 v[76:77], s[8:9], v74, s91, v[76:77]
	v_mov_b32_e32 v74, v77
	v_mad_u64_u32 v[74:75], s[8:9], v75, s91, v[74:75]
	v_cvt_pk_bf16_f32 v70, v70, v71
	v_cvt_pk_bf16_f32 v71, v72, v73
	v_cvt_pk_bf16_f32 v72, v66, v67
	v_add_u32_e32 v66, 0x80, v146
	v_mov_b32_e32 v77, v74
	v_ashrrev_i32_e32 v67, 31, v66
	v_lshl_add_u64 v[74:75], s[56:57], 1, v[76:77]
	v_cvt_pk_bf16_f32 v73, v68, v69
	v_lshl_add_u64 v[68:69], s[58:59], 0, v[66:67]
	v_lshl_add_u64 v[74:75], v[142:143], 1, v[74:75]
	v_lshlrev_b64 v[68:69], 5, v[68:69]
	global_store_dwordx4 v[74:75], v[70:73], off
	v_lshl_add_u64 v[68:69], s[12:13], 0, v[68:69]
	v_mov_b64_e32 v[68:69], v[200:201]
	v_mov_b64_e32 v[70:71], v[202:203]
	s_and_b64 vcc, exec, s[4:5]
	v_cmp_gt_i32_e64 s[8:9], s90, v66
	v_lshl_or_b32 v78, v66, 5, v166
	s_waitcnt vmcnt(0)
	v_mov_b32_e32 v72, v69
	v_mov_b32_e32 v73, v70
	v_mov_b32_e32 v69, v71
	v_pk_add_f32 v[68:69], v[72:73], v[68:69]
	s_nop 0
	v_add_f32_e32 v68, v68, v69
	v_fmamk_f32 v68, v68, 0x3b800000, v163
	v_mul_f32_e32 v69, 0x4b800000, v68
	v_cmp_gt_f32_e64 s[10:11], s89, v68
	s_nop 1
	v_cndmask_b32_e64 v68, v68, v69, s[10:11]
	v_rsq_f32_e32 v68, v68
	s_nop 0
	v_mul_f32_e32 v69, 0x45800000, v68
	v_cndmask_b32_e64 v68, v68, v69, s[10:11]
	v_mul_f32_e32 v68, 0x3dd53b94, v68
	v_pk_mul_f32 v[64:65], v[64:65], v[68:69] op_sel_hi:[1,0]
	v_pk_mul_f32 v[62:63], v[62:63], v[68:69] op_sel_hi:[1,0]
	v_pk_mul_f32 v[60:61], v[60:61], v[68:69] op_sel_hi:[1,0]
	v_pk_mul_f32 v[58:59], v[58:59], v[68:69] op_sel_hi:[1,0]
	s_cbranch_vccnz .LBB0_429
	v_and_b32_e32 v70, 64, v165
	v_xor_b32_e32 v69, 32, v165
	v_add_u32_e32 v70, 64, v70
	v_cmp_lt_i32_e32 vcc, v69, v70
	s_nop 1
	v_cndmask_b32_e32 v69, v165, v69, vcc
	v_lshlrev_b32_e32 v69, 2, v69
	ds_bpermute_b32 v74, v69, v62
	ds_bpermute_b32 v70, v69, v58
	ds_bpermute_b32 v75, v69, v63
	ds_bpermute_b32 v71, v69, v59
	ds_bpermute_b32 v76, v69, v64
	ds_bpermute_b32 v72, v69, v60
	ds_bpermute_b32 v77, v69, v65
	ds_bpermute_b32 v73, v69, v61
	s_and_saveexec_b64 s[10:11], s[8:9]
	s_cbranch_execz .LBB0_428
	s_add_i32 s33, s54, 0xffffff80
	s_lshr_b32 s33, s33, 1
	v_add_u32_e32 v80, s33, v78
	v_ashrrev_i32_e32 v81, 31, v80
	v_lshlrev_b64 v[88:89], 2, v[80:81]
	v_lshl_add_u64 v[84:85], s[18:19], 0, v[88:89]
	global_load_dwordx4 v[80:83], v[84:85], off
	s_nop 0
	global_load_dwordx4 v[84:87], v[84:85], off offset:16
	v_lshl_add_u64 v[92:93], s[16:17], 0, v[88:89]
	global_load_dwordx4 v[88:91], v[92:93], off
	s_nop 0
	global_load_dwordx4 v[92:95], v[92:93], off offset:16
	v_mov_b32_e32 v96, v144
	v_mov_b32_e32 v97, v144
	s_waitcnt vmcnt(3)
	v_pk_mul_f32 v[82:83], v[96:97], v[82:83]
	v_pk_mul_f32 v[80:81], v[144:145], v[80:81]
	s_waitcnt vmcnt(2)
	v_pk_mul_f32 v[86:87], v[96:97], v[86:87]
	v_pk_mul_f32 v[84:85], v[144:145], v[84:85]
	s_waitcnt lgkmcnt(1)
	v_pk_mul_f32 v[76:77], v[82:83], v[76:77]
	v_pk_mul_f32 v[74:75], v[80:81], v[74:75]
	s_waitcnt lgkmcnt(0)
	v_pk_mul_f32 v[72:73], v[86:87], v[72:73]
	v_pk_mul_f32 v[70:71], v[84:85], v[70:71]
	s_waitcnt vmcnt(1)
	v_pk_fma_f32 v[64:65], v[64:65], v[90:91], v[76:77]
	v_pk_fma_f32 v[62:63], v[62:63], v[88:89], v[74:75]
	s_waitcnt vmcnt(0)
	v_pk_fma_f32 v[60:61], v[60:61], v[94:95], v[72:73]
	v_pk_fma_f32 v[58:59], v[58:59], v[92:93], v[70:71]

; __device__ __forceinline__ unsigned cvt_pk(float lo, float hi) { unsigned r; asm volatile("v_cvt_pk_bf16_f32 %0, %1, %2" : "=v"(r) : "v"(lo), "v"(hi)); return r; }
;     __device__ __forceinline__ void operator()(const Acc& acc, const Unit& u, int wr, int wc, int fr, int fq) const {
;     ...
;             for (int m = 0; m < 4; ++m) { const int row = u.pm * 256 + ai * 128 + wr * 64 + m * 16 + fr; const size_t R = (size_t)u.pb * NT + row;
;                 const f32x4 sa = *(const f32x4*)(stats + R * 8 + (ISQ ? 0 : 4));
;                 float rr = rsqrtf(((sa[0] + sa[1]) + (sa[2] + sa[3])) * (ISQ ? (1.f / 256.f) : (1.f / 128.f)) + EPS); if (ISQ) rr *= QSCALE;
; #pragma unroll
;                 for (int bj = 0; bj < 2; ++bj) { const int cg_ = u.pn * 256 + bj * 128 + wc * 32; const int h = cg_ / 192, d0 = cg_ - h * 192;
;                     f32x4 a = acc[ai][bj][m][0], b = acc[ai][bj][m][1];
;                     if (d0 < 128) { a = a * rr; b = b * rr; }
;                     else { if (ISQ) { a = a * rr; b = b * rr; }
;                         f32x4 pa, pb;
; #pragma unroll
;                         for (int i = 0; i < 4; ++i) { pa[i] = __shfl_xor(a[i], 32); pb[i] = __shfl_xor(b[i], 32); }
;                         if (row < TL) { const int ti = row * 32 + ((d0 - 128) >> 5) * 16 + 8 * (fq & 1); const float sg = fq < 2 ? -1.f : 1.f;
;                             const f32x4 c0 = *(const f32x4*)(cosT + ti), c1 = *(const f32x4*)(cosT + ti + 4), s0 = *(const f32x4*)(sinT + ti) * sg, s1 = *(const f32x4*)(sinT + ti + 4) * sg;
;                             a = a * c0 + pa * s0; b = b * c1 + pb * s1; } }
;                     bf16_t* dst = O + ((size_t)(u.pb * 4 + h) * NT + row) * pitch + d0 + 8 * fq;
;                     u32x4 w; w.x = cvt_pk(a[0], a[1]); w.y = cvt_pk(a[2], a[3]); w.z = cvt_pk(b[0], b[1]); w.w = cvt_pk(b[2], b[3]); *(u32x4*)dst = w; } }
.LBB0_433:
	s_waitcnt lgkmcnt(4)
	v_lshl_add_u64 v[58:59], s[66:67], 0, v[66:67]
	s_waitcnt lgkmcnt(0)
	v_mov_b64_e32 v[60:61], s[22:23]
	v_mad_u64_u32 v[60:61], s[8:9], v58, s91, v[60:61]
	v_mov_b32_e32 v58, v61
	v_mad_u64_u32 v[58:59], s[8:9], v59, s91, v[58:59]
	v_cvt_pk_bf16_f32 v54, v54, v55
	v_cvt_pk_bf16_f32 v55, v56, v57
	v_cvt_pk_bf16_f32 v56, v50, v51
	v_add_u32_e32 v50, 0x90, v146
	v_mov_b32_e32 v61, v58
	v_ashrrev_i32_e32 v51, 31, v50
	v_lshl_add_u64 v[58:59], s[56:57], 1, v[60:61]
	v_cvt_pk_bf16_f32 v57, v52, v53
	v_lshl_add_u64 v[52:53], s[58:59], 0, v[50:51]
	v_lshl_add_u64 v[58:59], v[142:143], 1, v[58:59]
	v_lshlrev_b64 v[52:53], 5, v[52:53]
	global_store_dwordx4 v[58:59], v[54:57], off
	v_lshl_add_u64 v[52:53], s[12:13], 0, v[52:53]
	v_mov_b64_e32 v[52:53], v[204:205]
	v_mov_b64_e32 v[54:55], v[206:207]
	s_and_b64 vcc, exec, s[4:5]
	v_cmp_gt_i32_e64 s[8:9], s90, v50
	v_lshl_or_b32 v62, v50, 5, v166
	s_waitcnt vmcnt(0)
	v_mov_b32_e32 v56, v53
	v_mov_b32_e32 v57, v54
	v_mov_b32_e32 v53, v55
	v_pk_add_f32 v[52:53], v[56:57], v[52:53]
	s_nop 0
	v_add_f32_e32 v52, v52, v53
	v_fmamk_f32 v52, v52, 0x3b800000, v163
	v_mul_f32_e32 v53, 0x4b800000, v52
	v_cmp_gt_f32_e64 s[10:11], s89, v52
	s_nop 1
	v_cndmask_b32_e64 v52, v52, v53, s[10:11]
	v_rsq_f32_e32 v52, v52
	s_nop 0
	v_mul_f32_e32 v53, 0x45800000, v52
	v_cndmask_b32_e64 v52, v52, v53, s[10:11]
	v_mul_f32_e32 v52, 0x3dd53b94, v52
	v_pk_mul_f32 v[48:49], v[48:49], v[52:53] op_sel_hi:[1,0]
	v_pk_mul_f32 v[46:47], v[46:47], v[52:53] op_sel_hi:[1,0]
	v_pk_mul_f32 v[44:45], v[44:45], v[52:53] op_sel_hi:[1,0]
	v_pk_mul_f32 v[42:43], v[42:43], v[52:53] op_sel_hi:[1,0]
	s_cbranch_vccnz .LBB0_437
	v_and_b32_e32 v54, 64, v165
	v_xor_b32_e32 v53, 32, v165
	v_add_u32_e32 v54, 64, v54
	v_cmp_lt_i32_e32 vcc, v53, v54
	s_nop 1
	v_cndmask_b32_e32 v53, v165, v53, vcc
	v_lshlrev_b32_e32 v53, 2, v53
	ds_bpermute_b32 v58, v53, v46
	ds_bpermute_b32 v54, v53, v42
	ds_bpermute_b32 v59, v53, v47
	ds_bpermute_b32 v55, v53, v43
	ds_bpermute_b32 v60, v53, v48
	ds_bpermute_b32 v56, v53, v44
	ds_bpermute_b32 v61, v53, v49
	ds_bpermute_b32 v57, v53, v45
	s_and_saveexec_b64 s[10:11], s[8:9]
	s_cbranch_execz .LBB0_436
	s_add_i32 s33, s54, 0xffffff80
	s_lshr_b32 s33, s33, 1
	v_add_u32_e32 v64, s33, v62
	v_ashrrev_i32_e32 v65, 31, v64
	v_lshlrev_b64 v[72:73], 2, v[64:65]
	v_lshl_add_u64 v[68:69], s[18:19], 0, v[72:73]
	global_load_dwordx4 v[64:67], v[68:69], off
	s_nop 0
	global_load_dwordx4 v[68:71], v[68:69], off offset:16
	v_lshl_add_u64 v[76:77], s[16:17], 0, v[72:73]
	global_load_dwordx4 v[72:75], v[76:77], off
	s_nop 0
	global_load_dwordx4 v[76:79], v[76:77], off offset:16
	v_mov_b32_e32 v80, v144
	v_mov_b32_e32 v81, v144
	s_waitcnt vmcnt(3)
	v_pk_mul_f32 v[66:67], v[80:81], v[66:67]
	v_pk_mul_f32 v[64:65], v[144:145], v[64:65]
	s_waitcnt vmcnt(2)
	v_pk_mul_f32 v[70:71], v[80:81], v[70:71]
	v_pk_mul_f32 v[68:69], v[144:145], v[68:69]
	s_waitcnt lgkmcnt(1)
	v_pk_mul_f32 v[60:61], v[66:67], v[60:61]
	v_pk_mul_f32 v[58:59], v[64:65], v[58:59]
	s_waitcnt lgkmcnt(0)
	v_pk_mul_f32 v[56:57], v[70:71], v[56:57]
	v_pk_mul_f32 v[54:55], v[68:69], v[54:55]
	s_waitcnt vmcnt(1)
	v_pk_fma_f32 v[48:49], v[48:49], v[74:75], v[60:61]
	v_pk_fma_f32 v[46:47], v[46:47], v[72:73], v[58:59]
	s_waitcnt vmcnt(0)
	v_pk_fma_f32 v[44:45], v[44:45], v[78:79], v[56:57]
	v_pk_fma_f32 v[42:43], v[42:43], v[76:77], v[54:55]

; __device__ __forceinline__ unsigned cvt_pk(float lo, float hi) { unsigned r; asm volatile("v_cvt_pk_bf16_f32 %0, %1, %2" : "=v"(r) : "v"(lo), "v"(hi)); return r; }
;     __device__ __forceinline__ void operator()(const Acc& acc, const Unit& u, int wr, int wc, int fr, int fq) const {
;     ...
;             for (int m = 0; m < 4; ++m) { const int row = u.pm * 256 + ai * 128 + wr * 64 + m * 16 + fr; const size_t R = (size_t)u.pb * NT + row;
;                 const f32x4 sa = *(const f32x4*)(stats + R * 8 + (ISQ ? 0 : 4));
;                 float rr = rsqrtf(((sa[0] + sa[1]) + (sa[2] + sa[3])) * (ISQ ? (1.f / 256.f) : (1.f / 128.f)) + EPS); if (ISQ) rr *= QSCALE;
; #pragma unroll
;                 for (int bj = 0; bj < 2; ++bj) { const int cg_ = u.pn * 256 + bj * 128 + wc * 32; const int h = cg_ / 192, d0 = cg_ - h * 192;
;                     f32x4 a = acc[ai][bj][m][0], b = acc[ai][bj][m][1];
;                     if (d0 < 128) { a = a * rr; b = b * rr; }
;                     else { if (ISQ) { a = a * rr; b = b * rr; }
;                         f32x4 pa, pb;
; #pragma unroll
;                         for (int i = 0; i < 4; ++i) { pa[i] = __shfl_xor(a[i], 32); pb[i] = __shfl_xor(b[i], 32); }
;                         if (row < TL) { const int ti = row * 32 + ((d0 - 128) >> 5) * 16 + 8 * (fq & 1); const float sg = fq < 2 ? -1.f : 1.f;
;                             const f32x4 c0 = *(const f32x4*)(cosT + ti), c1 = *(const f32x4*)(cosT + ti + 4), s0 = *(const f32x4*)(sinT + ti) * sg, s1 = *(const f32x4*)(sinT + ti + 4) * sg;
;                             a = a * c0 + pa * s0; b = b * c1 + pb * s1; } }
;                     bf16_t* dst = O + ((size_t)(u.pb * 4 + h) * NT + row) * pitch + d0 + 8 * fq;
;                     u32x4 w; w.x = cvt_pk(a[0], a[1]); w.y = cvt_pk(a[2], a[3]); w.z = cvt_pk(b[0], b[1]); w.w = cvt_pk(b[2], b[3]); *(u32x4*)dst = w; } }
.LBB0_441:
	s_waitcnt lgkmcnt(4)
	v_lshl_add_u64 v[42:43], s[66:67], 0, v[50:51]
	s_waitcnt lgkmcnt(0)
	v_mov_b64_e32 v[44:45], s[22:23]
	v_mad_u64_u32 v[44:45], s[8:9], v42, s91, v[44:45]
	v_mov_b32_e32 v42, v45
	v_mad_u64_u32 v[42:43], s[8:9], v43, s91, v[42:43]
	v_cvt_pk_bf16_f32 v38, v38, v39
	v_cvt_pk_bf16_f32 v39, v40, v41
	v_cvt_pk_bf16_f32 v40, v34, v35
	v_add_u32_e32 v34, 0xa0, v146
	v_mov_b32_e32 v45, v42
	v_ashrrev_i32_e32 v35, 31, v34
	v_lshl_add_u64 v[42:43], s[56:57], 1, v[44:45]
	v_cvt_pk_bf16_f32 v41, v36, v37
	v_lshl_add_u64 v[36:37], s[58:59], 0, v[34:35]
	v_lshl_add_u64 v[42:43], v[142:143], 1, v[42:43]
	v_lshlrev_b64 v[36:37], 5, v[36:37]
	global_store_dwordx4 v[42:43], v[38:41], off
	v_lshl_add_u64 v[36:37], s[12:13], 0, v[36:37]
	v_mov_b64_e32 v[36:37], v[208:209]
	v_mov_b64_e32 v[38:39], v[210:211]
	s_and_b64 vcc, exec, s[4:5]
	v_cmp_gt_i32_e64 s[8:9], s90, v34
	v_lshl_or_b32 v46, v34, 5, v166
	s_waitcnt vmcnt(0)
	v_mov_b32_e32 v40, v37
	v_mov_b32_e32 v41, v38
	v_mov_b32_e32 v37, v39
	v_pk_add_f32 v[36:37], v[40:41], v[36:37]
	s_nop 0
	v_add_f32_e32 v36, v36, v37
	v_fmamk_f32 v36, v36, 0x3b800000, v163
	v_mul_f32_e32 v37, 0x4b800000, v36
	v_cmp_gt_f32_e64 s[10:11], s89, v36
	s_nop 1
	v_cndmask_b32_e64 v36, v36, v37, s[10:11]
	v_rsq_f32_e32 v36, v36
	s_nop 0
	v_mul_f32_e32 v37, 0x45800000, v36
	v_cndmask_b32_e64 v36, v36, v37, s[10:11]
	v_mul_f32_e32 v36, 0x3dd53b94, v36
	v_pk_mul_f32 v[32:33], v[32:33], v[36:37] op_sel_hi:[1,0]
	v_pk_mul_f32 v[30:31], v[30:31], v[36:37] op_sel_hi:[1,0]
	v_pk_mul_f32 v[28:29], v[28:29], v[36:37] op_sel_hi:[1,0]
	v_pk_mul_f32 v[26:27], v[26:27], v[36:37] op_sel_hi:[1,0]
	s_cbranch_vccnz .LBB0_445
	v_and_b32_e32 v38, 64, v165
	v_xor_b32_e32 v37, 32, v165
	v_add_u32_e32 v38, 64, v38
	v_cmp_lt_i32_e32 vcc, v37, v38
	s_nop 1
	v_cndmask_b32_e32 v37, v165, v37, vcc
	v_lshlrev_b32_e32 v37, 2, v37
	ds_bpermute_b32 v42, v37, v30
	ds_bpermute_b32 v38, v37, v26
	ds_bpermute_b32 v43, v37, v31
	ds_bpermute_b32 v39, v37, v27
	ds_bpermute_b32 v44, v37, v32
	ds_bpermute_b32 v40, v37, v28
	ds_bpermute_b32 v45, v37, v33
	ds_bpermute_b32 v41, v37, v29
	s_and_saveexec_b64 s[10:11], s[8:9]
	s_cbranch_execz .LBB0_444
	s_add_i32 s33, s54, 0xffffff80
	s_lshr_b32 s33, s33, 1
	v_add_u32_e32 v48, s33, v46
	v_ashrrev_i32_e32 v49, 31, v48
	v_lshlrev_b64 v[56:57], 2, v[48:49]
	v_lshl_add_u64 v[52:53], s[18:19], 0, v[56:57]
	global_load_dwordx4 v[48:51], v[52:53], off
	s_nop 0
	global_load_dwordx4 v[52:55], v[52:53], off offset:16
	v_lshl_add_u64 v[60:61], s[16:17], 0, v[56:57]
	global_load_dwordx4 v[56:59], v[60:61], off
	s_nop 0
	global_load_dwordx4 v[60:63], v[60:61], off offset:16
	v_mov_b32_e32 v64, v144
	v_mov_b32_e32 v65, v144
	s_waitcnt vmcnt(3)
	v_pk_mul_f32 v[50:51], v[64:65], v[50:51]
	v_pk_mul_f32 v[48:49], v[144:145], v[48:49]
	s_waitcnt vmcnt(2)
	v_pk_mul_f32 v[54:55], v[64:65], v[54:55]
	v_pk_mul_f32 v[52:53], v[144:145], v[52:53]
	s_waitcnt lgkmcnt(1)
	v_pk_mul_f32 v[44:45], v[50:51], v[44:45]
	v_pk_mul_f32 v[42:43], v[48:49], v[42:43]
	s_waitcnt lgkmcnt(0)
	v_pk_mul_f32 v[40:41], v[54:55], v[40:41]
	v_pk_mul_f32 v[38:39], v[52:53], v[38:39]
	s_waitcnt vmcnt(1)
	v_pk_fma_f32 v[32:33], v[32:33], v[58:59], v[44:45]
	v_pk_fma_f32 v[30:31], v[30:31], v[56:57], v[42:43]
	s_waitcnt vmcnt(0)
	v_pk_fma_f32 v[28:29], v[28:29], v[62:63], v[40:41]
	v_pk_fma_f32 v[26:27], v[26:27], v[60:61], v[38:39]

; __device__ __forceinline__ unsigned cvt_pk(float lo, float hi) { unsigned r; asm volatile("v_cvt_pk_bf16_f32 %0, %1, %2" : "=v"(r) : "v"(lo), "v"(hi)); return r; }
;     __device__ __forceinline__ void operator()(const Acc& acc, const Unit& u, int wr, int wc, int fr, int fq) const {
;     ...
;             for (int m = 0; m < 4; ++m) { const int row = u.pm * 256 + ai * 128 + wr * 64 + m * 16 + fr; const size_t R = (size_t)u.pb * NT + row;
;                 const f32x4 sa = *(const f32x4*)(stats + R * 8 + (ISQ ? 0 : 4));
;                 float rr = rsqrtf(((sa[0] + sa[1]) + (sa[2] + sa[3])) * (ISQ ? (1.f / 256.f) : (1.f / 128.f)) + EPS); if (ISQ) rr *= QSCALE;
; #pragma unroll
;                 for (int bj = 0; bj < 2; ++bj) { const int cg_ = u.pn * 256 + bj * 128 + wc * 32; const int h = cg_ / 192, d0 = cg_ - h * 192;
;                     f32x4 a = acc[ai][bj][m][0], b = acc[ai][bj][m][1];
;                     if (d0 < 128) { a = a * rr; b = b * rr; }
;                     else { if (ISQ) { a = a * rr; b = b * rr; }
;                         f32x4 pa, pb;
; #pragma unroll
;                         for (int i = 0; i < 4; ++i) { pa[i] = __shfl_xor(a[i], 32); pb[i] = __shfl_xor(b[i], 32); }
;                         if (row < TL) { const int ti = row * 32 + ((d0 - 128) >> 5) * 16 + 8 * (fq & 1); const float sg = fq < 2 ? -1.f : 1.f;
;                             const f32x4 c0 = *(const f32x4*)(cosT + ti), c1 = *(const f32x4*)(cosT + ti + 4), s0 = *(const f32x4*)(sinT + ti) * sg, s1 = *(const f32x4*)(sinT + ti + 4) * sg;
;                             a = a * c0 + pa * s0; b = b * c1 + pb * s1; } }
;                     bf16_t* dst = O + ((size_t)(u.pb * 4 + h) * NT + row) * pitch + d0 + 8 * fq;
;                     u32x4 w; w.x = cvt_pk(a[0], a[1]); w.y = cvt_pk(a[2], a[3]); w.z = cvt_pk(b[0], b[1]); w.w = cvt_pk(b[2], b[3]); *(u32x4*)dst = w; } }
.LBB0_449:
	s_waitcnt lgkmcnt(4)
	v_lshl_add_u64 v[26:27], s[66:67], 0, v[34:35]
	s_waitcnt lgkmcnt(0)
	v_mov_b64_e32 v[28:29], s[22:23]
	v_mad_u64_u32 v[28:29], s[8:9], v26, s91, v[28:29]
	v_mov_b32_e32 v26, v29
	v_mad_u64_u32 v[26:27], s[8:9], v27, s91, v[26:27]
	v_cvt_pk_bf16_f32 v22, v22, v23
	v_cvt_pk_bf16_f32 v23, v24, v25
	v_cvt_pk_bf16_f32 v24, v18, v19
	v_add_u32_e32 v18, 0xb0, v146
	v_mov_b32_e32 v29, v26
	v_ashrrev_i32_e32 v19, 31, v18
	v_lshl_add_u64 v[26:27], s[56:57], 1, v[28:29]
	v_cvt_pk_bf16_f32 v25, v20, v21
	v_lshl_add_u64 v[20:21], s[58:59], 0, v[18:19]
	v_lshl_add_u64 v[26:27], v[142:143], 1, v[26:27]
	v_lshlrev_b64 v[20:21], 5, v[20:21]
	global_store_dwordx4 v[26:27], v[22:25], off
	v_lshl_add_u64 v[20:21], s[12:13], 0, v[20:21]
	v_mov_b64_e32 v[20:21], v[212:213]
	v_mov_b64_e32 v[22:23], v[214:215]
	s_and_b64 vcc, exec, s[4:5]
	v_cmp_gt_i32_e64 s[4:5], s90, v18
	v_lshl_or_b32 v30, v18, 5, v166
	s_waitcnt vmcnt(0)
	v_mov_b32_e32 v24, v21
	v_mov_b32_e32 v25, v22
	v_mov_b32_e32 v21, v23
	v_pk_add_f32 v[20:21], v[24:25], v[20:21]
	s_nop 0
	v_add_f32_e32 v20, v20, v21
	v_fmamk_f32 v20, v20, 0x3b800000, v163
	v_mul_f32_e32 v21, 0x4b800000, v20
	v_cmp_gt_f32_e64 s[8:9], s89, v20
	s_nop 1
	v_cndmask_b32_e64 v20, v20, v21, s[8:9]
	v_rsq_f32_e32 v20, v20
	s_nop 0
	v_mul_f32_e32 v21, 0x45800000, v20
	v_cndmask_b32_e64 v20, v20, v21, s[8:9]
	v_mul_f32_e32 v20, 0x3dd53b94, v20
	v_pk_mul_f32 v[16:17], v[16:17], v[20:21] op_sel_hi:[1,0]
	v_pk_mul_f32 v[14:15], v[14:15], v[20:21] op_sel_hi:[1,0]
	v_pk_mul_f32 v[12:13], v[12:13], v[20:21] op_sel_hi:[1,0]
	v_pk_mul_f32 v[10:11], v[10:11], v[20:21] op_sel_hi:[1,0]
	s_cbranch_vccnz .LBB0_453
	v_and_b32_e32 v22, 64, v165
	v_xor_b32_e32 v21, 32, v165
	v_add_u32_e32 v22, 64, v22
	v_cmp_lt_i32_e32 vcc, v21, v22
	s_nop 1
	v_cndmask_b32_e32 v21, v165, v21, vcc
	v_lshlrev_b32_e32 v21, 2, v21
	ds_bpermute_b32 v26, v21, v14
	ds_bpermute_b32 v22, v21, v10
	ds_bpermute_b32 v27, v21, v15
	ds_bpermute_b32 v23, v21, v11
	ds_bpermute_b32 v28, v21, v16
	ds_bpermute_b32 v24, v21, v12
	ds_bpermute_b32 v29, v21, v17
	ds_bpermute_b32 v25, v21, v13
	s_and_saveexec_b64 s[8:9], s[4:5]
	s_cbranch_execz .LBB0_452
	s_add_i32 s10, s54, 0xffffff80
	s_lshr_b32 s10, s10, 1
	v_add_u32_e32 v32, s10, v30
	v_ashrrev_i32_e32 v33, 31, v32
	v_lshlrev_b64 v[40:41], 2, v[32:33]
	v_lshl_add_u64 v[36:37], s[18:19], 0, v[40:41]
	global_load_dwordx4 v[32:35], v[36:37], off
	s_nop 0
	global_load_dwordx4 v[36:39], v[36:37], off offset:16
	v_lshl_add_u64 v[44:45], s[16:17], 0, v[40:41]
	global_load_dwordx4 v[40:43], v[44:45], off
	s_nop 0
	global_load_dwordx4 v[44:47], v[44:45], off offset:16
	v_mov_b32_e32 v48, v144
	v_mov_b32_e32 v49, v144
	s_waitcnt vmcnt(3)
	v_pk_mul_f32 v[34:35], v[48:49], v[34:35]
	v_pk_mul_f32 v[32:33], v[144:145], v[32:33]
	s_waitcnt vmcnt(2)
	v_pk_mul_f32 v[38:39], v[48:49], v[38:39]
	v_pk_mul_f32 v[36:37], v[144:145], v[36:37]
	s_waitcnt lgkmcnt(1)
	v_pk_mul_f32 v[28:29], v[34:35], v[28:29]
	v_pk_mul_f32 v[26:27], v[32:33], v[26:27]
	s_waitcnt lgkmcnt(0)
	v_pk_mul_f32 v[24:25], v[38:39], v[24:25]
	v_pk_mul_f32 v[22:23], v[36:37], v[22:23]
	s_waitcnt vmcnt(1)
	v_pk_fma_f32 v[16:17], v[16:17], v[42:43], v[28:29]
	v_pk_fma_f32 v[14:15], v[14:15], v[40:41], v[26:27]
	s_waitcnt vmcnt(0)
	v_pk_fma_f32 v[12:13], v[12:13], v[46:47], v[24:25]
	v_pk_fma_f32 v[10:11], v[10:11], v[44:45], v[22:23]

;     __device__ __forceinline__ void operator()(const Acc& acc, const Unit& u, int wr, int wc, int fr, int fq) const {
;     ...
;             for (int m = 0; m < 4; ++m) { const int row = u.pm * 256 + ai * 128 + wr * 64 + m * 16 + fr; const size_t R = (size_t)u.pb * NT + row;
;                 const f32x4 sa = *(const f32x4*)(stats + R * 8 + (ISQ ? 0 : 4));
;                 float rr = rsqrtf(((sa[0] + sa[1]) + (sa[2] + sa[3])) * (ISQ ? (1.f / 256.f) : (1.f / 128.f)) + EPS); if (ISQ) rr *= QSCALE;
; #pragma unroll
;                 for (int bj = 0; bj < 2; ++bj) { const int cg_ = u.pn * 256 + bj * 128 + wc * 32; const int h = cg_ / 192, d0 = cg_ - h * 192;
;                     f32x4 a = acc[ai][bj][m][0], b = acc[ai][bj][m][1];
;                     if (d0 < 128) { a = a * rr; b = b * rr; }
;                     else { if (ISQ) { a = a * rr; b = b * rr; }
;                         f32x4 pa, pb;
; #pragma unroll
;                         for (int i = 0; i < 4; ++i) { pa[i] = __shfl_xor(a[i], 32); pb[i] = __shfl_xor(b[i], 32); }
;                         if (row < TL) { const int ti = row * 32 + ((d0 - 128) >> 5) * 16 + 8 * (fq & 1); const float sg = fq < 2 ? -1.f : 1.f;
;                             const f32x4 c0 = *(const f32x4*)(cosT + ti), c1 = *(const f32x4*)(cosT + ti + 4), s0 = *(const f32x4*)(sinT + ti) * sg, s1 = *(const f32x4*)(sinT + ti + 4) * sg;
;                             a = a * c0 + pa * s0; b = b * c1 + pb * s1; } }
.LBB0_479:
	v_mov_b32_e32 v134, v164
	s_lshl_b32 s38, s69, 8
	v_and_or_b32 v173, v134, 15, s91
	v_add_u32_e32 v154, s38, v173
	v_ashrrev_i32_e32 v155, 31, v154
	v_mad_i64_i32 v[130:131], s[4:5], s15, v170, v[154:155]
	v_lshlrev_b64 v[130:131], 5, v[130:131]
	v_lshl_add_u64 v[130:131], s[12:13], 0, v[130:131]
	v_mov_b64_e32 v[218:219], v[130:131]
	global_load_dwordx4 v[130:133], v[130:131], off offset:16
	s_mov_b32 s98, 0x1000
	s_mov_b32 s99, 0
	global_load_dwordx4 v[188:191], v[218:219], off offset:528
	global_load_dwordx4 v[192:195], v[218:219], off offset:1040
	global_load_dwordx4 v[196:199], v[218:219], off offset:1552
	v_lshl_add_u64 v[216:217], v[218:219], 0, s[98:99]
	global_load_dwordx4 v[200:203], v[216:217], off offset:16
	global_load_dwordx4 v[204:207], v[216:217], off offset:528
	global_load_dwordx4 v[208:211], v[216:217], off offset:1040
	global_load_dwordx4 v[212:215], v[216:217], off offset:1552
	s_lshl_b32 s4, s68, 8
	s_or_b32 s8, s4, s92
	s_mul_hi_i32 s4, s8, 0x2aaaaaab
	v_ashrrev_i32_e32 v134, 4, v134
	s_lshr_b32 s6, s4, 31
	s_ashr_i32 s33, s4, 5
	v_lshlrev_b32_e32 v150, 3, v134
	v_cmp_gt_i32_e32 vcc, 2, v134
	s_add_i32 s33, s33, s6
	s_mul_i32 s6, s33, 0xffffff40
	s_add_i32 s54, s6, s8
	v_cndmask_b32_e64 v152, 1.0, -1.0, vcc
	v_and_b32_e32 v172, 8, v150
	s_cmpk_gt_i32 s54, 0x7f
	v_mov_b32_e32 v153, v152
	v_cmp_gt_i32_e64 s[4:5], s78, v154
	v_lshl_or_b32 v174, v154, 5, v172
	s_cselect_b64 s[10:11], -1, 0
	s_cmpk_lt_i32 s54, 0x80
	s_mov_b64 s[6:7], -1
	s_waitcnt vmcnt(0)
	v_mov_b32_e32 v134, v131
	v_mov_b32_e32 v135, v132
	v_mov_b32_e32 v131, v133
	v_pk_add_f32 v[130:131], v[134:135], v[130:131]
	s_nop 0
	v_add_f32_e32 v130, v130, v131
	v_fmamk_f32 v151, v130, 0x3c000000, v169
	v_cmp_gt_f32_e32 vcc, s97, v151
	s_cbranch_scc1 .LBB0_483
	v_and_b32_e32 v131, 64, v171
	v_xor_b32_e32 v130, 32, v171
	v_add_u32_e32 v131, 64, v131
	v_cmp_lt_i32_e64 s[6:7], v130, v131
	v_mov_b64_e32 v[136:137], v[124:125]
	v_mov_b64_e32 v[134:135], v[122:123]
	v_cndmask_b32_e64 v130, v171, v130, s[6:7]
	v_lshlrev_b32_e32 v130, 2, v130
	ds_bpermute_b32 v160, v130, v126
	ds_bpermute_b32 v156, v130, v122
	ds_bpermute_b32 v161, v130, v127
	ds_bpermute_b32 v157, v130, v123
	ds_bpermute_b32 v162, v130, v128
	ds_bpermute_b32 v158, v130, v124
	ds_bpermute_b32 v163, v130, v129
	ds_bpermute_b32 v159, v130, v125
	v_mov_b64_e32 v[132:133], v[128:129]
	v_mov_b64_e32 v[130:131], v[126:127]
	s_and_saveexec_b64 s[6:7], s[4:5]
	s_cbranch_execz .LBB0_482
	s_add_i32 s9, s54, 0xffffff80
	s_lshr_b32 s9, s9, 1
	v_add_u32_e32 v130, s9, v174
	v_ashrrev_i32_e32 v131, 31, v130
	v_lshlrev_b64 v[176:177], 2, v[130:131]
	v_lshl_add_u64 v[134:135], s[18:19], 0, v[176:177]
	global_load_dwordx4 v[130:133], v[134:135], off
	s_nop 0
	global_load_dwordx4 v[134:137], v[134:135], off offset:16
	v_lshl_add_u64 v[180:181], s[16:17], 0, v[176:177]
	global_load_dwordx4 v[176:179], v[180:181], off
	s_nop 0
	global_load_dwordx4 v[180:183], v[180:181], off offset:16
	v_mov_b32_e32 v184, v152
	v_mov_b32_e32 v185, v152
	s_waitcnt vmcnt(3)
	v_pk_mul_f32 v[132:133], v[184:185], v[132:133]
	v_pk_mul_f32 v[130:131], v[152:153], v[130:131]
	s_waitcnt vmcnt(2)
	v_pk_mul_f32 v[136:137], v[184:185], v[136:137]
	v_pk_mul_f32 v[134:135], v[152:153], v[134:135]
	s_waitcnt lgkmcnt(1)
	v_pk_mul_f32 v[132:133], v[132:133], v[162:163]
	v_pk_mul_f32 v[130:131], v[130:131], v[160:161]
	s_waitcnt lgkmcnt(0)
	v_pk_mul_f32 v[136:137], v[136:137], v[158:159]
	v_pk_mul_f32 v[134:135], v[134:135], v[156:157]
	s_waitcnt vmcnt(1)
	v_pk_fma_f32 v[132:133], v[128:129], v[178:179], v[132:133]
	v_pk_fma_f32 v[130:131], v[126:127], v[176:177], v[130:131]
	s_waitcnt vmcnt(0)
	v_pk_fma_f32 v[136:137], v[124:125], v[182:183], v[136:137]
	v_pk_fma_f32 v[134:135], v[122:123], v[180:181], v[134:135]

; __device__ __forceinline__ unsigned cvt_pk(float lo, float hi) { unsigned r; asm volatile("v_cvt_pk_bf16_f32 %0, %1, %2" : "=v"(r) : "v"(lo), "v"(hi)); return r; }
;     __device__ __forceinline__ void operator()(const Acc& acc, const Unit& u, int wr, int wc, int fr, int fq) const {
;     ...
;             for (int m = 0; m < 4; ++m) { const int row = u.pm * 256 + ai * 128 + wr * 64 + m * 16 + fr; const size_t R = (size_t)u.pb * NT + row;
;                 const f32x4 sa = *(const f32x4*)(stats + R * 8 + (ISQ ? 0 : 4));
;                 float rr = rsqrtf(((sa[0] + sa[1]) + (sa[2] + sa[3])) * (ISQ ? (1.f / 256.f) : (1.f / 128.f)) + EPS); if (ISQ) rr *= QSCALE;
; #pragma unroll
;                 for (int bj = 0; bj < 2; ++bj) { const int cg_ = u.pn * 256 + bj * 128 + wc * 32; const int h = cg_ / 192, d0 = cg_ - h * 192;
;                     f32x4 a = acc[ai][bj][m][0], b = acc[ai][bj][m][1];
;                     if (d0 < 128) { a = a * rr; b = b * rr; }
;                     else { if (ISQ) { a = a * rr; b = b * rr; }
;                         f32x4 pa, pb;
; #pragma unroll
;                         for (int i = 0; i < 4; ++i) { pa[i] = __shfl_xor(a[i], 32); pb[i] = __shfl_xor(b[i], 32); }
;                         if (row < TL) { const int ti = row * 32 + ((d0 - 128) >> 5) * 16 + 8 * (fq & 1); const float sg = fq < 2 ? -1.f : 1.f;
;                             const f32x4 c0 = *(const f32x4*)(cosT + ti), c1 = *(const f32x4*)(cosT + ti + 4), s0 = *(const f32x4*)(sinT + ti) * sg, s1 = *(const f32x4*)(sinT + ti + 4) * sg;
;                             a = a * c0 + pa * s0; b = b * c1 + pb * s1; } }
;                     bf16_t* dst = O + ((size_t)(u.pb * 4 + h) * NT + row) * pitch + d0 + 8 * fq;
;                     u32x4 w; w.x = cvt_pk(a[0], a[1]); w.y = cvt_pk(a[2], a[3]); w.z = cvt_pk(b[0], b[1]); w.w = cvt_pk(b[2], b[3]); *(u32x4*)dst = w; } }
.LBB0_491:
	s_mul_hi_i32 s59, s15, 0x900
	s_mul_i32 s58, s15, 0x900
	s_add_i32 s15, s8, s9
	v_mad_i64_i32 v[114:115], s[4:5], s15, v170, v[154:155]
	v_mov_b64_e32 v[116:117], s[22:23]
	v_mad_u64_u32 v[116:117], s[4:5], v114, s34, v[116:117]
	v_mad_i32_i24 v117, v115, s34, v117
	s_ashr_i32 s57, s56, 31
	v_lshl_add_u64 v[114:115], s[56:57], 1, v[116:117]
	v_lshl_add_u64 v[118:119], v[150:151], 1, v[114:115]
	v_cvt_pk_bf16_f32 v114, v122, v123
	v_add3_u32 v122, s38, v173, 16
	v_cvt_pk_bf16_f32 v115, v124, v125
	v_ashrrev_i32_e32 v123, 31, v122
	v_cvt_pk_bf16_f32 v116, v126, v127
	v_cvt_pk_bf16_f32 v117, v128, v129
	global_store_dwordx4 v[118:119], v[114:117], off
	v_cndmask_b32_e64 v118, 0, 1, s[10:11]
	v_cmp_ne_u32_e64 s[4:5], 1, v118
	v_lshl_add_u64 v[114:115], s[58:59], 0, v[122:123]
	v_lshlrev_b64 v[114:115], 5, v[114:115]
	v_lshl_add_u64 v[114:115], s[12:13], 0, v[114:115]
	v_mov_b64_e32 v[114:115], v[188:189]
	v_mov_b64_e32 v[116:117], v[190:191]
	v_cmp_gt_i32_e64 s[8:9], s78, v122
	s_waitcnt lgkmcnt(2)
	v_lshl_or_b32 v132, v122, 5, v172
	s_andn2_b64 vcc, exec, s[10:11]
	s_mov_b64 s[10:11], -1
	s_waitcnt vmcnt(0)
	v_mov_b32_e32 v118, v115
	v_mov_b32_e32 v119, v116
	v_mov_b32_e32 v115, v117
	v_pk_add_f32 v[114:115], v[118:119], v[114:115]
	s_nop 0
	v_add_f32_e32 v114, v114, v115
	s_waitcnt lgkmcnt(0)
	v_fmamk_f32 v133, v114, 0x3c000000, v169
	v_cmp_gt_f32_e64 s[6:7], s97, v133
	s_cbranch_vccnz .LBB0_495
	v_and_b32_e32 v115, 64, v171
	v_xor_b32_e32 v114, 32, v171
	v_add_u32_e32 v115, 64, v115
	v_cmp_lt_i32_e32 vcc, v114, v115
	v_mov_b64_e32 v[120:121], v[108:109]
	v_mov_b64_e32 v[118:119], v[106:107]
	v_cndmask_b32_e32 v114, v171, v114, vcc
	v_lshlrev_b32_e32 v114, 2, v114
	ds_bpermute_b32 v128, v114, v110
	ds_bpermute_b32 v124, v114, v106
	ds_bpermute_b32 v129, v114, v111
	ds_bpermute_b32 v125, v114, v107
	ds_bpermute_b32 v130, v114, v112
	ds_bpermute_b32 v126, v114, v108
	ds_bpermute_b32 v131, v114, v113
	ds_bpermute_b32 v127, v114, v109
	v_mov_b64_e32 v[116:117], v[112:113]
	v_mov_b64_e32 v[114:115], v[110:111]
	s_and_saveexec_b64 s[10:11], s[8:9]
	s_cbranch_execz .LBB0_494
	s_add_i32 s33, s54, 0xffffff80
	s_lshr_b32 s33, s33, 1
	v_add_u32_e32 v114, s33, v132
	v_ashrrev_i32_e32 v115, 31, v114
	v_lshlrev_b64 v[134:135], 2, v[114:115]
	v_lshl_add_u64 v[118:119], s[18:19], 0, v[134:135]
	global_load_dwordx4 v[114:117], v[118:119], off
	s_nop 0
	global_load_dwordx4 v[118:121], v[118:119], off offset:16
	v_lshl_add_u64 v[156:157], s[16:17], 0, v[134:135]
	global_load_dwordx4 v[134:137], v[156:157], off
	s_nop 0
	global_load_dwordx4 v[156:159], v[156:157], off offset:16
	v_mov_b32_e32 v160, v152
	v_mov_b32_e32 v161, v152
	s_waitcnt vmcnt(3)
	v_pk_mul_f32 v[116:117], v[160:161], v[116:117]
	v_pk_mul_f32 v[114:115], v[152:153], v[114:115]
	s_waitcnt vmcnt(2)
	v_pk_mul_f32 v[120:121], v[160:161], v[120:121]
	v_pk_mul_f32 v[118:119], v[152:153], v[118:119]
	s_waitcnt lgkmcnt(1)
	v_pk_mul_f32 v[116:117], v[116:117], v[130:131]
	v_pk_mul_f32 v[114:115], v[114:115], v[128:129]
	s_waitcnt lgkmcnt(0)
	v_pk_mul_f32 v[120:121], v[120:121], v[126:127]
	v_pk_mul_f32 v[118:119], v[118:119], v[124:125]
	s_waitcnt vmcnt(1)
	v_pk_fma_f32 v[116:117], v[112:113], v[136:137], v[116:117]
	v_pk_fma_f32 v[114:115], v[110:111], v[134:135], v[114:115]
	s_waitcnt vmcnt(0)
	v_pk_fma_f32 v[120:121], v[108:109], v[158:159], v[120:121]
	v_pk_fma_f32 v[118:119], v[106:107], v[156:157], v[118:119]

; __device__ __forceinline__ unsigned cvt_pk(float lo, float hi) { unsigned r; asm volatile("v_cvt_pk_bf16_f32 %0, %1, %2" : "=v"(r) : "v"(lo), "v"(hi)); return r; }
;     __device__ __forceinline__ void operator()(const Acc& acc, const Unit& u, int wr, int wc, int fr, int fq) const {
;     ...
;             for (int m = 0; m < 4; ++m) { const int row = u.pm * 256 + ai * 128 + wr * 64 + m * 16 + fr; const size_t R = (size_t)u.pb * NT + row;
;                 const f32x4 sa = *(const f32x4*)(stats + R * 8 + (ISQ ? 0 : 4));
;                 float rr = rsqrtf(((sa[0] + sa[1]) + (sa[2] + sa[3])) * (ISQ ? (1.f / 256.f) : (1.f / 128.f)) + EPS); if (ISQ) rr *= QSCALE;
; #pragma unroll
;                 for (int bj = 0; bj < 2; ++bj) { const int cg_ = u.pn * 256 + bj * 128 + wc * 32; const int h = cg_ / 192, d0 = cg_ - h * 192;
;                     f32x4 a = acc[ai][bj][m][0], b = acc[ai][bj][m][1];
;                     if (d0 < 128) { a = a * rr; b = b * rr; }
;                     else { if (ISQ) { a = a * rr; b = b * rr; }
;                         f32x4 pa, pb;
; #pragma unroll
;                         for (int i = 0; i < 4; ++i) { pa[i] = __shfl_xor(a[i], 32); pb[i] = __shfl_xor(b[i], 32); }
;                         if (row < TL) { const int ti = row * 32 + ((d0 - 128) >> 5) * 16 + 8 * (fq & 1); const float sg = fq < 2 ? -1.f : 1.f;
;                             const f32x4 c0 = *(const f32x4*)(cosT + ti), c1 = *(const f32x4*)(cosT + ti + 4), s0 = *(const f32x4*)(sinT + ti) * sg, s1 = *(const f32x4*)(sinT + ti + 4) * sg;
;                             a = a * c0 + pa * s0; b = b * c1 + pb * s1; } }
;                     bf16_t* dst = O + ((size_t)(u.pb * 4 + h) * NT + row) * pitch + d0 + 8 * fq;
;                     u32x4 w; w.x = cvt_pk(a[0], a[1]); w.y = cvt_pk(a[2], a[3]); w.z = cvt_pk(b[0], b[1]); w.w = cvt_pk(b[2], b[3]); *(u32x4*)dst = w; } }
.LBB0_503:
	s_mul_hi_i32 s67, s15, 0x900
	s_mul_i32 s66, s15, 0x900
	v_lshl_add_u64 v[98:99], s[66:67], 0, v[122:123]
	v_mov_b64_e32 v[100:101], s[22:23]
	v_mad_u64_u32 v[100:101], s[8:9], v98, s34, v[100:101]
	v_mov_b32_e32 v98, v101
	v_mad_u64_u32 v[98:99], s[8:9], v99, s34, v[98:99]
	v_mov_b32_e32 v101, v98
	v_lshl_add_u64 v[98:99], s[56:57], 1, v[100:101]
	v_lshl_add_u64 v[102:103], v[150:151], 1, v[98:99]
	v_cvt_pk_bf16_f32 v98, v106, v107
	v_add3_u32 v106, s38, v173, 32
	v_cvt_pk_bf16_f32 v99, v108, v109
	v_ashrrev_i32_e32 v107, 31, v106
	v_cvt_pk_bf16_f32 v100, v110, v111
	v_cvt_pk_bf16_f32 v101, v112, v113
	global_store_dwordx4 v[102:103], v[98:101], off
	s_and_b64 vcc, exec, s[4:5]
	v_cmp_gt_i32_e64 s[8:9], s78, v106
	v_lshl_add_u64 v[98:99], s[58:59], 0, v[106:107]
	v_lshlrev_b64 v[98:99], 5, v[98:99]
	v_lshl_add_u64 v[98:99], s[12:13], 0, v[98:99]
	v_mov_b64_e32 v[98:99], v[192:193]
	v_mov_b64_e32 v[100:101], v[194:195]
	s_waitcnt lgkmcnt(2)
	v_lshl_or_b32 v116, v106, 5, v172
	s_mov_b64 s[68:69], -1
	s_waitcnt vmcnt(0)
	v_mov_b32_e32 v102, v99
	v_mov_b32_e32 v103, v100
	v_mov_b32_e32 v99, v101
	v_pk_add_f32 v[98:99], v[102:103], v[98:99]
	s_nop 0
	v_add_f32_e32 v98, v98, v99
	s_waitcnt lgkmcnt(0)
	v_fmamk_f32 v117, v98, 0x3c000000, v169
	v_cmp_gt_f32_e64 s[10:11], s97, v117
	s_cbranch_vccnz .LBB0_507
	v_and_b32_e32 v99, 64, v171
	v_xor_b32_e32 v98, 32, v171
	v_add_u32_e32 v99, 64, v99
	v_cmp_lt_i32_e32 vcc, v98, v99
	v_mov_b64_e32 v[104:105], v[92:93]
	v_mov_b64_e32 v[102:103], v[90:91]
	v_cndmask_b32_e32 v98, v171, v98, vcc
	v_lshlrev_b32_e32 v98, 2, v98
	ds_bpermute_b32 v112, v98, v94
	ds_bpermute_b32 v108, v98, v90
	ds_bpermute_b32 v113, v98, v95
	ds_bpermute_b32 v109, v98, v91
	ds_bpermute_b32 v114, v98, v96
	ds_bpermute_b32 v110, v98, v92
	ds_bpermute_b32 v115, v98, v97
	ds_bpermute_b32 v111, v98, v93
	v_mov_b64_e32 v[100:101], v[96:97]
	v_mov_b64_e32 v[98:99], v[94:95]
	s_and_saveexec_b64 s[68:69], s[8:9]
	s_cbranch_execz .LBB0_506
	s_add_i32 s15, s54, 0xffffff80
	s_lshr_b32 s15, s15, 1
	v_add_u32_e32 v98, s15, v116
	v_ashrrev_i32_e32 v99, 31, v98
	v_lshlrev_b64 v[118:119], 2, v[98:99]
	v_lshl_add_u64 v[102:103], s[18:19], 0, v[118:119]
	global_load_dwordx4 v[98:101], v[102:103], off
	s_nop 0
	global_load_dwordx4 v[102:105], v[102:103], off offset:16
	v_lshl_add_u64 v[122:123], s[16:17], 0, v[118:119]
	global_load_dwordx4 v[118:121], v[122:123], off
	s_nop 0
	global_load_dwordx4 v[122:125], v[122:123], off offset:16
	v_mov_b32_e32 v126, v152
	v_mov_b32_e32 v127, v152
	s_waitcnt vmcnt(3)
	v_pk_mul_f32 v[100:101], v[126:127], v[100:101]
	v_pk_mul_f32 v[98:99], v[152:153], v[98:99]
	s_waitcnt vmcnt(2)
	v_pk_mul_f32 v[104:105], v[126:127], v[104:105]
	v_pk_mul_f32 v[102:103], v[152:153], v[102:103]
	s_waitcnt lgkmcnt(1)
	v_pk_mul_f32 v[100:101], v[100:101], v[114:115]
	v_pk_mul_f32 v[98:99], v[98:99], v[112:113]
	s_waitcnt lgkmcnt(0)
	v_pk_mul_f32 v[104:105], v[104:105], v[110:111]
	v_pk_mul_f32 v[102:103], v[102:103], v[108:109]
	s_waitcnt vmcnt(1)
	v_pk_fma_f32 v[100:101], v[96:97], v[120:121], v[100:101]
	v_pk_fma_f32 v[98:99], v[94:95], v[118:119], v[98:99]
	s_waitcnt vmcnt(0)
	v_pk_fma_f32 v[104:105], v[92:93], v[124:125], v[104:105]
	v_pk_fma_f32 v[102:103], v[90:91], v[122:123], v[102:103]

; __device__ __forceinline__ unsigned cvt_pk(float lo, float hi) { unsigned r; asm volatile("v_cvt_pk_bf16_f32 %0, %1, %2" : "=v"(r) : "v"(lo), "v"(hi)); return r; }
;     __device__ __forceinline__ void operator()(const Acc& acc, const Unit& u, int wr, int wc, int fr, int fq) const {
;     ...
;             for (int m = 0; m < 4; ++m) { const int row = u.pm * 256 + ai * 128 + wr * 64 + m * 16 + fr; const size_t R = (size_t)u.pb * NT + row;
;                 const f32x4 sa = *(const f32x4*)(stats + R * 8 + (ISQ ? 0 : 4));
;                 float rr = rsqrtf(((sa[0] + sa[1]) + (sa[2] + sa[3])) * (ISQ ? (1.f / 256.f) : (1.f / 128.f)) + EPS); if (ISQ) rr *= QSCALE;
; #pragma unroll
;                 for (int bj = 0; bj < 2; ++bj) { const int cg_ = u.pn * 256 + bj * 128 + wc * 32; const int h = cg_ / 192, d0 = cg_ - h * 192;
;                     f32x4 a = acc[ai][bj][m][0], b = acc[ai][bj][m][1];
;                     if (d0 < 128) { a = a * rr; b = b * rr; }
;                     else { if (ISQ) { a = a * rr; b = b * rr; }
;                         f32x4 pa, pb;
; #pragma unroll
;                         for (int i = 0; i < 4; ++i) { pa[i] = __shfl_xor(a[i], 32); pb[i] = __shfl_xor(b[i], 32); }
;                         if (row < TL) { const int ti = row * 32 + ((d0 - 128) >> 5) * 16 + 8 * (fq & 1); const float sg = fq < 2 ? -1.f : 1.f;
;                             const f32x4 c0 = *(const f32x4*)(cosT + ti), c1 = *(const f32x4*)(cosT + ti + 4), s0 = *(const f32x4*)(sinT + ti) * sg, s1 = *(const f32x4*)(sinT + ti + 4) * sg;
;                             a = a * c0 + pa * s0; b = b * c1 + pb * s1; } }
;                     bf16_t* dst = O + ((size_t)(u.pb * 4 + h) * NT + row) * pitch + d0 + 8 * fq;
;                     u32x4 w; w.x = cvt_pk(a[0], a[1]); w.y = cvt_pk(a[2], a[3]); w.z = cvt_pk(b[0], b[1]); w.w = cvt_pk(b[2], b[3]); *(u32x4*)dst = w; } }
.LBB0_515:
	v_lshl_add_u64 v[82:83], s[66:67], 0, v[106:107]
	v_mov_b64_e32 v[84:85], s[22:23]
	v_mad_u64_u32 v[84:85], s[8:9], v82, s34, v[84:85]
	v_mov_b32_e32 v82, v85
	v_mad_u64_u32 v[82:83], s[8:9], v83, s34, v[82:83]
	v_mov_b32_e32 v85, v82
	v_lshl_add_u64 v[82:83], s[56:57], 1, v[84:85]
	v_lshl_add_u64 v[86:87], v[150:151], 1, v[82:83]
	v_cvt_pk_bf16_f32 v82, v90, v91
	v_add3_u32 v90, s38, v173, 48
	v_cvt_pk_bf16_f32 v83, v92, v93
	v_ashrrev_i32_e32 v91, 31, v90
	v_cvt_pk_bf16_f32 v84, v94, v95
	v_cvt_pk_bf16_f32 v85, v96, v97
	global_store_dwordx4 v[86:87], v[82:85], off
	s_and_b64 vcc, exec, s[4:5]
	v_cmp_gt_i32_e64 s[8:9], s78, v90
	v_lshl_add_u64 v[82:83], s[58:59], 0, v[90:91]
	v_lshlrev_b64 v[82:83], 5, v[82:83]
	v_lshl_add_u64 v[82:83], s[12:13], 0, v[82:83]
	v_mov_b64_e32 v[82:83], v[196:197]
	v_mov_b64_e32 v[84:85], v[198:199]
	s_waitcnt lgkmcnt(2)
	v_lshl_or_b32 v100, v90, 5, v172
	s_mov_b64 s[68:69], -1
	s_waitcnt vmcnt(0)
	v_mov_b32_e32 v86, v83
	v_mov_b32_e32 v87, v84
	v_mov_b32_e32 v83, v85
	v_pk_add_f32 v[82:83], v[86:87], v[82:83]
	s_nop 0
	v_add_f32_e32 v82, v82, v83
	s_waitcnt lgkmcnt(0)
	v_fmamk_f32 v101, v82, 0x3c000000, v169
	v_cmp_gt_f32_e64 s[10:11], s97, v101
	s_cbranch_vccnz .LBB0_519
	v_and_b32_e32 v83, 64, v171
	v_xor_b32_e32 v82, 32, v171
	v_add_u32_e32 v83, 64, v83
	v_cmp_lt_i32_e32 vcc, v82, v83
	v_mov_b64_e32 v[88:89], v[76:77]
	v_mov_b64_e32 v[86:87], v[74:75]
	v_cndmask_b32_e32 v82, v171, v82, vcc
	v_lshlrev_b32_e32 v82, 2, v82
	ds_bpermute_b32 v96, v82, v78
	ds_bpermute_b32 v92, v82, v74
	ds_bpermute_b32 v97, v82, v79
	ds_bpermute_b32 v93, v82, v75
	ds_bpermute_b32 v98, v82, v80
	ds_bpermute_b32 v94, v82, v76
	ds_bpermute_b32 v99, v82, v81
	ds_bpermute_b32 v95, v82, v77
	v_mov_b64_e32 v[84:85], v[80:81]
	v_mov_b64_e32 v[82:83], v[78:79]
	s_and_saveexec_b64 s[68:69], s[8:9]
	s_cbranch_execz .LBB0_518
	s_add_i32 s15, s54, 0xffffff80
	s_lshr_b32 s15, s15, 1
	v_add_u32_e32 v82, s15, v100
	v_ashrrev_i32_e32 v83, 31, v82
	v_lshlrev_b64 v[102:103], 2, v[82:83]
	v_lshl_add_u64 v[86:87], s[18:19], 0, v[102:103]
	global_load_dwordx4 v[82:85], v[86:87], off
	s_nop 0
	global_load_dwordx4 v[86:89], v[86:87], off offset:16
	v_lshl_add_u64 v[106:107], s[16:17], 0, v[102:103]
	global_load_dwordx4 v[102:105], v[106:107], off
	s_nop 0
	global_load_dwordx4 v[106:109], v[106:107], off offset:16
	v_mov_b32_e32 v110, v152
	v_mov_b32_e32 v111, v152
	s_waitcnt vmcnt(3)
	v_pk_mul_f32 v[84:85], v[110:111], v[84:85]
	v_pk_mul_f32 v[82:83], v[152:153], v[82:83]
	s_waitcnt vmcnt(2)
	v_pk_mul_f32 v[88:89], v[110:111], v[88:89]
	v_pk_mul_f32 v[86:87], v[152:153], v[86:87]
	s_waitcnt lgkmcnt(1)
	v_pk_mul_f32 v[84:85], v[84:85], v[98:99]
	v_pk_mul_f32 v[82:83], v[82:83], v[96:97]
	s_waitcnt lgkmcnt(0)
	v_pk_mul_f32 v[88:89], v[88:89], v[94:95]
	v_pk_mul_f32 v[86:87], v[86:87], v[92:93]
	s_waitcnt vmcnt(1)
	v_pk_fma_f32 v[84:85], v[80:81], v[104:105], v[84:85]
	v_pk_fma_f32 v[82:83], v[78:79], v[102:103], v[82:83]
	s_waitcnt vmcnt(0)
	v_pk_fma_f32 v[88:89], v[76:77], v[108:109], v[88:89]
	v_pk_fma_f32 v[86:87], v[74:75], v[106:107], v[86:87]

; __device__ __forceinline__ unsigned cvt_pk(float lo, float hi) { unsigned r; asm volatile("v_cvt_pk_bf16_f32 %0, %1, %2" : "=v"(r) : "v"(lo), "v"(hi)); return r; }
;     __device__ __forceinline__ void operator()(const Acc& acc, const Unit& u, int wr, int wc, int fr, int fq) const {
;     ...
;             for (int m = 0; m < 4; ++m) { const int row = u.pm * 256 + ai * 128 + wr * 64 + m * 16 + fr; const size_t R = (size_t)u.pb * NT + row;
;                 const f32x4 sa = *(const f32x4*)(stats + R * 8 + (ISQ ? 0 : 4));
;                 float rr = rsqrtf(((sa[0] + sa[1]) + (sa[2] + sa[3])) * (ISQ ? (1.f / 256.f) : (1.f / 128.f)) + EPS); if (ISQ) rr *= QSCALE;
; #pragma unroll
;                 for (int bj = 0; bj < 2; ++bj) { const int cg_ = u.pn * 256 + bj * 128 + wc * 32; const int h = cg_ / 192, d0 = cg_ - h * 192;
;                     f32x4 a = acc[ai][bj][m][0], b = acc[ai][bj][m][1];
;                     if (d0 < 128) { a = a * rr; b = b * rr; }
;                     else { if (ISQ) { a = a * rr; b = b * rr; }
;                         f32x4 pa, pb;
; #pragma unroll
;                         for (int i = 0; i < 4; ++i) { pa[i] = __shfl_xor(a[i], 32); pb[i] = __shfl_xor(b[i], 32); }
;                         if (row < TL) { const int ti = row * 32 + ((d0 - 128) >> 5) * 16 + 8 * (fq & 1); const float sg = fq < 2 ? -1.f : 1.f;
;                             const f32x4 c0 = *(const f32x4*)(cosT + ti), c1 = *(const f32x4*)(cosT + ti + 4), s0 = *(const f32x4*)(sinT + ti) * sg, s1 = *(const f32x4*)(sinT + ti + 4) * sg;
;                             a = a * c0 + pa * s0; b = b * c1 + pb * s1; } }
;                     bf16_t* dst = O + ((size_t)(u.pb * 4 + h) * NT + row) * pitch + d0 + 8 * fq;
;                     u32x4 w; w.x = cvt_pk(a[0], a[1]); w.y = cvt_pk(a[2], a[3]); w.z = cvt_pk(b[0], b[1]); w.w = cvt_pk(b[2], b[3]); *(u32x4*)dst = w; } }
.LBB0_527:
	v_lshl_add_u64 v[66:67], s[66:67], 0, v[90:91]
	v_mov_b64_e32 v[68:69], s[22:23]
	v_mad_u64_u32 v[68:69], s[8:9], v66, s34, v[68:69]
	v_mov_b32_e32 v66, v69
	v_mad_u64_u32 v[66:67], s[8:9], v67, s34, v[66:67]
	v_mov_b32_e32 v69, v66
	v_lshl_add_u64 v[66:67], s[56:57], 1, v[68:69]
	v_lshl_add_u64 v[70:71], v[150:151], 1, v[66:67]
	v_cvt_pk_bf16_f32 v66, v74, v75
	v_add_u32_e32 v74, 0x80, v154
	v_cvt_pk_bf16_f32 v67, v76, v77
	v_ashrrev_i32_e32 v75, 31, v74
	v_cvt_pk_bf16_f32 v68, v78, v79
	v_cvt_pk_bf16_f32 v69, v80, v81
	global_store_dwordx4 v[70:71], v[66:69], off
	s_and_b64 vcc, exec, s[4:5]
	v_cmp_gt_i32_e64 s[8:9], s78, v74
	v_lshl_add_u64 v[66:67], s[58:59], 0, v[74:75]
	v_lshlrev_b64 v[66:67], 5, v[66:67]
	v_lshl_add_u64 v[66:67], s[12:13], 0, v[66:67]
	v_mov_b64_e32 v[66:67], v[200:201]
	v_mov_b64_e32 v[68:69], v[202:203]
	s_waitcnt lgkmcnt(2)
	v_lshl_or_b32 v84, v74, 5, v172
	s_mov_b64 s[68:69], -1
	s_waitcnt vmcnt(0)
	v_mov_b32_e32 v70, v67
	v_mov_b32_e32 v71, v68
	v_mov_b32_e32 v67, v69
	v_pk_add_f32 v[66:67], v[70:71], v[66:67]
	s_nop 0
	v_add_f32_e32 v66, v66, v67
	s_waitcnt lgkmcnt(0)
	v_fmamk_f32 v85, v66, 0x3c000000, v169
	v_cmp_gt_f32_e64 s[10:11], s97, v85
	s_cbranch_vccnz .LBB0_531
	v_and_b32_e32 v67, 64, v171
	v_xor_b32_e32 v66, 32, v171
	v_add_u32_e32 v67, 64, v67
	v_cmp_lt_i32_e32 vcc, v66, v67
	v_mov_b64_e32 v[72:73], v[60:61]
	v_mov_b64_e32 v[70:71], v[58:59]
	v_cndmask_b32_e32 v66, v171, v66, vcc
	v_lshlrev_b32_e32 v66, 2, v66
	ds_bpermute_b32 v80, v66, v62
	ds_bpermute_b32 v76, v66, v58
	ds_bpermute_b32 v81, v66, v63
	ds_bpermute_b32 v77, v66, v59
	ds_bpermute_b32 v82, v66, v64
	ds_bpermute_b32 v78, v66, v60
	ds_bpermute_b32 v83, v66, v65
	ds_bpermute_b32 v79, v66, v61
	v_mov_b64_e32 v[68:69], v[64:65]
	v_mov_b64_e32 v[66:67], v[62:63]
	s_and_saveexec_b64 s[68:69], s[8:9]
	s_cbranch_execz .LBB0_530
	s_add_i32 s15, s54, 0xffffff80
	s_lshr_b32 s15, s15, 1
	v_add_u32_e32 v66, s15, v84
	v_ashrrev_i32_e32 v67, 31, v66
	v_lshlrev_b64 v[86:87], 2, v[66:67]
	v_lshl_add_u64 v[70:71], s[18:19], 0, v[86:87]
	global_load_dwordx4 v[66:69], v[70:71], off
	s_nop 0
	global_load_dwordx4 v[70:73], v[70:71], off offset:16
	v_lshl_add_u64 v[90:91], s[16:17], 0, v[86:87]
	global_load_dwordx4 v[86:89], v[90:91], off
	s_nop 0
	global_load_dwordx4 v[90:93], v[90:91], off offset:16
	v_mov_b32_e32 v94, v152
	v_mov_b32_e32 v95, v152
	s_waitcnt vmcnt(3)
	v_pk_mul_f32 v[68:69], v[94:95], v[68:69]
	v_pk_mul_f32 v[66:67], v[152:153], v[66:67]
	s_waitcnt vmcnt(2)
	v_pk_mul_f32 v[72:73], v[94:95], v[72:73]
	v_pk_mul_f32 v[70:71], v[152:153], v[70:71]
	s_waitcnt lgkmcnt(1)
	v_pk_mul_f32 v[68:69], v[68:69], v[82:83]
	v_pk_mul_f32 v[66:67], v[66:67], v[80:81]
	s_waitcnt lgkmcnt(0)
	v_pk_mul_f32 v[72:73], v[72:73], v[78:79]
	v_pk_mul_f32 v[70:71], v[70:71], v[76:77]
	s_waitcnt vmcnt(1)
	v_pk_fma_f32 v[68:69], v[64:65], v[88:89], v[68:69]
	v_pk_fma_f32 v[66:67], v[62:63], v[86:87], v[66:67]
	s_waitcnt vmcnt(0)
	v_pk_fma_f32 v[72:73], v[60:61], v[92:93], v[72:73]
	v_pk_fma_f32 v[70:71], v[58:59], v[90:91], v[70:71]

; __device__ __forceinline__ unsigned cvt_pk(float lo, float hi) { unsigned r; asm volatile("v_cvt_pk_bf16_f32 %0, %1, %2" : "=v"(r) : "v"(lo), "v"(hi)); return r; }
;     __device__ __forceinline__ void operator()(const Acc& acc, const Unit& u, int wr, int wc, int fr, int fq) const {
;     ...
;             for (int m = 0; m < 4; ++m) { const int row = u.pm * 256 + ai * 128 + wr * 64 + m * 16 + fr; const size_t R = (size_t)u.pb * NT + row;
;                 const f32x4 sa = *(const f32x4*)(stats + R * 8 + (ISQ ? 0 : 4));
;                 float rr = rsqrtf(((sa[0] + sa[1]) + (sa[2] + sa[3])) * (ISQ ? (1.f / 256.f) : (1.f / 128.f)) + EPS); if (ISQ) rr *= QSCALE;
; #pragma unroll
;                 for (int bj = 0; bj < 2; ++bj) { const int cg_ = u.pn * 256 + bj * 128 + wc * 32; const int h = cg_ / 192, d0 = cg_ - h * 192;
;                     f32x4 a = acc[ai][bj][m][0], b = acc[ai][bj][m][1];
;                     if (d0 < 128) { a = a * rr; b = b * rr; }
;                     else { if (ISQ) { a = a * rr; b = b * rr; }
;                         f32x4 pa, pb;
; #pragma unroll
;                         for (int i = 0; i < 4; ++i) { pa[i] = __shfl_xor(a[i], 32); pb[i] = __shfl_xor(b[i], 32); }
;                         if (row < TL) { const int ti = row * 32 + ((d0 - 128) >> 5) * 16 + 8 * (fq & 1); const float sg = fq < 2 ? -1.f : 1.f;
;                             const f32x4 c0 = *(const f32x4*)(cosT + ti), c1 = *(const f32x4*)(cosT + ti + 4), s0 = *(const f32x4*)(sinT + ti) * sg, s1 = *(const f32x4*)(sinT + ti + 4) * sg;
;                             a = a * c0 + pa * s0; b = b * c1 + pb * s1; } }
;                     bf16_t* dst = O + ((size_t)(u.pb * 4 + h) * NT + row) * pitch + d0 + 8 * fq;
;                     u32x4 w; w.x = cvt_pk(a[0], a[1]); w.y = cvt_pk(a[2], a[3]); w.z = cvt_pk(b[0], b[1]); w.w = cvt_pk(b[2], b[3]); *(u32x4*)dst = w; } }
.LBB0_539:
	v_lshl_add_u64 v[50:51], s[66:67], 0, v[74:75]
	v_mov_b64_e32 v[52:53], s[22:23]
	v_mad_u64_u32 v[52:53], s[8:9], v50, s34, v[52:53]
	v_mov_b32_e32 v50, v53
	v_mad_u64_u32 v[50:51], s[8:9], v51, s34, v[50:51]
	v_mov_b32_e32 v53, v50
	v_lshl_add_u64 v[50:51], s[56:57], 1, v[52:53]
	v_lshl_add_u64 v[54:55], v[150:151], 1, v[50:51]
	v_cvt_pk_bf16_f32 v50, v58, v59
	v_add_u32_e32 v58, 0x90, v154
	v_cvt_pk_bf16_f32 v51, v60, v61
	v_ashrrev_i32_e32 v59, 31, v58
	v_cvt_pk_bf16_f32 v52, v62, v63
	v_cvt_pk_bf16_f32 v53, v64, v65
	global_store_dwordx4 v[54:55], v[50:53], off
	s_and_b64 vcc, exec, s[4:5]
	v_cmp_gt_i32_e64 s[8:9], s78, v58
	v_lshl_add_u64 v[50:51], s[58:59], 0, v[58:59]
	v_lshlrev_b64 v[50:51], 5, v[50:51]
	v_lshl_add_u64 v[50:51], s[12:13], 0, v[50:51]
	v_mov_b64_e32 v[50:51], v[204:205]
	v_mov_b64_e32 v[52:53], v[206:207]
	s_waitcnt lgkmcnt(2)
	v_lshl_or_b32 v68, v58, 5, v172
	s_mov_b64 s[68:69], -1
	s_waitcnt vmcnt(0)
	v_mov_b32_e32 v54, v51
	v_mov_b32_e32 v55, v52
	v_mov_b32_e32 v51, v53
	v_pk_add_f32 v[50:51], v[54:55], v[50:51]
	s_nop 0
	v_add_f32_e32 v50, v50, v51
	s_waitcnt lgkmcnt(0)
	v_fmamk_f32 v69, v50, 0x3c000000, v169
	v_cmp_gt_f32_e64 s[10:11], s97, v69
	s_cbranch_vccnz .LBB0_543
	v_and_b32_e32 v51, 64, v171
	v_xor_b32_e32 v50, 32, v171
	v_add_u32_e32 v51, 64, v51
	v_cmp_lt_i32_e32 vcc, v50, v51
	v_mov_b64_e32 v[56:57], v[44:45]
	v_mov_b64_e32 v[54:55], v[42:43]
	v_cndmask_b32_e32 v50, v171, v50, vcc
	v_lshlrev_b32_e32 v50, 2, v50
	ds_bpermute_b32 v64, v50, v46
	ds_bpermute_b32 v60, v50, v42
	ds_bpermute_b32 v65, v50, v47
	ds_bpermute_b32 v61, v50, v43
	ds_bpermute_b32 v66, v50, v48
	ds_bpermute_b32 v62, v50, v44
	ds_bpermute_b32 v67, v50, v49
	ds_bpermute_b32 v63, v50, v45
	v_mov_b64_e32 v[52:53], v[48:49]
	v_mov_b64_e32 v[50:51], v[46:47]
	s_and_saveexec_b64 s[68:69], s[8:9]
	s_cbranch_execz .LBB0_542
	s_add_i32 s15, s54, 0xffffff80
	s_lshr_b32 s15, s15, 1
	v_add_u32_e32 v50, s15, v68
	v_ashrrev_i32_e32 v51, 31, v50
	v_lshlrev_b64 v[70:71], 2, v[50:51]
	v_lshl_add_u64 v[54:55], s[18:19], 0, v[70:71]
	global_load_dwordx4 v[50:53], v[54:55], off
	s_nop 0
	global_load_dwordx4 v[54:57], v[54:55], off offset:16
	v_lshl_add_u64 v[74:75], s[16:17], 0, v[70:71]
	global_load_dwordx4 v[70:73], v[74:75], off
	s_nop 0
	global_load_dwordx4 v[74:77], v[74:75], off offset:16
	v_mov_b32_e32 v78, v152
	v_mov_b32_e32 v79, v152
	s_waitcnt vmcnt(3)
	v_pk_mul_f32 v[52:53], v[78:79], v[52:53]
	v_pk_mul_f32 v[50:51], v[152:153], v[50:51]
	s_waitcnt vmcnt(2)
	v_pk_mul_f32 v[56:57], v[78:79], v[56:57]
	v_pk_mul_f32 v[54:55], v[152:153], v[54:55]
	s_waitcnt lgkmcnt(1)
	v_pk_mul_f32 v[52:53], v[52:53], v[66:67]
	v_pk_mul_f32 v[50:51], v[50:51], v[64:65]
	s_waitcnt lgkmcnt(0)
	v_pk_mul_f32 v[56:57], v[56:57], v[62:63]
	v_pk_mul_f32 v[54:55], v[54:55], v[60:61]
	s_waitcnt vmcnt(1)
	v_pk_fma_f32 v[52:53], v[48:49], v[72:73], v[52:53]
	v_pk_fma_f32 v[50:51], v[46:47], v[70:71], v[50:51]
	s_waitcnt vmcnt(0)
	v_pk_fma_f32 v[56:57], v[44:45], v[76:77], v[56:57]
	v_pk_fma_f32 v[54:55], v[42:43], v[74:75], v[54:55]

; __device__ __forceinline__ unsigned cvt_pk(float lo, float hi) { unsigned r; asm volatile("v_cvt_pk_bf16_f32 %0, %1, %2" : "=v"(r) : "v"(lo), "v"(hi)); return r; }
;     __device__ __forceinline__ void operator()(const Acc& acc, const Unit& u, int wr, int wc, int fr, int fq) const {
;     ...
;             for (int m = 0; m < 4; ++m) { const int row = u.pm * 256 + ai * 128 + wr * 64 + m * 16 + fr; const size_t R = (size_t)u.pb * NT + row;
;                 const f32x4 sa = *(const f32x4*)(stats + R * 8 + (ISQ ? 0 : 4));
;                 float rr = rsqrtf(((sa[0] + sa[1]) + (sa[2] + sa[3])) * (ISQ ? (1.f / 256.f) : (1.f / 128.f)) + EPS); if (ISQ) rr *= QSCALE;
; #pragma unroll
;                 for (int bj = 0; bj < 2; ++bj) { const int cg_ = u.pn * 256 + bj * 128 + wc * 32; const int h = cg_ / 192, d0 = cg_ - h * 192;
;                     f32x4 a = acc[ai][bj][m][0], b = acc[ai][bj][m][1];
;                     if (d0 < 128) { a = a * rr; b = b * rr; }
;                     else { if (ISQ) { a = a * rr; b = b * rr; }
;                         f32x4 pa, pb;
; #pragma unroll
;                         for (int i = 0; i < 4; ++i) { pa[i] = __shfl_xor(a[i], 32); pb[i] = __shfl_xor(b[i], 32); }
;                         if (row < TL) { const int ti = row * 32 + ((d0 - 128) >> 5) * 16 + 8 * (fq & 1); const float sg = fq < 2 ? -1.f : 1.f;
;                             const f32x4 c0 = *(const f32x4*)(cosT + ti), c1 = *(const f32x4*)(cosT + ti + 4), s0 = *(const f32x4*)(sinT + ti) * sg, s1 = *(const f32x4*)(sinT + ti + 4) * sg;
;                             a = a * c0 + pa * s0; b = b * c1 + pb * s1; } }
;                     bf16_t* dst = O + ((size_t)(u.pb * 4 + h) * NT + row) * pitch + d0 + 8 * fq;
;                     u32x4 w; w.x = cvt_pk(a[0], a[1]); w.y = cvt_pk(a[2], a[3]); w.z = cvt_pk(b[0], b[1]); w.w = cvt_pk(b[2], b[3]); *(u32x4*)dst = w; } }
.LBB0_551:
	v_lshl_add_u64 v[34:35], s[66:67], 0, v[58:59]
	v_mov_b64_e32 v[36:37], s[22:23]
	v_mad_u64_u32 v[36:37], s[8:9], v34, s34, v[36:37]
	v_mov_b32_e32 v34, v37
	v_mad_u64_u32 v[34:35], s[8:9], v35, s34, v[34:35]
	v_mov_b32_e32 v37, v34
	v_lshl_add_u64 v[34:35], s[56:57], 1, v[36:37]
	v_lshl_add_u64 v[38:39], v[150:151], 1, v[34:35]
	v_cvt_pk_bf16_f32 v34, v42, v43
	v_add_u32_e32 v42, 0xa0, v154
	v_cvt_pk_bf16_f32 v35, v44, v45
	v_ashrrev_i32_e32 v43, 31, v42
	v_cvt_pk_bf16_f32 v36, v46, v47
	v_cvt_pk_bf16_f32 v37, v48, v49
	global_store_dwordx4 v[38:39], v[34:37], off
	s_and_b64 vcc, exec, s[4:5]
	v_cmp_gt_i32_e64 s[8:9], s78, v42
	v_lshl_add_u64 v[34:35], s[58:59], 0, v[42:43]
	v_lshlrev_b64 v[34:35], 5, v[34:35]
	v_lshl_add_u64 v[34:35], s[12:13], 0, v[34:35]
	v_mov_b64_e32 v[34:35], v[208:209]
	v_mov_b64_e32 v[36:37], v[210:211]
	s_waitcnt lgkmcnt(2)
	v_lshl_or_b32 v52, v42, 5, v172
	s_mov_b64 s[68:69], -1
	s_waitcnt vmcnt(0)
	v_mov_b32_e32 v38, v35
	v_mov_b32_e32 v39, v36
	v_mov_b32_e32 v35, v37
	v_pk_add_f32 v[34:35], v[38:39], v[34:35]
	s_nop 0
	v_add_f32_e32 v34, v34, v35
	s_waitcnt lgkmcnt(0)
	v_fmamk_f32 v53, v34, 0x3c000000, v169
	v_cmp_gt_f32_e64 s[10:11], s97, v53
	s_cbranch_vccnz .LBB0_555
	v_and_b32_e32 v35, 64, v171
	v_xor_b32_e32 v34, 32, v171
	v_add_u32_e32 v35, 64, v35
	v_cmp_lt_i32_e32 vcc, v34, v35
	v_mov_b64_e32 v[40:41], v[28:29]
	v_mov_b64_e32 v[38:39], v[26:27]
	v_cndmask_b32_e32 v34, v171, v34, vcc
	v_lshlrev_b32_e32 v34, 2, v34
	ds_bpermute_b32 v48, v34, v30
	ds_bpermute_b32 v44, v34, v26
	ds_bpermute_b32 v49, v34, v31
	ds_bpermute_b32 v45, v34, v27
	ds_bpermute_b32 v50, v34, v32
	ds_bpermute_b32 v46, v34, v28
	ds_bpermute_b32 v51, v34, v33
	ds_bpermute_b32 v47, v34, v29
	v_mov_b64_e32 v[36:37], v[32:33]
	v_mov_b64_e32 v[34:35], v[30:31]
	s_and_saveexec_b64 s[68:69], s[8:9]
	s_cbranch_execz .LBB0_554
	s_add_i32 s15, s54, 0xffffff80
	s_lshr_b32 s15, s15, 1
	v_add_u32_e32 v34, s15, v52
	v_ashrrev_i32_e32 v35, 31, v34
	v_lshlrev_b64 v[54:55], 2, v[34:35]
	v_lshl_add_u64 v[38:39], s[18:19], 0, v[54:55]
	global_load_dwordx4 v[34:37], v[38:39], off
	s_nop 0
	global_load_dwordx4 v[38:41], v[38:39], off offset:16
	v_lshl_add_u64 v[58:59], s[16:17], 0, v[54:55]
	global_load_dwordx4 v[54:57], v[58:59], off
	s_nop 0
	global_load_dwordx4 v[58:61], v[58:59], off offset:16
	v_mov_b32_e32 v62, v152
	v_mov_b32_e32 v63, v152
	s_waitcnt vmcnt(3)
	v_pk_mul_f32 v[36:37], v[62:63], v[36:37]
	v_pk_mul_f32 v[34:35], v[152:153], v[34:35]
	s_waitcnt vmcnt(2)
	v_pk_mul_f32 v[40:41], v[62:63], v[40:41]
	v_pk_mul_f32 v[38:39], v[152:153], v[38:39]
	s_waitcnt lgkmcnt(1)
	v_pk_mul_f32 v[36:37], v[36:37], v[50:51]
	v_pk_mul_f32 v[34:35], v[34:35], v[48:49]
	s_waitcnt lgkmcnt(0)
	v_pk_mul_f32 v[40:41], v[40:41], v[46:47]
	v_pk_mul_f32 v[38:39], v[38:39], v[44:45]
	s_waitcnt vmcnt(1)
	v_pk_fma_f32 v[36:37], v[32:33], v[56:57], v[36:37]
	v_pk_fma_f32 v[34:35], v[30:31], v[54:55], v[34:35]
	s_waitcnt vmcnt(0)
	v_pk_fma_f32 v[40:41], v[28:29], v[60:61], v[40:41]
	v_pk_fma_f32 v[38:39], v[26:27], v[58:59], v[38:39]

; __device__ __forceinline__ unsigned cvt_pk(float lo, float hi) { unsigned r; asm volatile("v_cvt_pk_bf16_f32 %0, %1, %2" : "=v"(r) : "v"(lo), "v"(hi)); return r; }
;     __device__ __forceinline__ void operator()(const Acc& acc, const Unit& u, int wr, int wc, int fr, int fq) const {
;     ...
;             for (int m = 0; m < 4; ++m) { const int row = u.pm * 256 + ai * 128 + wr * 64 + m * 16 + fr; const size_t R = (size_t)u.pb * NT + row;
;                 const f32x4 sa = *(const f32x4*)(stats + R * 8 + (ISQ ? 0 : 4));
;                 float rr = rsqrtf(((sa[0] + sa[1]) + (sa[2] + sa[3])) * (ISQ ? (1.f / 256.f) : (1.f / 128.f)) + EPS); if (ISQ) rr *= QSCALE;
; #pragma unroll
;                 for (int bj = 0; bj < 2; ++bj) { const int cg_ = u.pn * 256 + bj * 128 + wc * 32; const int h = cg_ / 192, d0 = cg_ - h * 192;
;                     f32x4 a = acc[ai][bj][m][0], b = acc[ai][bj][m][1];
;                     if (d0 < 128) { a = a * rr; b = b * rr; }
;                     else { if (ISQ) { a = a * rr; b = b * rr; }
;                         f32x4 pa, pb;
; #pragma unroll
;                         for (int i = 0; i < 4; ++i) { pa[i] = __shfl_xor(a[i], 32); pb[i] = __shfl_xor(b[i], 32); }
;                         if (row < TL) { const int ti = row * 32 + ((d0 - 128) >> 5) * 16 + 8 * (fq & 1); const float sg = fq < 2 ? -1.f : 1.f;
;                             const f32x4 c0 = *(const f32x4*)(cosT + ti), c1 = *(const f32x4*)(cosT + ti + 4), s0 = *(const f32x4*)(sinT + ti) * sg, s1 = *(const f32x4*)(sinT + ti + 4) * sg;
;                             a = a * c0 + pa * s0; b = b * c1 + pb * s1; } }
;                     bf16_t* dst = O + ((size_t)(u.pb * 4 + h) * NT + row) * pitch + d0 + 8 * fq;
;                     u32x4 w; w.x = cvt_pk(a[0], a[1]); w.y = cvt_pk(a[2], a[3]); w.z = cvt_pk(b[0], b[1]); w.w = cvt_pk(b[2], b[3]); *(u32x4*)dst = w; } }
.LBB0_563:
	v_lshl_add_u64 v[18:19], s[66:67], 0, v[42:43]
	v_mov_b64_e32 v[20:21], s[22:23]
	v_mad_u64_u32 v[20:21], s[8:9], v18, s34, v[20:21]
	v_mov_b32_e32 v18, v21
	v_mad_u64_u32 v[18:19], s[8:9], v19, s34, v[18:19]
	v_mov_b32_e32 v21, v18
	v_lshl_add_u64 v[18:19], s[56:57], 1, v[20:21]
	v_lshl_add_u64 v[22:23], v[150:151], 1, v[18:19]
	v_cvt_pk_bf16_f32 v18, v26, v27
	v_add_u32_e32 v26, 0xb0, v154
	v_cvt_pk_bf16_f32 v19, v28, v29
	v_ashrrev_i32_e32 v27, 31, v26
	v_cvt_pk_bf16_f32 v20, v30, v31
	v_cvt_pk_bf16_f32 v21, v32, v33
	global_store_dwordx4 v[22:23], v[18:21], off
	s_and_b64 vcc, exec, s[4:5]
	v_cmp_gt_i32_e64 s[4:5], s78, v26
	v_lshl_add_u64 v[18:19], s[58:59], 0, v[26:27]
	v_lshlrev_b64 v[18:19], 5, v[18:19]
	v_lshl_add_u64 v[18:19], s[12:13], 0, v[18:19]
	v_mov_b64_e32 v[18:19], v[212:213]
	v_mov_b64_e32 v[20:21], v[214:215]
	s_waitcnt lgkmcnt(2)
	v_lshl_or_b32 v36, v26, 5, v172
	s_mov_b64 s[10:11], -1
	s_waitcnt vmcnt(0)
	v_mov_b32_e32 v22, v19
	v_mov_b32_e32 v23, v20
	v_mov_b32_e32 v19, v21
	v_pk_add_f32 v[18:19], v[22:23], v[18:19]
	s_nop 0
	v_add_f32_e32 v18, v18, v19
	s_waitcnt lgkmcnt(0)
	v_fmamk_f32 v37, v18, 0x3c000000, v169
	v_cmp_gt_f32_e64 s[8:9], s97, v37
	s_cbranch_vccnz .LBB0_567
	v_and_b32_e32 v19, 64, v171
	v_xor_b32_e32 v18, 32, v171
	v_add_u32_e32 v19, 64, v19
	v_cmp_lt_i32_e32 vcc, v18, v19
	v_mov_b64_e32 v[24:25], v[12:13]
	v_mov_b64_e32 v[22:23], v[10:11]
	v_cndmask_b32_e32 v18, v171, v18, vcc
	v_lshlrev_b32_e32 v18, 2, v18
	ds_bpermute_b32 v32, v18, v14
	ds_bpermute_b32 v28, v18, v10
	ds_bpermute_b32 v33, v18, v15
	ds_bpermute_b32 v29, v18, v11
	ds_bpermute_b32 v34, v18, v16
	ds_bpermute_b32 v30, v18, v12
	ds_bpermute_b32 v35, v18, v17
	ds_bpermute_b32 v31, v18, v13
	v_mov_b64_e32 v[20:21], v[16:17]
	v_mov_b64_e32 v[18:19], v[14:15]
	s_and_saveexec_b64 s[10:11], s[4:5]
	s_cbranch_execz .LBB0_566
	s_add_i32 s15, s54, 0xffffff80
	s_lshr_b32 s15, s15, 1
	v_add_u32_e32 v18, s15, v36
	v_ashrrev_i32_e32 v19, 31, v18
	v_lshlrev_b64 v[38:39], 2, v[18:19]
	v_lshl_add_u64 v[22:23], s[18:19], 0, v[38:39]
	global_load_dwordx4 v[18:21], v[22:23], off
	s_nop 0
	global_load_dwordx4 v[22:25], v[22:23], off offset:16
	v_lshl_add_u64 v[42:43], s[16:17], 0, v[38:39]
	global_load_dwordx4 v[38:41], v[42:43], off
	s_nop 0
	global_load_dwordx4 v[42:45], v[42:43], off offset:16
	v_mov_b32_e32 v46, v152
	v_mov_b32_e32 v47, v152
	s_waitcnt vmcnt(3)
	v_pk_mul_f32 v[20:21], v[46:47], v[20:21]
	v_pk_mul_f32 v[18:19], v[152:153], v[18:19]
	s_waitcnt vmcnt(2)
	v_pk_mul_f32 v[24:25], v[46:47], v[24:25]
	v_pk_mul_f32 v[22:23], v[152:153], v[22:23]
	s_waitcnt lgkmcnt(1)
	v_pk_mul_f32 v[20:21], v[20:21], v[34:35]
	v_pk_mul_f32 v[18:19], v[18:19], v[32:33]
	s_waitcnt lgkmcnt(0)
	v_pk_mul_f32 v[24:25], v[24:25], v[30:31]
	v_pk_mul_f32 v[22:23], v[22:23], v[28:29]
	s_waitcnt vmcnt(1)
	v_pk_fma_f32 v[20:21], v[16:17], v[40:41], v[20:21]
	v_pk_fma_f32 v[18:19], v[14:15], v[38:39], v[18:19]
	s_waitcnt vmcnt(0)
	v_pk_fma_f32 v[24:25], v[12:13], v[44:45], v[24:25]
	v_pk_fma_f32 v[22:23], v[10:11], v[42:43], v[22:23]

; #define LAS __attribute__((address_space(3)))
; __device__ __forceinline__ void attn_unit(LAS unsigned char* lds, int b, int h, int q0, int kbeg, int ntiles, const bf16_t* Q, const bf16_t* K, const bf16_t* Vt, bf16_t* cat) {
;     ...
;     asm volatile("s_waitcnt vmcnt(0)" ::: "memory");
;     __syncthreads();
;     f32x16 pc0, pc1;
;     { const LAS unsigned char* kb = lds + r32 * (KP * 2) + hi * 16;
; #pragma unroll
;       for (int r = 0; r < 16; ++r) { pc0[r] = 0.f; pc1[r] = 0.f; }
; #pragma unroll
;       for (int ds = 0; ds < 12; ++ds) {
;           const bf16x8 k0 = *(const LAS bf16x8*)(kb + ds * 32), k1 = *(const LAS bf16x8*)(kb + 32 * (KP * 2) + ds * 32);
;           pc0 = __builtin_amdgcn_mfma_f32_32x32x16_bf16(k0, qf[ds], pc0, 0, 0, 0);
;           pc1 = __builtin_amdgcn_mfma_f32_32x32x16_bf16(k1, qf[ds], pc1, 0, 0, 0); } }
;     float mxc;
;     { float mx = fmaxf(pc0[0], pc1[0]);
; #pragma unroll
;       for (int r = 1; r < 16; ++r) mx = fmaxf(mx, fmaxf(pc0[r], pc1[r]));
;       mxc = fmaxf(mx, __shfl_xor(mx, 32)); }
;     __syncthreads();
;     for (int kt = 0; kt < ntiles; ++kt) {
;         const int buf = kt & 1;
;         if (kt + 2 < ntiles) ALOADK(kt + 2, buf);
.LBB0_798:
	v_mad_u32_u24 v36, v34, s90, 0
	v_lshl_add_u32 v193, v35, 4, v36
	s_waitcnt lgkmcnt(0)
	s_waitcnt lgkmcnt(0)
	s_barrier
	ds_read_b128 v[2:5], v193
	ds_read_b128 v[38:41], v193 offset:32
	s_waitcnt lgkmcnt(1)
	v_mfma_f32_32x32x16_bf16 v[18:33], v[2:5], v[174:177], 0
	ds_read_b128 v[2:5], v193 offset:12800
	ds_read_b128 v[42:45], v193 offset:12832
	v_lshl_add_u64 v[50:51], v[122:123], 0, s[52:53]
	s_mov_b32 m0, s16
	v_lshl_add_u64 v[52:53], v[50:51], 0, s[8:9]
	s_waitcnt lgkmcnt(1)
	v_mfma_f32_32x32x16_bf16 v[2:17], v[2:5], v[174:177], 0
	v_mfma_f32_32x32x16_bf16 v[18:33], v[38:41], v[170:173], v[18:33]
	s_waitcnt lgkmcnt(0)
	v_mfma_f32_32x32x16_bf16 v[2:17], v[42:45], v[170:173], v[2:17]
	ds_read_b128 v[38:41], v193 offset:64
	ds_read_b128 v[42:45], v193 offset:96
	s_waitcnt lgkmcnt(1)
	v_mfma_f32_32x32x16_bf16 v[18:33], v[38:41], v[166:169], v[18:33]
	ds_read_b128 v[38:41], v193 offset:12864
	ds_read_b128 v[46:49], v193 offset:12896
	s_waitcnt lgkmcnt(1)
	v_mfma_f32_32x32x16_bf16 v[2:17], v[38:41], v[166:169], v[2:17]
	v_mfma_f32_32x32x16_bf16 v[18:33], v[42:45], v[162:165], v[18:33]
	ds_read_b128 v[38:41], v193 offset:128
	ds_read_b128 v[42:45], v193 offset:160
	s_waitcnt lgkmcnt(2)
	v_mfma_f32_32x32x16_bf16 v[2:17], v[46:49], v[162:165], v[2:17]
	s_waitcnt lgkmcnt(1)
	v_mfma_f32_32x32x16_bf16 v[18:33], v[38:41], v[158:161], v[18:33]
	ds_read_b128 v[38:41], v193 offset:12928
	ds_read_b128 v[46:49], v193 offset:12960
	s_waitcnt lgkmcnt(1)
	v_mfma_f32_32x32x16_bf16 v[2:17], v[38:41], v[158:161], v[2:17]
	v_mfma_f32_32x32x16_bf16 v[18:33], v[42:45], v[154:157], v[18:33]
	ds_read_b128 v[38:41], v193 offset:192
	ds_read_b128 v[42:45], v193 offset:224
	s_waitcnt lgkmcnt(2)
	v_mfma_f32_32x32x16_bf16 v[2:17], v[46:49], v[154:157], v[2:17]
	s_waitcnt lgkmcnt(1)
	v_mfma_f32_32x32x16_bf16 v[18:33], v[38:41], v[150:153], v[18:33]
	ds_read_b128 v[38:41], v193 offset:12992
	ds_read_b128 v[46:49], v193 offset:13024
	s_waitcnt lgkmcnt(1)
	v_mfma_f32_32x32x16_bf16 v[2:17], v[38:41], v[150:153], v[2:17]
	v_mfma_f32_32x32x16_bf16 v[18:33], v[42:45], v[146:149], v[18:33]
	ds_read_b128 v[38:41], v193 offset:256
	ds_read_b128 v[42:45], v193 offset:288
	s_waitcnt lgkmcnt(2)
	v_mfma_f32_32x32x16_bf16 v[2:17], v[46:49], v[146:149], v[2:17]
	s_waitcnt lgkmcnt(1)
	v_mfma_f32_32x32x16_bf16 v[18:33], v[38:41], v[142:145], v[18:33]
	ds_read_b128 v[38:41], v193 offset:13056
	ds_read_b128 v[46:49], v193 offset:13088
	s_waitcnt lgkmcnt(1)
	v_mfma_f32_32x32x16_bf16 v[2:17], v[38:41], v[142:145], v[2:17]
	v_mfma_f32_32x32x16_bf16 v[18:33], v[42:45], v[138:141], v[18:33]
	ds_read_b128 v[38:41], v193 offset:320
	ds_read_b128 v[42:45], v193 offset:352
	s_waitcnt lgkmcnt(2)
	v_mfma_f32_32x32x16_bf16 v[2:17], v[46:49], v[138:141], v[2:17]
	s_waitcnt lgkmcnt(1)
	v_mfma_f32_32x32x16_bf16 v[18:33], v[38:41], v[134:137], v[18:33]
	ds_read_b128 v[38:41], v193 offset:13120
	ds_read_b128 v[46:49], v193 offset:13152
	s_waitcnt vmcnt(0) lgkmcnt(0)
	s_barrier
	global_load_lds_dwordx4 v[52:53], off
	s_add_i32 m0, s16, 0x2000
	v_mfma_f32_32x32x16_bf16 v[2:17], v[38:41], v[134:137], v[2:17]
	v_lshl_add_u64 v[38:39], v[50:51], 0, s[4:5]
	global_load_lds_dwordx4 v[38:39], off
	v_lshl_add_u64 v[38:39], v[50:51], 0, s[6:7]
	s_add_i32 m0, s16, 0x4000
	s_nop 0
	global_load_lds_dwordx4 v[38:39], off
	v_mfma_f32_32x32x16_bf16 v[2:17], v[46:49], v[130:133], v[2:17]
	v_mfma_f32_32x32x16_bf16 v[18:33], v[42:45], v[130:133], v[18:33]
	s_nop 10
	v_max_f32_e32 v37, v3, v3
	v_max_f32_e32 v38, v19, v19
	v_max_f32_e32 v37, v38, v37
	v_max_f32_e32 v38, v4, v4
	v_max_f32_e32 v39, v20, v20
	v_max_f32_e32 v38, v39, v38
	v_max_f32_e32 v39, v5, v5
	v_max_f32_e32 v40, v21, v21
	v_max3_f32 v37, v18, v2, v37
	v_max_f32_e32 v39, v40, v39
	v_max3_f32 v37, v37, v38, v39
	v_max_f32_e32 v38, v6, v6
	v_max_f32_e32 v39, v22, v22
	v_max_f32_e32 v38, v39, v38
	v_max_f32_e32 v39, v7, v7
	v_max_f32_e32 v40, v23, v23
	v_max_f32_e32 v39, v40, v39
	v_max3_f32 v37, v37, v38, v39
	v_max_f32_e32 v38, v8, v8
	v_max_f32_e32 v39, v24, v24
	v_max_f32_e32 v38, v39, v38
	v_max_f32_e32 v39, v9, v9
	v_max_f32_e32 v40, v25, v25
	v_max_f32_e32 v39, v40, v39
	v_max3_f32 v37, v37, v38, v39
	v_max_f32_e32 v38, v10, v10
	v_max_f32_e32 v39, v26, v26
	v_max_f32_e32 v38, v39, v38
	v_max_f32_e32 v39, v11, v11
	v_max_f32_e32 v40, v27, v27
	v_max_f32_e32 v39, v40, v39
	v_max3_f32 v37, v37, v38, v39
	v_max_f32_e32 v38, v12, v12
	v_max_f32_e32 v39, v28, v28
	v_max_f32_e32 v38, v39, v38
	v_max_f32_e32 v39, v13, v13
	v_max_f32_e32 v40, v29, v29
	v_max_f32_e32 v39, v40, v39
	v_max3_f32 v37, v37, v38, v39
	v_max_f32_e32 v38, v14, v14
	v_max_f32_e32 v39, v30, v30
	v_max_f32_e32 v38, v39, v38
	v_max_f32_e32 v39, v15, v15
	v_max_f32_e32 v40, v31, v31
	v_max_f32_e32 v39, v40, v39
	v_max3_f32 v37, v37, v38, v39
	v_max_f32_e32 v38, v16, v16
	v_max_f32_e32 v39, v32, v32
	v_max_f32_e32 v38, v39, v38
	v_max_f32_e32 v39, v17, v17
	v_max_f32_e32 v40, v33, v33
	v_max_f32_e32 v39, v40, v39
	v_max3_f32 v37, v37, v38, v39
	v_and_b32_e32 v39, 64, v224
	v_xor_b32_e32 v38, 32, v224
	v_add_u32_e32 v39, 64, v39
	v_cmp_lt_i32_e32 vcc, v38, v39
	s_nop 1
	v_cndmask_b32_e32 v38, v224, v38, vcc
	v_lshlrev_b32_e32 v192, 2, v38
	ds_bpermute_b32 v38, v192, v37
	s_and_b64 vcc, exec, s[2:3]
	s_cbranch_vccnz .LBB0_800
	v_lshl_add_u64 v[40:41], v[122:123], 0, s[54:55]
	s_mov_b32 m0, s86
	s_nop 0
	global_load_lds_dwordx4 v[40:41], off

; #define LAS __attribute__((address_space(3)))
; __device__ __forceinline__ void attn_unit(LAS unsigned char* lds, int b, int h, int q0, int kbeg, int ntiles, const bf16_t* Q, const bf16_t* K, const bf16_t* Vt, bf16_t* cat) {
;     ...
;     f32x16 o[4];
; #pragma unroll
;     for (int d = 0; d < 4; ++d)
; #pragma unroll
;         for (int r = 0; r < 16; ++r) o[d][r] = 0.f;
;     float mrun = -1e30f, lrun = 0.f;
;     ...
;     asm volatile("s_waitcnt vmcnt(0)" ::: "memory");
;     __syncthreads();
;     f32x16 pc0, pc1;
;     { const LAS unsigned char* kb = lds + r32 * (KP * 2) + hi * 16;
; #pragma unroll
;       for (int r = 0; r < 16; ++r) { pc0[r] = 0.f; pc1[r] = 0.f; }
; #pragma unroll
;       for (int ds = 0; ds < 12; ++ds) {
;           const bf16x8 k0 = *(const LAS bf16x8*)(kb + ds * 32), k1 = *(const LAS bf16x8*)(kb + 32 * (KP * 2) + ds * 32);
;           pc0 = __builtin_amdgcn_mfma_f32_32x32x16_bf16(k0, qf[ds], pc0, 0, 0, 0);
;           pc1 = __builtin_amdgcn_mfma_f32_32x32x16_bf16(k1, qf[ds], pc1, 0, 0, 0); } }
;     float mxc;
;     { float mx = fmaxf(pc0[0], pc1[0]);
; #pragma unroll
;       for (int r = 1; r < 16; ++r) mx = fmaxf(mx, fmaxf(pc0[r], pc1[r]));
;       mxc = fmaxf(mx, __shfl_xor(mx, 32)); }
;     __syncthreads();
.LBB0_813:
	v_mad_u32_u24 v22, v19, s90, 0
	v_lshl_add_u32 v228, v4, 4, v22
	s_waitcnt lgkmcnt(0)
	s_waitcnt lgkmcnt(0)
	s_barrier
	ds_read_b128 v[6:9], v228
	ds_read_b128 v[10:13], v228 offset:32
	s_waitcnt lgkmcnt(1)
	v_mfma_f32_32x32x16_bf16 v[82:97], v[6:9], v[174:177], 0
	ds_read_b128 v[6:9], v228 offset:12800
	ds_read_b128 v[14:17], v228 offset:12832
	v_lshlrev_b32_e32 v206, 3, v4
	v_mad_i64_i32 v[20:21], s[4:5], v5, s87, 0
	s_mov_b32 s4, 0
	s_mov_b32 s5, s4
	s_mov_b32 s6, s4
	s_waitcnt lgkmcnt(2)
	v_mfma_f32_32x32x16_bf16 v[82:97], v[10:13], v[170:173], v[82:97]
	s_mov_b32 s7, s4
	s_mov_b32 s8, s4
	s_mov_b32 s9, s4
	s_mov_b32 s10, s4
	s_mov_b32 s11, s4
	s_mov_b32 s12, s4
	s_mov_b32 s13, s4
	s_waitcnt lgkmcnt(1)
	v_mfma_f32_32x32x16_bf16 v[66:81], v[6:9], v[174:177], 0
	ds_read_b128 v[6:9], v228 offset:64
	ds_read_b128 v[10:13], v228 offset:96
	s_mov_b32 s14, s4
	s_mov_b32 s15, s4
	s_mov_b32 s16, s4
	s_mov_b32 s17, s4
	s_mov_b32 s18, s4
	s_mov_b32 s19, s4
	s_waitcnt lgkmcnt(1)
	v_mfma_f32_32x32x16_bf16 v[82:97], v[6:9], v[166:169], v[82:97]
	v_mul_i32_i24_e32 v19, 0xfffffef8, v19
	v_and_b32_e32 v18, 7, v18
	v_add3_u32 v229, v22, v19, v206
	v_mov_b32_e32 v230, 0xf149f2ca
	v_mfma_f32_32x32x16_bf16 v[66:81], v[14:17], v[170:173], v[66:81]
	ds_read_b128 v[6:9], v228 offset:12864
	ds_read_b128 v[14:17], v228 offset:12896
	s_waitcnt lgkmcnt(2)
	v_mfma_f32_32x32x16_bf16 v[82:97], v[10:13], v[162:165], v[82:97]
	s_waitcnt lgkmcnt(1)
	v_mfma_f32_32x32x16_bf16 v[66:81], v[6:9], v[166:169], v[66:81]
	ds_read_b128 v[6:9], v228 offset:128
	ds_read_b128 v[10:13], v228 offset:160
	s_waitcnt lgkmcnt(1)
	v_mfma_f32_32x32x16_bf16 v[82:97], v[6:9], v[158:161], v[82:97]
	v_mfma_f32_32x32x16_bf16 v[66:81], v[14:17], v[162:165], v[66:81]
	ds_read_b128 v[6:9], v228 offset:12928
	ds_read_b128 v[14:17], v228 offset:12960
	s_waitcnt lgkmcnt(2)
	v_mfma_f32_32x32x16_bf16 v[82:97], v[10:13], v[154:157], v[82:97]
	s_waitcnt lgkmcnt(1)
	v_mfma_f32_32x32x16_bf16 v[66:81], v[6:9], v[158:161], v[66:81]
	ds_read_b128 v[6:9], v228 offset:192
	ds_read_b128 v[10:13], v228 offset:224
	s_waitcnt lgkmcnt(1)
	v_mfma_f32_32x32x16_bf16 v[82:97], v[6:9], v[150:153], v[82:97]
	v_mfma_f32_32x32x16_bf16 v[66:81], v[14:17], v[154:157], v[66:81]
	ds_read_b128 v[6:9], v228 offset:12992
	ds_read_b128 v[14:17], v228 offset:13024
	s_waitcnt lgkmcnt(2)
	v_mfma_f32_32x32x16_bf16 v[82:97], v[10:13], v[146:149], v[82:97]
	s_waitcnt lgkmcnt(1)
	v_mfma_f32_32x32x16_bf16 v[66:81], v[6:9], v[150:153], v[66:81]
	ds_read_b128 v[6:9], v228 offset:256
	ds_read_b128 v[10:13], v228 offset:288
	s_waitcnt lgkmcnt(1)
	v_mfma_f32_32x32x16_bf16 v[82:97], v[6:9], v[142:145], v[82:97]
	v_mfma_f32_32x32x16_bf16 v[66:81], v[14:17], v[146:149], v[66:81]
	ds_read_b128 v[6:9], v228 offset:13056
	ds_read_b128 v[14:17], v228 offset:13088
	s_waitcnt lgkmcnt(2)
	v_mfma_f32_32x32x16_bf16 v[82:97], v[10:13], v[138:141], v[82:97]
	s_waitcnt lgkmcnt(1)
	v_mfma_f32_32x32x16_bf16 v[66:81], v[6:9], v[142:145], v[66:81]
	ds_read_b128 v[6:9], v228 offset:320
	ds_read_b128 v[10:13], v228 offset:352
	ds_read_b128 v[2:5], v228 offset:13152
	s_waitcnt lgkmcnt(2)
	v_mfma_f32_32x32x16_bf16 v[82:97], v[6:9], v[134:137], v[82:97]
	ds_read_b128 v[6:9], v228 offset:13120
	s_waitcnt vmcnt(0) lgkmcnt(0)
	s_barrier
	v_mfma_f32_32x32x16_bf16 v[66:81], v[14:17], v[138:141], v[66:81]
	v_mfma_f32_32x32x16_bf16 v[66:81], v[6:9], v[134:137], v[66:81]
	v_mfma_f32_32x32x16_bf16 v[66:81], v[2:5], v[130:133], v[66:81]
	v_mfma_f32_32x32x16_bf16 v[82:97], v[10:13], v[130:133], v[82:97]
	s_nop 10
	v_max_f32_e32 v2, v67, v67
	v_max_f32_e32 v3, v83, v83
	v_max_f32_e32 v2, v3, v2
	v_max_f32_e32 v3, v68, v68
	v_max_f32_e32 v4, v84, v84
	v_max_f32_e32 v3, v4, v3
	v_max_f32_e32 v4, v69, v69
	v_max_f32_e32 v5, v85, v85
	v_max3_f32 v2, v82, v66, v2
	v_max_f32_e32 v4, v5, v4
	v_max3_f32 v2, v2, v3, v4
	v_max_f32_e32 v3, v70, v70
	v_max_f32_e32 v4, v86, v86
	v_max_f32_e32 v3, v4, v3
	v_max_f32_e32 v4, v71, v71
	v_max_f32_e32 v5, v87, v87
	v_max_f32_e32 v4, v5, v4
	v_max3_f32 v2, v2, v3, v4
	v_max_f32_e32 v3, v72, v72
	v_max_f32_e32 v4, v88, v88
	v_max_f32_e32 v3, v4, v3
	v_max_f32_e32 v4, v73, v73
	v_max_f32_e32 v5, v89, v89
	v_max_f32_e32 v4, v5, v4
	v_max3_f32 v2, v2, v3, v4
	v_max_f32_e32 v3, v74, v74
	v_max_f32_e32 v4, v90, v90
	v_max_f32_e32 v3, v4, v3
	v_max_f32_e32 v4, v75, v75
	v_max_f32_e32 v5, v91, v91
	v_max_f32_e32 v4, v5, v4
	v_max3_f32 v2, v2, v3, v4
	v_max_f32_e32 v3, v76, v76
	v_max_f32_e32 v4, v92, v92
	v_max_f32_e32 v3, v4, v3
	v_max_f32_e32 v4, v77, v77
	v_max_f32_e32 v5, v93, v93
	v_max_f32_e32 v4, v5, v4
	v_max3_f32 v2, v2, v3, v4
	v_max_f32_e32 v3, v78, v78
	v_max_f32_e32 v4, v94, v94
	v_max_f32_e32 v3, v4, v3
	v_max_f32_e32 v4, v79, v79
	v_max_f32_e32 v5, v95, v95
	v_max_f32_e32 v4, v5, v4
	v_max3_f32 v2, v2, v3, v4
	v_max_f32_e32 v3, v80, v80
	v_max_f32_e32 v4, v96, v96
	v_max_f32_e32 v3, v4, v3
	v_max_f32_e32 v4, v81, v81
	v_max_f32_e32 v5, v97, v97
	v_max_f32_e32 v4, v5, v4
	v_max3_f32 v23, v2, v3, v4
	v_and_b32_e32 v3, 64, v224
	v_xor_b32_e32 v2, 32, v224
	v_add_u32_e32 v3, 64, v3
	v_cmp_lt_i32_e32 vcc, v2, v3
	s_nop 1
	v_cndmask_b32_e32 v2, v224, v2, vcc
	v_lshlrev_b32_e32 v207, 2, v2
	v_mov_b64_e32 v[2:3], s[4:5]
	ds_bpermute_b32 v24, v207, v23
	v_mov_b64_e32 v[4:5], s[6:7]
	v_mov_b64_e32 v[6:7], s[8:9]
	v_mov_b64_e32 v[8:9], s[10:11]
	v_mov_b64_e32 v[10:11], s[12:13]
	v_mov_b64_e32 v[12:13], s[14:15]
	v_mov_b64_e32 v[14:15], s[16:17]
	v_mov_b64_e32 v[16:17], s[18:19]
	s_add_i32 s5, s38, s34
	s_mul_i32 s7, s5, 0xe1000
	s_mul_hi_i32 s6, s5, 0xe1000
	s_add_u32 s8, s7, 0xfcb8800
	s_addc_u32 s9, s6, 0
	s_add_u32 s7, s7, 0xfcbe800
	s_waitcnt lgkmcnt(0)
	v_max_f32_e32 v24, v24, v24
	s_addc_u32 s6, s6, 0
	v_max_f32_e32 v98, v23, v24
	v_mov_b32_e32 v23, s9
	v_or_b32_e32 v22, s8, v202
	v_mov_b32_e32 v219, s6
	v_or_b32_e32 v218, s7, v202
	v_mad_i64_i32 v[20:21], s[6:7], s5, v226, v[20:21]
	v_lshlrev_b32_e32 v202, 4, v18
	v_lshl_add_u64 v[212:213], v[22:23], 0, s[68:69]
	v_lshl_add_u64 v[214:215], v[22:23], 0, s[70:71]
	v_lshl_add_u64 v[216:217], v[22:23], 0, s[72:73]
	v_lshl_add_u64 v[220:221], v[20:21], 0, v[202:203]
	v_mov_b64_e32 v[32:33], v[16:17]
	v_mov_b64_e32 v[48:49], v[16:17]
	v_mov_b64_e32 v[64:65], v[16:17]
	v_mov_b32_e32 v202, 0
	v_mov_b64_e32 v[30:31], v[14:15]
	v_mov_b64_e32 v[28:29], v[12:13]
	v_mov_b64_e32 v[26:27], v[10:11]
	v_mov_b64_e32 v[24:25], v[8:9]
	v_mov_b64_e32 v[22:23], v[6:7]
	v_mov_b64_e32 v[20:21], v[4:5]
	v_mov_b64_e32 v[18:19], v[2:3]
	v_mov_b64_e32 v[46:47], v[14:15]
	v_mov_b64_e32 v[44:45], v[12:13]
	v_mov_b64_e32 v[42:43], v[10:11]
	v_mov_b64_e32 v[40:41], v[8:9]
	v_mov_b64_e32 v[38:39], v[6:7]
	v_mov_b64_e32 v[36:37], v[4:5]
	v_mov_b64_e32 v[34:35], v[2:3]
	v_mov_b64_e32 v[62:63], v[14:15]
	v_mov_b64_e32 v[60:61], v[12:13]
	v_mov_b64_e32 v[58:59], v[10:11]
	v_mov_b64_e32 v[56:57], v[8:9]
	v_mov_b64_e32 v[54:55], v[6:7]
	v_mov_b64_e32 v[52:53], v[4:5]
	v_mov_b64_e32 v[50:51], v[2:3]
	s_branch .LBB0_815

; __device__ __forceinline__ unsigned cvt_pk(float lo, float hi) { unsigned r; asm volatile("v_cvt_pk_bf16_f32 %0, %1, %2" : "=v"(r) : "v"(lo), "v"(hi)); return r; }
;     __device__ __forceinline__ void operator()(const Acc& acc, const Unit& u, int wr, int wc, int fr, int fq) const {
;     ...
;             for (int m = 0; m < 4; ++m) { const int row = u.pm * 256 + ai * 128 + wr * 64 + m * 16 + fr; const size_t R = (size_t)u.pb * NT + row;
;                 const f32x4 sa = *(const f32x4*)(stats + R * 8 + (ISQ ? 0 : 4));
;                 float rr = rsqrtf(((sa[0] + sa[1]) + (sa[2] + sa[3])) * (ISQ ? (1.f / 256.f) : (1.f / 128.f)) + EPS); if (ISQ) rr *= QSCALE;
; #pragma unroll
;                 for (int bj = 0; bj < 2; ++bj) { const int cg_ = u.pn * 256 + bj * 128 + wc * 32; const int h = cg_ / 192, d0 = cg_ - h * 192;
;                     f32x4 a = acc[ai][bj][m][0], b = acc[ai][bj][m][1];
;                     if (d0 < 128) { a = a * rr; b = b * rr; }
;                     else { if (ISQ) { a = a * rr; b = b * rr; }
;                         f32x4 pa, pb;
; #pragma unroll
;                         for (int i = 0; i < 4; ++i) { pa[i] = __shfl_xor(a[i], 32); pb[i] = __shfl_xor(b[i], 32); }
;                         if (row < TL) { const int ti = row * 32 + ((d0 - 128) >> 5) * 16 + 8 * (fq & 1); const float sg = fq < 2 ? -1.f : 1.f;
;                             const f32x4 c0 = *(const f32x4*)(cosT + ti), c1 = *(const f32x4*)(cosT + ti + 4), s0 = *(const f32x4*)(sinT + ti) * sg, s1 = *(const f32x4*)(sinT + ti + 4) * sg;
;                             a = a * c0 + pa * s0; b = b * c1 + pb * s1; } }
;                     bf16_t* dst = O + ((size_t)(u.pb * 4 + h) * NT + row) * pitch + d0 + 8 * fq;
;                     u32x4 w; w.x = cvt_pk(a[0], a[1]); w.y = cvt_pk(a[2], a[3]); w.z = cvt_pk(b[0], b[1]); w.w = cvt_pk(b[2], b[3]); *(u32x4*)dst = w; } }
.LBB0_1454:
	v_mov_b32_e32 v144, v158
	s_lshl_b32 s92, s92, 8
	v_and_or_b32 v167, v144, 15, s78
	v_add_u32_e32 v146, s92, v167
	v_ashrrev_i32_e32 v147, 31, v146
	v_mad_i64_i32 v[142:143], s[4:5], s90, v164, v[146:147]
	v_lshlrev_b64 v[142:143], 5, v[142:143]
	v_lshl_add_u64 v[142:143], s[12:13], 0, v[142:143]
	v_mov_b64_e32 v[218:219], v[142:143]
	global_load_dwordx4 v[148:151], v[142:143], off
	s_mov_b32 s98, 0x1000
	s_mov_b32 s99, 0
	global_load_dwordx4 v[188:191], v[218:219], off offset:512
	global_load_dwordx4 v[192:195], v[218:219], off offset:1024
	global_load_dwordx4 v[196:199], v[218:219], off offset:1536
	v_lshl_add_u64 v[216:217], v[218:219], 0, s[98:99]
	global_load_dwordx4 v[200:203], v[216:217], off
	global_load_dwordx4 v[204:207], v[216:217], off offset:512
	global_load_dwordx4 v[208:211], v[216:217], off offset:1024
	global_load_dwordx4 v[212:215], v[216:217], off offset:1536
	s_lshl_b32 s4, s91, 8
	s_or_b32 s6, s4, s79
	s_mul_hi_i32 s4, s6, 0x2aaaaaab
	v_ashrrev_i32_e32 v143, 4, v144
	s_lshr_b32 s5, s4, 31
	s_ashr_i32 s8, s4, 5
	v_lshlrev_b32_e32 v142, 3, v143
	v_cmp_gt_i32_e32 vcc, 2, v143
	s_add_i32 s8, s8, s5
	s_mul_i32 s4, s8, 0xffffff40
	s_add_i32 s44, s4, s6
	v_cndmask_b32_e64 v144, 1.0, -1.0, vcc
	v_and_b32_e32 v166, 8, v142
	s_cmpk_gt_i32 s44, 0x7f
	v_mov_b32_e32 v145, v144
	v_cmp_gt_i32_e32 vcc, s85, v146
	v_lshl_or_b32 v168, v146, 5, v166
	s_cselect_b64 s[10:11], -1, 0
	s_cmpk_lt_i32 s44, 0x80
	s_waitcnt vmcnt(0)
	v_mov_b32_e32 v152, v149
	v_mov_b32_e32 v153, v150
	v_mov_b32_e32 v149, v151
	v_pk_add_f32 v[148:149], v[152:153], v[148:149]
	s_nop 0
	v_add_f32_e32 v143, v148, v149
	v_fmamk_f32 v143, v143, 0x3b800000, v163
	v_mul_f32_e32 v148, 0x4b800000, v143
	v_cmp_gt_f32_e64 s[4:5], s84, v143
	s_nop 1
	v_cndmask_b32_e64 v143, v143, v148, s[4:5]
	v_rsq_f32_e32 v143, v143
	s_nop 0
	v_mul_f32_e32 v148, 0x45800000, v143
	v_cndmask_b32_e64 v143, v143, v148, s[4:5]
	v_mul_f32_e32 v148, 0x3dd53b94, v143
	v_pk_mul_f32 v[128:129], v[128:129], v[148:149] op_sel_hi:[1,0]
	v_pk_mul_f32 v[126:127], v[126:127], v[148:149] op_sel_hi:[1,0]
	v_pk_mul_f32 v[124:125], v[124:125], v[148:149] op_sel_hi:[1,0]
	v_pk_mul_f32 v[122:123], v[122:123], v[148:149] op_sel_hi:[1,0]
	s_cbranch_scc1 .LBB0_1458
	v_and_b32_e32 v149, 64, v165
	v_xor_b32_e32 v143, 32, v165
	v_add_u32_e32 v149, 64, v149
	v_cmp_lt_i32_e64 s[4:5], v143, v149
	s_nop 1
	v_cndmask_b32_e64 v143, v165, v143, s[4:5]
	v_lshlrev_b32_e32 v143, 2, v143
	ds_bpermute_b32 v154, v143, v126
	ds_bpermute_b32 v150, v143, v122
	ds_bpermute_b32 v155, v143, v127
	ds_bpermute_b32 v151, v143, v123
	ds_bpermute_b32 v156, v143, v128
	ds_bpermute_b32 v152, v143, v124
	ds_bpermute_b32 v157, v143, v129
	ds_bpermute_b32 v153, v143, v125
	s_and_saveexec_b64 s[4:5], vcc
	s_cbranch_execz .LBB0_1457
	s_add_i32 s7, s44, 0xffffff80
	s_lshr_b32 s7, s7, 1
	v_add_u32_e32 v170, s7, v168
	v_ashrrev_i32_e32 v171, 31, v170
	v_lshlrev_b64 v[178:179], 2, v[170:171]
	v_lshl_add_u64 v[174:175], s[16:17], 0, v[178:179]
	global_load_dwordx4 v[170:173], v[174:175], off
	s_nop 0
	global_load_dwordx4 v[174:177], v[174:175], off offset:16
	v_lshl_add_u64 v[182:183], s[14:15], 0, v[178:179]
	global_load_dwordx4 v[178:181], v[182:183], off
	s_nop 0
	global_load_dwordx4 v[182:185], v[182:183], off offset:16
	v_mov_b32_e32 v186, v144
	v_mov_b32_e32 v187, v144
	s_waitcnt vmcnt(3)
	v_pk_mul_f32 v[172:173], v[186:187], v[172:173]
	v_pk_mul_f32 v[170:171], v[144:145], v[170:171]
	s_waitcnt vmcnt(2)
	v_pk_mul_f32 v[176:177], v[186:187], v[176:177]
	v_pk_mul_f32 v[174:175], v[144:145], v[174:175]
	s_waitcnt lgkmcnt(1)
	v_pk_mul_f32 v[156:157], v[172:173], v[156:157]
	v_pk_mul_f32 v[154:155], v[170:171], v[154:155]
	s_waitcnt lgkmcnt(0)
	v_pk_mul_f32 v[152:153], v[176:177], v[152:153]
	v_pk_mul_f32 v[150:151], v[174:175], v[150:151]
	s_waitcnt vmcnt(1)
	v_pk_fma_f32 v[128:129], v[128:129], v[180:181], v[156:157]
	v_pk_fma_f32 v[126:127], v[126:127], v[178:179], v[154:155]
	s_waitcnt vmcnt(0)
	v_pk_fma_f32 v[124:125], v[124:125], v[184:185], v[152:153]
	v_pk_fma_f32 v[122:123], v[122:123], v[182:183], v[150:151]

; __device__ __forceinline__ unsigned cvt_pk(float lo, float hi) { unsigned r; asm volatile("v_cvt_pk_bf16_f32 %0, %1, %2" : "=v"(r) : "v"(lo), "v"(hi)); return r; }
;     __device__ __forceinline__ void operator()(const Acc& acc, const Unit& u, int wr, int wc, int fr, int fq) const {
;     ...
;             for (int m = 0; m < 4; ++m) { const int row = u.pm * 256 + ai * 128 + wr * 64 + m * 16 + fr; const size_t R = (size_t)u.pb * NT + row;
;                 const f32x4 sa = *(const f32x4*)(stats + R * 8 + (ISQ ? 0 : 4));
;                 float rr = rsqrtf(((sa[0] + sa[1]) + (sa[2] + sa[3])) * (ISQ ? (1.f / 256.f) : (1.f / 128.f)) + EPS); if (ISQ) rr *= QSCALE;
; #pragma unroll
;                 for (int bj = 0; bj < 2; ++bj) { const int cg_ = u.pn * 256 + bj * 128 + wc * 32; const int h = cg_ / 192, d0 = cg_ - h * 192;
;                     f32x4 a = acc[ai][bj][m][0], b = acc[ai][bj][m][1];
;                     if (d0 < 128) { a = a * rr; b = b * rr; }
;                     else { if (ISQ) { a = a * rr; b = b * rr; }
;                         f32x4 pa, pb;
; #pragma unroll
;                         for (int i = 0; i < 4; ++i) { pa[i] = __shfl_xor(a[i], 32); pb[i] = __shfl_xor(b[i], 32); }
;                         if (row < TL) { const int ti = row * 32 + ((d0 - 128) >> 5) * 16 + 8 * (fq & 1); const float sg = fq < 2 ? -1.f : 1.f;
;                             const f32x4 c0 = *(const f32x4*)(cosT + ti), c1 = *(const f32x4*)(cosT + ti + 4), s0 = *(const f32x4*)(sinT + ti) * sg, s1 = *(const f32x4*)(sinT + ti + 4) * sg;
;                             a = a * c0 + pa * s0; b = b * c1 + pb * s1; } }
;                     bf16_t* dst = O + ((size_t)(u.pb * 4 + h) * NT + row) * pitch + d0 + 8 * fq;
;                     u32x4 w; w.x = cvt_pk(a[0], a[1]); w.y = cvt_pk(a[2], a[3]); w.z = cvt_pk(b[0], b[1]); w.w = cvt_pk(b[2], b[3]); *(u32x4*)dst = w; } }
.LBB0_1462:
	s_mul_hi_i32 s49, s90, 0x900
	s_mul_i32 s48, s90, 0x900
	s_add_i32 s90, s6, s7
	s_waitcnt lgkmcnt(4)
	v_mad_i64_i32 v[122:123], s[4:5], s90, v164, v[146:147]
	s_waitcnt lgkmcnt(0)
	v_mov_b64_e32 v[124:125], s[20:21]
	v_mad_u64_u32 v[124:125], s[4:5], v122, s86, v[124:125]
	v_cvt_pk_bf16_f32 v118, v118, v119
	v_cvt_pk_bf16_f32 v119, v120, v121
	v_cvt_pk_bf16_f32 v120, v114, v115
	v_add3_u32 v114, s92, v167, 16
	v_mad_i32_i24 v125, v123, s86, v125
	s_ashr_i32 s47, s46, 31
	v_ashrrev_i32_e32 v115, 31, v114
	v_lshl_add_u64 v[122:123], s[46:47], 1, v[124:125]
	v_cvt_pk_bf16_f32 v121, v116, v117
	v_lshl_add_u64 v[116:117], s[48:49], 0, v[114:115]
	v_lshl_add_u64 v[122:123], v[142:143], 1, v[122:123]
	v_lshlrev_b64 v[116:117], 5, v[116:117]
	global_store_dwordx4 v[122:123], v[118:121], off
	v_lshl_add_u64 v[116:117], s[12:13], 0, v[116:117]
	v_mov_b64_e32 v[116:117], v[188:189]
	v_mov_b64_e32 v[118:119], v[190:191]
	v_cndmask_b32_e64 v122, 0, 1, s[10:11]
	v_cmp_gt_i32_e64 s[8:9], s85, v114
	v_lshl_or_b32 v126, v114, 5, v166
	v_cmp_ne_u32_e64 s[4:5], 1, v122
	s_andn2_b64 vcc, exec, s[10:11]
	s_waitcnt vmcnt(0)
	v_mov_b32_e32 v120, v117
	v_mov_b32_e32 v121, v118
	v_mov_b32_e32 v117, v119
	v_pk_add_f32 v[116:117], v[120:121], v[116:117]
	s_nop 0
	v_add_f32_e32 v116, v116, v117
	v_fmamk_f32 v116, v116, 0x3b800000, v163
	v_mul_f32_e32 v117, 0x4b800000, v116
	v_cmp_gt_f32_e64 s[6:7], s84, v116
	s_nop 1
	v_cndmask_b32_e64 v116, v116, v117, s[6:7]
	v_rsq_f32_e32 v116, v116
	s_nop 0
	v_mul_f32_e32 v117, 0x45800000, v116
	v_cndmask_b32_e64 v116, v116, v117, s[6:7]
	v_mul_f32_e32 v116, 0x3dd53b94, v116
	v_pk_mul_f32 v[112:113], v[112:113], v[116:117] op_sel_hi:[1,0]
	v_pk_mul_f32 v[110:111], v[110:111], v[116:117] op_sel_hi:[1,0]
	v_pk_mul_f32 v[108:109], v[108:109], v[116:117] op_sel_hi:[1,0]
	v_pk_mul_f32 v[106:107], v[106:107], v[116:117] op_sel_hi:[1,0]
	s_cbranch_vccnz .LBB0_1466
	v_and_b32_e32 v118, 64, v165
	v_xor_b32_e32 v117, 32, v165
	v_add_u32_e32 v118, 64, v118
	v_cmp_lt_i32_e32 vcc, v117, v118
	s_nop 1
	v_cndmask_b32_e32 v117, v165, v117, vcc
	v_lshlrev_b32_e32 v117, 2, v117
	ds_bpermute_b32 v122, v117, v110
	ds_bpermute_b32 v118, v117, v106
	ds_bpermute_b32 v123, v117, v111
	ds_bpermute_b32 v119, v117, v107
	ds_bpermute_b32 v124, v117, v112
	ds_bpermute_b32 v120, v117, v108
	ds_bpermute_b32 v125, v117, v113
	ds_bpermute_b32 v121, v117, v109
	s_and_saveexec_b64 s[6:7], s[8:9]
	s_cbranch_execz .LBB0_1465
	s_add_i32 s10, s44, 0xffffff80
	s_lshr_b32 s10, s10, 1
	v_add_u32_e32 v128, s10, v126
	v_ashrrev_i32_e32 v129, 31, v128
	v_lshlrev_b64 v[128:129], 2, v[128:129]
	v_lshl_add_u64 v[152:153], s[16:17], 0, v[128:129]
	global_load_dwordx4 v[148:151], v[152:153], off
	s_nop 0
	global_load_dwordx4 v[152:155], v[152:153], off offset:16
	v_lshl_add_u64 v[128:129], s[14:15], 0, v[128:129]
	global_load_dwordx4 v[168:171], v[128:129], off
	global_load_dwordx4 v[172:175], v[128:129], off offset:16
	v_mov_b32_e32 v128, v144
	v_mov_b32_e32 v129, v144
	s_waitcnt vmcnt(3)
	v_pk_mul_f32 v[150:151], v[128:129], v[150:151]
	v_pk_mul_f32 v[148:149], v[144:145], v[148:149]
	s_waitcnt vmcnt(2)
	v_pk_mul_f32 v[128:129], v[128:129], v[154:155]
	v_pk_mul_f32 v[152:153], v[144:145], v[152:153]
	s_waitcnt lgkmcnt(1)
	v_pk_mul_f32 v[124:125], v[150:151], v[124:125]
	v_pk_mul_f32 v[122:123], v[148:149], v[122:123]
	s_waitcnt lgkmcnt(0)
	v_pk_mul_f32 v[120:121], v[128:129], v[120:121]
	v_pk_mul_f32 v[118:119], v[152:153], v[118:119]
	s_waitcnt vmcnt(1)
	v_pk_fma_f32 v[112:113], v[112:113], v[170:171], v[124:125]
	v_pk_fma_f32 v[110:111], v[110:111], v[168:169], v[122:123]
	s_waitcnt vmcnt(0)
	v_pk_fma_f32 v[108:109], v[108:109], v[174:175], v[120:121]
	v_pk_fma_f32 v[106:107], v[106:107], v[172:173], v[118:119]

; __device__ __forceinline__ unsigned cvt_pk(float lo, float hi) { unsigned r; asm volatile("v_cvt_pk_bf16_f32 %0, %1, %2" : "=v"(r) : "v"(lo), "v"(hi)); return r; }
;     __device__ __forceinline__ void operator()(const Acc& acc, const Unit& u, int wr, int wc, int fr, int fq) const {
;     ...
;             for (int m = 0; m < 4; ++m) { const int row = u.pm * 256 + ai * 128 + wr * 64 + m * 16 + fr; const size_t R = (size_t)u.pb * NT + row;
;                 const f32x4 sa = *(const f32x4*)(stats + R * 8 + (ISQ ? 0 : 4));
;                 float rr = rsqrtf(((sa[0] + sa[1]) + (sa[2] + sa[3])) * (ISQ ? (1.f / 256.f) : (1.f / 128.f)) + EPS); if (ISQ) rr *= QSCALE;
; #pragma unroll
;                 for (int bj = 0; bj < 2; ++bj) { const int cg_ = u.pn * 256 + bj * 128 + wc * 32; const int h = cg_ / 192, d0 = cg_ - h * 192;
;                     f32x4 a = acc[ai][bj][m][0], b = acc[ai][bj][m][1];
;                     if (d0 < 128) { a = a * rr; b = b * rr; }
;                     else { if (ISQ) { a = a * rr; b = b * rr; }
;                         f32x4 pa, pb;
; #pragma unroll
;                         for (int i = 0; i < 4; ++i) { pa[i] = __shfl_xor(a[i], 32); pb[i] = __shfl_xor(b[i], 32); }
;                         if (row < TL) { const int ti = row * 32 + ((d0 - 128) >> 5) * 16 + 8 * (fq & 1); const float sg = fq < 2 ? -1.f : 1.f;
;                             const f32x4 c0 = *(const f32x4*)(cosT + ti), c1 = *(const f32x4*)(cosT + ti + 4), s0 = *(const f32x4*)(sinT + ti) * sg, s1 = *(const f32x4*)(sinT + ti + 4) * sg;
;                             a = a * c0 + pa * s0; b = b * c1 + pb * s1; } }
;                     bf16_t* dst = O + ((size_t)(u.pb * 4 + h) * NT + row) * pitch + d0 + 8 * fq;
;                     u32x4 w; w.x = cvt_pk(a[0], a[1]); w.y = cvt_pk(a[2], a[3]); w.z = cvt_pk(b[0], b[1]); w.w = cvt_pk(b[2], b[3]); *(u32x4*)dst = w; } }
.LBB0_1470:
	s_mul_hi_i32 s55, s90, 0x900
	s_mul_i32 s54, s90, 0x900
	s_waitcnt lgkmcnt(4)
	v_lshl_add_u64 v[106:107], s[54:55], 0, v[114:115]
	s_waitcnt lgkmcnt(0)
	v_mov_b64_e32 v[108:109], s[20:21]
	v_mad_u64_u32 v[108:109], s[8:9], v106, s86, v[108:109]
	v_mov_b32_e32 v106, v109
	v_mad_u64_u32 v[106:107], s[8:9], v107, s86, v[106:107]
	v_cvt_pk_bf16_f32 v102, v102, v103
	v_cvt_pk_bf16_f32 v103, v104, v105
	v_cvt_pk_bf16_f32 v104, v98, v99
	v_add3_u32 v98, s92, v167, 32
	v_mov_b32_e32 v109, v106
	v_ashrrev_i32_e32 v99, 31, v98
	v_lshl_add_u64 v[106:107], s[46:47], 1, v[108:109]
	v_cvt_pk_bf16_f32 v105, v100, v101
	v_lshl_add_u64 v[100:101], s[48:49], 0, v[98:99]
	v_lshl_add_u64 v[106:107], v[142:143], 1, v[106:107]
	v_lshlrev_b64 v[100:101], 5, v[100:101]
	global_store_dwordx4 v[106:107], v[102:105], off
	v_lshl_add_u64 v[100:101], s[12:13], 0, v[100:101]
	v_mov_b64_e32 v[100:101], v[192:193]
	v_mov_b64_e32 v[102:103], v[194:195]
	s_and_b64 vcc, exec, s[4:5]
	v_cmp_gt_i32_e64 s[8:9], s85, v98
	v_lshl_or_b32 v110, v98, 5, v166
	s_waitcnt vmcnt(0)
	v_mov_b32_e32 v104, v101
	v_mov_b32_e32 v105, v102
	v_mov_b32_e32 v101, v103
	v_pk_add_f32 v[100:101], v[104:105], v[100:101]
	s_nop 0
	v_add_f32_e32 v100, v100, v101
	v_fmamk_f32 v100, v100, 0x3b800000, v163
	v_mul_f32_e32 v101, 0x4b800000, v100
	v_cmp_gt_f32_e64 s[10:11], s84, v100
	s_nop 1
	v_cndmask_b32_e64 v100, v100, v101, s[10:11]
	v_rsq_f32_e32 v100, v100
	s_nop 0
	v_mul_f32_e32 v101, 0x45800000, v100
	v_cndmask_b32_e64 v100, v100, v101, s[10:11]
	v_mul_f32_e32 v100, 0x3dd53b94, v100
	v_pk_mul_f32 v[96:97], v[96:97], v[100:101] op_sel_hi:[1,0]
	v_pk_mul_f32 v[94:95], v[94:95], v[100:101] op_sel_hi:[1,0]
	v_pk_mul_f32 v[92:93], v[92:93], v[100:101] op_sel_hi:[1,0]
	v_pk_mul_f32 v[90:91], v[90:91], v[100:101] op_sel_hi:[1,0]
	s_cbranch_vccnz .LBB0_1474
	v_and_b32_e32 v102, 64, v165
	v_xor_b32_e32 v101, 32, v165
	v_add_u32_e32 v102, 64, v102
	v_cmp_lt_i32_e32 vcc, v101, v102
	s_nop 1
	v_cndmask_b32_e32 v101, v165, v101, vcc
	v_lshlrev_b32_e32 v101, 2, v101
	ds_bpermute_b32 v106, v101, v94
	ds_bpermute_b32 v102, v101, v90
	ds_bpermute_b32 v107, v101, v95
	ds_bpermute_b32 v103, v101, v91
	ds_bpermute_b32 v108, v101, v96
	ds_bpermute_b32 v104, v101, v92
	ds_bpermute_b32 v109, v101, v97
	ds_bpermute_b32 v105, v101, v93
	s_and_saveexec_b64 s[10:11], s[8:9]
	s_cbranch_execz .LBB0_1473
	s_add_i32 s33, s44, 0xffffff80
	s_lshr_b32 s33, s33, 1
	v_add_u32_e32 v112, s33, v110
	v_ashrrev_i32_e32 v113, 31, v112
	v_lshlrev_b64 v[120:121], 2, v[112:113]
	v_lshl_add_u64 v[116:117], s[16:17], 0, v[120:121]
	global_load_dwordx4 v[112:115], v[116:117], off
	s_nop 0
	global_load_dwordx4 v[116:119], v[116:117], off offset:16
	v_lshl_add_u64 v[124:125], s[14:15], 0, v[120:121]
	global_load_dwordx4 v[120:123], v[124:125], off
	s_nop 0
	global_load_dwordx4 v[124:127], v[124:125], off offset:16
	v_mov_b32_e32 v128, v144
	v_mov_b32_e32 v129, v144
	s_waitcnt vmcnt(3)
	v_pk_mul_f32 v[114:115], v[128:129], v[114:115]
	v_pk_mul_f32 v[112:113], v[144:145], v[112:113]
	s_waitcnt vmcnt(2)
	v_pk_mul_f32 v[118:119], v[128:129], v[118:119]
	v_pk_mul_f32 v[116:117], v[144:145], v[116:117]
	s_waitcnt lgkmcnt(1)
	v_pk_mul_f32 v[108:109], v[114:115], v[108:109]
	v_pk_mul_f32 v[106:107], v[112:113], v[106:107]
	s_waitcnt lgkmcnt(0)
	v_pk_mul_f32 v[104:105], v[118:119], v[104:105]
	v_pk_mul_f32 v[102:103], v[116:117], v[102:103]
	s_waitcnt vmcnt(1)
	v_pk_fma_f32 v[96:97], v[96:97], v[122:123], v[108:109]
	v_pk_fma_f32 v[94:95], v[94:95], v[120:121], v[106:107]
	s_waitcnt vmcnt(0)
	v_pk_fma_f32 v[92:93], v[92:93], v[126:127], v[104:105]
	v_pk_fma_f32 v[90:91], v[90:91], v[124:125], v[102:103]

; __device__ __forceinline__ unsigned cvt_pk(float lo, float hi) { unsigned r; asm volatile("v_cvt_pk_bf16_f32 %0, %1, %2" : "=v"(r) : "v"(lo), "v"(hi)); return r; }
;     __device__ __forceinline__ void operator()(const Acc& acc, const Unit& u, int wr, int wc, int fr, int fq) const {
;     ...
;             for (int m = 0; m < 4; ++m) { const int row = u.pm * 256 + ai * 128 + wr * 64 + m * 16 + fr; const size_t R = (size_t)u.pb * NT + row;
;                 const f32x4 sa = *(const f32x4*)(stats + R * 8 + (ISQ ? 0 : 4));
;                 float rr = rsqrtf(((sa[0] + sa[1]) + (sa[2] + sa[3])) * (ISQ ? (1.f / 256.f) : (1.f / 128.f)) + EPS); if (ISQ) rr *= QSCALE;
; #pragma unroll
;                 for (int bj = 0; bj < 2; ++bj) { const int cg_ = u.pn * 256 + bj * 128 + wc * 32; const int h = cg_ / 192, d0 = cg_ - h * 192;
;                     f32x4 a = acc[ai][bj][m][0], b = acc[ai][bj][m][1];
;                     if (d0 < 128) { a = a * rr; b = b * rr; }
;                     else { if (ISQ) { a = a * rr; b = b * rr; }
;                         f32x4 pa, pb;
; #pragma unroll
;                         for (int i = 0; i < 4; ++i) { pa[i] = __shfl_xor(a[i], 32); pb[i] = __shfl_xor(b[i], 32); }
;                         if (row < TL) { const int ti = row * 32 + ((d0 - 128) >> 5) * 16 + 8 * (fq & 1); const float sg = fq < 2 ? -1.f : 1.f;
;                             const f32x4 c0 = *(const f32x4*)(cosT + ti), c1 = *(const f32x4*)(cosT + ti + 4), s0 = *(const f32x4*)(sinT + ti) * sg, s1 = *(const f32x4*)(sinT + ti + 4) * sg;
;                             a = a * c0 + pa * s0; b = b * c1 + pb * s1; } }
;                     bf16_t* dst = O + ((size_t)(u.pb * 4 + h) * NT + row) * pitch + d0 + 8 * fq;
;                     u32x4 w; w.x = cvt_pk(a[0], a[1]); w.y = cvt_pk(a[2], a[3]); w.z = cvt_pk(b[0], b[1]); w.w = cvt_pk(b[2], b[3]); *(u32x4*)dst = w; } }
.LBB0_1478:
	s_waitcnt lgkmcnt(4)
	v_lshl_add_u64 v[90:91], s[54:55], 0, v[98:99]
	s_waitcnt lgkmcnt(0)
	v_mov_b64_e32 v[92:93], s[20:21]
	v_mad_u64_u32 v[92:93], s[8:9], v90, s86, v[92:93]
	v_mov_b32_e32 v90, v93
	v_mad_u64_u32 v[90:91], s[8:9], v91, s86, v[90:91]
	v_cvt_pk_bf16_f32 v86, v86, v87
	v_cvt_pk_bf16_f32 v87, v88, v89
	v_cvt_pk_bf16_f32 v88, v82, v83
	v_add3_u32 v82, s92, v167, 48
	v_mov_b32_e32 v93, v90
	v_ashrrev_i32_e32 v83, 31, v82
	v_lshl_add_u64 v[90:91], s[46:47], 1, v[92:93]
	v_cvt_pk_bf16_f32 v89, v84, v85
	v_lshl_add_u64 v[84:85], s[48:49], 0, v[82:83]
	v_lshl_add_u64 v[90:91], v[142:143], 1, v[90:91]
	v_lshlrev_b64 v[84:85], 5, v[84:85]
	global_store_dwordx4 v[90:91], v[86:89], off
	v_lshl_add_u64 v[84:85], s[12:13], 0, v[84:85]
	v_mov_b64_e32 v[84:85], v[196:197]
	v_mov_b64_e32 v[86:87], v[198:199]
	s_and_b64 vcc, exec, s[4:5]
	v_cmp_gt_i32_e64 s[8:9], s85, v82
	v_lshl_or_b32 v94, v82, 5, v166
	s_waitcnt vmcnt(0)
	v_mov_b32_e32 v88, v85
	v_mov_b32_e32 v89, v86
	v_mov_b32_e32 v85, v87
	v_pk_add_f32 v[84:85], v[88:89], v[84:85]
	s_nop 0
	v_add_f32_e32 v84, v84, v85
	v_fmamk_f32 v84, v84, 0x3b800000, v163
	v_mul_f32_e32 v85, 0x4b800000, v84
	v_cmp_gt_f32_e64 s[10:11], s84, v84
	s_nop 1
	v_cndmask_b32_e64 v84, v84, v85, s[10:11]
	v_rsq_f32_e32 v84, v84
	s_nop 0
	v_mul_f32_e32 v85, 0x45800000, v84
	v_cndmask_b32_e64 v84, v84, v85, s[10:11]
	v_mul_f32_e32 v84, 0x3dd53b94, v84
	v_pk_mul_f32 v[80:81], v[80:81], v[84:85] op_sel_hi:[1,0]
	v_pk_mul_f32 v[78:79], v[78:79], v[84:85] op_sel_hi:[1,0]
	v_pk_mul_f32 v[76:77], v[76:77], v[84:85] op_sel_hi:[1,0]
	v_pk_mul_f32 v[74:75], v[74:75], v[84:85] op_sel_hi:[1,0]
	s_cbranch_vccnz .LBB0_1482
	v_and_b32_e32 v86, 64, v165
	v_xor_b32_e32 v85, 32, v165
	v_add_u32_e32 v86, 64, v86
	v_cmp_lt_i32_e32 vcc, v85, v86
	s_nop 1
	v_cndmask_b32_e32 v85, v165, v85, vcc
	v_lshlrev_b32_e32 v85, 2, v85
	ds_bpermute_b32 v90, v85, v78
	ds_bpermute_b32 v86, v85, v74
	ds_bpermute_b32 v91, v85, v79
	ds_bpermute_b32 v87, v85, v75
	ds_bpermute_b32 v92, v85, v80
	ds_bpermute_b32 v88, v85, v76
	ds_bpermute_b32 v93, v85, v81
	ds_bpermute_b32 v89, v85, v77
	s_and_saveexec_b64 s[10:11], s[8:9]
	s_cbranch_execz .LBB0_1481
	s_add_i32 s33, s44, 0xffffff80
	s_lshr_b32 s33, s33, 1
	v_add_u32_e32 v96, s33, v94
	v_ashrrev_i32_e32 v97, 31, v96
	v_lshlrev_b64 v[104:105], 2, v[96:97]
	v_lshl_add_u64 v[100:101], s[16:17], 0, v[104:105]
	global_load_dwordx4 v[96:99], v[100:101], off
	s_nop 0
	global_load_dwordx4 v[100:103], v[100:101], off offset:16
	v_lshl_add_u64 v[108:109], s[14:15], 0, v[104:105]
	global_load_dwordx4 v[104:107], v[108:109], off
	s_nop 0
	global_load_dwordx4 v[108:111], v[108:109], off offset:16
	v_mov_b32_e32 v112, v144
	v_mov_b32_e32 v113, v144
	s_waitcnt vmcnt(3)
	v_pk_mul_f32 v[98:99], v[112:113], v[98:99]
	v_pk_mul_f32 v[96:97], v[144:145], v[96:97]
	s_waitcnt vmcnt(2)
	v_pk_mul_f32 v[102:103], v[112:113], v[102:103]
	v_pk_mul_f32 v[100:101], v[144:145], v[100:101]
	s_waitcnt lgkmcnt(1)
	v_pk_mul_f32 v[92:93], v[98:99], v[92:93]
	v_pk_mul_f32 v[90:91], v[96:97], v[90:91]
	s_waitcnt lgkmcnt(0)
	v_pk_mul_f32 v[88:89], v[102:103], v[88:89]
	v_pk_mul_f32 v[86:87], v[100:101], v[86:87]
	s_waitcnt vmcnt(1)
	v_pk_fma_f32 v[80:81], v[80:81], v[106:107], v[92:93]
	v_pk_fma_f32 v[78:79], v[78:79], v[104:105], v[90:91]
	s_waitcnt vmcnt(0)
	v_pk_fma_f32 v[76:77], v[76:77], v[110:111], v[88:89]
	v_pk_fma_f32 v[74:75], v[74:75], v[108:109], v[86:87]

; __device__ __forceinline__ unsigned cvt_pk(float lo, float hi) { unsigned r; asm volatile("v_cvt_pk_bf16_f32 %0, %1, %2" : "=v"(r) : "v"(lo), "v"(hi)); return r; }
;     __device__ __forceinline__ void operator()(const Acc& acc, const Unit& u, int wr, int wc, int fr, int fq) const {
;     ...
;             for (int m = 0; m < 4; ++m) { const int row = u.pm * 256 + ai * 128 + wr * 64 + m * 16 + fr; const size_t R = (size_t)u.pb * NT + row;
;                 const f32x4 sa = *(const f32x4*)(stats + R * 8 + (ISQ ? 0 : 4));
;                 float rr = rsqrtf(((sa[0] + sa[1]) + (sa[2] + sa[3])) * (ISQ ? (1.f / 256.f) : (1.f / 128.f)) + EPS); if (ISQ) rr *= QSCALE;
; #pragma unroll
;                 for (int bj = 0; bj < 2; ++bj) { const int cg_ = u.pn * 256 + bj * 128 + wc * 32; const int h = cg_ / 192, d0 = cg_ - h * 192;
;                     f32x4 a = acc[ai][bj][m][0], b = acc[ai][bj][m][1];
;                     if (d0 < 128) { a = a * rr; b = b * rr; }
;                     else { if (ISQ) { a = a * rr; b = b * rr; }
;                         f32x4 pa, pb;
; #pragma unroll
;                         for (int i = 0; i < 4; ++i) { pa[i] = __shfl_xor(a[i], 32); pb[i] = __shfl_xor(b[i], 32); }
;                         if (row < TL) { const int ti = row * 32 + ((d0 - 128) >> 5) * 16 + 8 * (fq & 1); const float sg = fq < 2 ? -1.f : 1.f;
;                             const f32x4 c0 = *(const f32x4*)(cosT + ti), c1 = *(const f32x4*)(cosT + ti + 4), s0 = *(const f32x4*)(sinT + ti) * sg, s1 = *(const f32x4*)(sinT + ti + 4) * sg;
;                             a = a * c0 + pa * s0; b = b * c1 + pb * s1; } }
;                     bf16_t* dst = O + ((size_t)(u.pb * 4 + h) * NT + row) * pitch + d0 + 8 * fq;
;                     u32x4 w; w.x = cvt_pk(a[0], a[1]); w.y = cvt_pk(a[2], a[3]); w.z = cvt_pk(b[0], b[1]); w.w = cvt_pk(b[2], b[3]); *(u32x4*)dst = w; } }
.LBB0_1486:
	s_waitcnt lgkmcnt(4)
	v_lshl_add_u64 v[74:75], s[54:55], 0, v[82:83]
	s_waitcnt lgkmcnt(0)
	v_mov_b64_e32 v[76:77], s[20:21]
	v_mad_u64_u32 v[76:77], s[8:9], v74, s86, v[76:77]
	v_mov_b32_e32 v74, v77
	v_mad_u64_u32 v[74:75], s[8:9], v75, s86, v[74:75]
	v_cvt_pk_bf16_f32 v70, v70, v71
	v_cvt_pk_bf16_f32 v71, v72, v73
	v_cvt_pk_bf16_f32 v72, v66, v67
	v_add_u32_e32 v66, 0x80, v146
	v_mov_b32_e32 v77, v74
	v_ashrrev_i32_e32 v67, 31, v66
	v_lshl_add_u64 v[74:75], s[46:47], 1, v[76:77]
	v_cvt_pk_bf16_f32 v73, v68, v69
	v_lshl_add_u64 v[68:69], s[48:49], 0, v[66:67]
	v_lshl_add_u64 v[74:75], v[142:143], 1, v[74:75]
	v_lshlrev_b64 v[68:69], 5, v[68:69]
	global_store_dwordx4 v[74:75], v[70:73], off
	v_lshl_add_u64 v[68:69], s[12:13], 0, v[68:69]
	v_mov_b64_e32 v[68:69], v[200:201]
	v_mov_b64_e32 v[70:71], v[202:203]
	s_and_b64 vcc, exec, s[4:5]
	v_cmp_gt_i32_e64 s[8:9], s85, v66
	v_lshl_or_b32 v78, v66, 5, v166
	s_waitcnt vmcnt(0)
	v_mov_b32_e32 v72, v69
	v_mov_b32_e32 v73, v70
	v_mov_b32_e32 v69, v71
	v_pk_add_f32 v[68:69], v[72:73], v[68:69]
	s_nop 0
	v_add_f32_e32 v68, v68, v69
	v_fmamk_f32 v68, v68, 0x3b800000, v163
	v_mul_f32_e32 v69, 0x4b800000, v68
	v_cmp_gt_f32_e64 s[10:11], s84, v68
	s_nop 1
	v_cndmask_b32_e64 v68, v68, v69, s[10:11]
	v_rsq_f32_e32 v68, v68
	s_nop 0
	v_mul_f32_e32 v69, 0x45800000, v68
	v_cndmask_b32_e64 v68, v68, v69, s[10:11]
	v_mul_f32_e32 v68, 0x3dd53b94, v68
	v_pk_mul_f32 v[64:65], v[64:65], v[68:69] op_sel_hi:[1,0]
	v_pk_mul_f32 v[62:63], v[62:63], v[68:69] op_sel_hi:[1,0]
	v_pk_mul_f32 v[60:61], v[60:61], v[68:69] op_sel_hi:[1,0]
	v_pk_mul_f32 v[58:59], v[58:59], v[68:69] op_sel_hi:[1,0]
	s_cbranch_vccnz .LBB0_1490
	v_and_b32_e32 v70, 64, v165
	v_xor_b32_e32 v69, 32, v165
	v_add_u32_e32 v70, 64, v70
	v_cmp_lt_i32_e32 vcc, v69, v70
	s_nop 1
	v_cndmask_b32_e32 v69, v165, v69, vcc
	v_lshlrev_b32_e32 v69, 2, v69
	ds_bpermute_b32 v74, v69, v62
	ds_bpermute_b32 v70, v69, v58
	ds_bpermute_b32 v75, v69, v63
	ds_bpermute_b32 v71, v69, v59
	ds_bpermute_b32 v76, v69, v64
	ds_bpermute_b32 v72, v69, v60
	ds_bpermute_b32 v77, v69, v65
	ds_bpermute_b32 v73, v69, v61
	s_and_saveexec_b64 s[10:11], s[8:9]
	s_cbranch_execz .LBB0_1489
	s_add_i32 s33, s44, 0xffffff80
	s_lshr_b32 s33, s33, 1
	v_add_u32_e32 v80, s33, v78
	v_ashrrev_i32_e32 v81, 31, v80
	v_lshlrev_b64 v[88:89], 2, v[80:81]
	v_lshl_add_u64 v[84:85], s[16:17], 0, v[88:89]
	global_load_dwordx4 v[80:83], v[84:85], off
	s_nop 0
	global_load_dwordx4 v[84:87], v[84:85], off offset:16
	v_lshl_add_u64 v[92:93], s[14:15], 0, v[88:89]
	global_load_dwordx4 v[88:91], v[92:93], off
	s_nop 0
	global_load_dwordx4 v[92:95], v[92:93], off offset:16
	v_mov_b32_e32 v96, v144
	v_mov_b32_e32 v97, v144
	s_waitcnt vmcnt(3)
	v_pk_mul_f32 v[82:83], v[96:97], v[82:83]
	v_pk_mul_f32 v[80:81], v[144:145], v[80:81]
	s_waitcnt vmcnt(2)
	v_pk_mul_f32 v[86:87], v[96:97], v[86:87]
	v_pk_mul_f32 v[84:85], v[144:145], v[84:85]
	s_waitcnt lgkmcnt(1)
	v_pk_mul_f32 v[76:77], v[82:83], v[76:77]
	v_pk_mul_f32 v[74:75], v[80:81], v[74:75]
	s_waitcnt lgkmcnt(0)
	v_pk_mul_f32 v[72:73], v[86:87], v[72:73]
	v_pk_mul_f32 v[70:71], v[84:85], v[70:71]
	s_waitcnt vmcnt(1)
	v_pk_fma_f32 v[64:65], v[64:65], v[90:91], v[76:77]
	v_pk_fma_f32 v[62:63], v[62:63], v[88:89], v[74:75]
	s_waitcnt vmcnt(0)
	v_pk_fma_f32 v[60:61], v[60:61], v[94:95], v[72:73]
	v_pk_fma_f32 v[58:59], v[58:59], v[92:93], v[70:71]

; __device__ __forceinline__ unsigned cvt_pk(float lo, float hi) { unsigned r; asm volatile("v_cvt_pk_bf16_f32 %0, %1, %2" : "=v"(r) : "v"(lo), "v"(hi)); return r; }
;     __device__ __forceinline__ void operator()(const Acc& acc, const Unit& u, int wr, int wc, int fr, int fq) const {
;     ...
;             for (int m = 0; m < 4; ++m) { const int row = u.pm * 256 + ai * 128 + wr * 64 + m * 16 + fr; const size_t R = (size_t)u.pb * NT + row;
;                 const f32x4 sa = *(const f32x4*)(stats + R * 8 + (ISQ ? 0 : 4));
;                 float rr = rsqrtf(((sa[0] + sa[1]) + (sa[2] + sa[3])) * (ISQ ? (1.f / 256.f) : (1.f / 128.f)) + EPS); if (ISQ) rr *= QSCALE;
; #pragma unroll
;                 for (int bj = 0; bj < 2; ++bj) { const int cg_ = u.pn * 256 + bj * 128 + wc * 32; const int h = cg_ / 192, d0 = cg_ - h * 192;
;                     f32x4 a = acc[ai][bj][m][0], b = acc[ai][bj][m][1];
;                     if (d0 < 128) { a = a * rr; b = b * rr; }
;                     else { if (ISQ) { a = a * rr; b = b * rr; }
;                         f32x4 pa, pb;
; #pragma unroll
;                         for (int i = 0; i < 4; ++i) { pa[i] = __shfl_xor(a[i], 32); pb[i] = __shfl_xor(b[i], 32); }
;                         if (row < TL) { const int ti = row * 32 + ((d0 - 128) >> 5) * 16 + 8 * (fq & 1); const float sg = fq < 2 ? -1.f : 1.f;
;                             const f32x4 c0 = *(const f32x4*)(cosT + ti), c1 = *(const f32x4*)(cosT + ti + 4), s0 = *(const f32x4*)(sinT + ti) * sg, s1 = *(const f32x4*)(sinT + ti + 4) * sg;
;                             a = a * c0 + pa * s0; b = b * c1 + pb * s1; } }
;                     bf16_t* dst = O + ((size_t)(u.pb * 4 + h) * NT + row) * pitch + d0 + 8 * fq;
;                     u32x4 w; w.x = cvt_pk(a[0], a[1]); w.y = cvt_pk(a[2], a[3]); w.z = cvt_pk(b[0], b[1]); w.w = cvt_pk(b[2], b[3]); *(u32x4*)dst = w; } }
.LBB0_1494:
	s_waitcnt lgkmcnt(4)
	v_lshl_add_u64 v[58:59], s[54:55], 0, v[66:67]
	s_waitcnt lgkmcnt(0)
	v_mov_b64_e32 v[60:61], s[20:21]
	v_mad_u64_u32 v[60:61], s[8:9], v58, s86, v[60:61]
	v_mov_b32_e32 v58, v61
	v_mad_u64_u32 v[58:59], s[8:9], v59, s86, v[58:59]
	v_cvt_pk_bf16_f32 v54, v54, v55
	v_cvt_pk_bf16_f32 v55, v56, v57
	v_cvt_pk_bf16_f32 v56, v50, v51
	v_add_u32_e32 v50, 0x90, v146
	v_mov_b32_e32 v61, v58
	v_ashrrev_i32_e32 v51, 31, v50
	v_lshl_add_u64 v[58:59], s[46:47], 1, v[60:61]
	v_cvt_pk_bf16_f32 v57, v52, v53
	v_lshl_add_u64 v[52:53], s[48:49], 0, v[50:51]
	v_lshl_add_u64 v[58:59], v[142:143], 1, v[58:59]
	v_lshlrev_b64 v[52:53], 5, v[52:53]
	global_store_dwordx4 v[58:59], v[54:57], off
	v_lshl_add_u64 v[52:53], s[12:13], 0, v[52:53]
	v_mov_b64_e32 v[52:53], v[204:205]
	v_mov_b64_e32 v[54:55], v[206:207]
	s_and_b64 vcc, exec, s[4:5]
	v_cmp_gt_i32_e64 s[8:9], s85, v50
	v_lshl_or_b32 v62, v50, 5, v166
	s_waitcnt vmcnt(0)
	v_mov_b32_e32 v56, v53
	v_mov_b32_e32 v57, v54
	v_mov_b32_e32 v53, v55
	v_pk_add_f32 v[52:53], v[56:57], v[52:53]
	s_nop 0
	v_add_f32_e32 v52, v52, v53
	v_fmamk_f32 v52, v52, 0x3b800000, v163
	v_mul_f32_e32 v53, 0x4b800000, v52
	v_cmp_gt_f32_e64 s[10:11], s84, v52
	s_nop 1
	v_cndmask_b32_e64 v52, v52, v53, s[10:11]
	v_rsq_f32_e32 v52, v52
	s_nop 0
	v_mul_f32_e32 v53, 0x45800000, v52
	v_cndmask_b32_e64 v52, v52, v53, s[10:11]
	v_mul_f32_e32 v52, 0x3dd53b94, v52
	v_pk_mul_f32 v[48:49], v[48:49], v[52:53] op_sel_hi:[1,0]
	v_pk_mul_f32 v[46:47], v[46:47], v[52:53] op_sel_hi:[1,0]
	v_pk_mul_f32 v[44:45], v[44:45], v[52:53] op_sel_hi:[1,0]
	v_pk_mul_f32 v[42:43], v[42:43], v[52:53] op_sel_hi:[1,0]
	s_cbranch_vccnz .LBB0_1498
	v_and_b32_e32 v54, 64, v165
	v_xor_b32_e32 v53, 32, v165
	v_add_u32_e32 v54, 64, v54
	v_cmp_lt_i32_e32 vcc, v53, v54
	s_nop 1
	v_cndmask_b32_e32 v53, v165, v53, vcc
	v_lshlrev_b32_e32 v53, 2, v53
	ds_bpermute_b32 v58, v53, v46
	ds_bpermute_b32 v54, v53, v42
	ds_bpermute_b32 v59, v53, v47
	ds_bpermute_b32 v55, v53, v43
	ds_bpermute_b32 v60, v53, v48
	ds_bpermute_b32 v56, v53, v44
	ds_bpermute_b32 v61, v53, v49
	ds_bpermute_b32 v57, v53, v45
	s_and_saveexec_b64 s[10:11], s[8:9]
	s_cbranch_execz .LBB0_1497
	s_add_i32 s33, s44, 0xffffff80
	s_lshr_b32 s33, s33, 1
	v_add_u32_e32 v64, s33, v62
	v_ashrrev_i32_e32 v65, 31, v64
	v_lshlrev_b64 v[72:73], 2, v[64:65]
	v_lshl_add_u64 v[68:69], s[16:17], 0, v[72:73]
	global_load_dwordx4 v[64:67], v[68:69], off
	s_nop 0
	global_load_dwordx4 v[68:71], v[68:69], off offset:16
	v_lshl_add_u64 v[76:77], s[14:15], 0, v[72:73]
	global_load_dwordx4 v[72:75], v[76:77], off
	s_nop 0
	global_load_dwordx4 v[76:79], v[76:77], off offset:16
	v_mov_b32_e32 v80, v144
	v_mov_b32_e32 v81, v144
	s_waitcnt vmcnt(3)
	v_pk_mul_f32 v[66:67], v[80:81], v[66:67]
	v_pk_mul_f32 v[64:65], v[144:145], v[64:65]
	s_waitcnt vmcnt(2)
	v_pk_mul_f32 v[70:71], v[80:81], v[70:71]
	v_pk_mul_f32 v[68:69], v[144:145], v[68:69]
	s_waitcnt lgkmcnt(1)
	v_pk_mul_f32 v[60:61], v[66:67], v[60:61]
	v_pk_mul_f32 v[58:59], v[64:65], v[58:59]
	s_waitcnt lgkmcnt(0)
	v_pk_mul_f32 v[56:57], v[70:71], v[56:57]
	v_pk_mul_f32 v[54:55], v[68:69], v[54:55]
	s_waitcnt vmcnt(1)
	v_pk_fma_f32 v[48:49], v[48:49], v[74:75], v[60:61]
	v_pk_fma_f32 v[46:47], v[46:47], v[72:73], v[58:59]
	s_waitcnt vmcnt(0)
	v_pk_fma_f32 v[44:45], v[44:45], v[78:79], v[56:57]
	v_pk_fma_f32 v[42:43], v[42:43], v[76:77], v[54:55]

; __device__ __forceinline__ unsigned cvt_pk(float lo, float hi) { unsigned r; asm volatile("v_cvt_pk_bf16_f32 %0, %1, %2" : "=v"(r) : "v"(lo), "v"(hi)); return r; }
;     __device__ __forceinline__ void operator()(const Acc& acc, const Unit& u, int wr, int wc, int fr, int fq) const {
;     ...
;             for (int m = 0; m < 4; ++m) { const int row = u.pm * 256 + ai * 128 + wr * 64 + m * 16 + fr; const size_t R = (size_t)u.pb * NT + row;
;                 const f32x4 sa = *(const f32x4*)(stats + R * 8 + (ISQ ? 0 : 4));
;                 float rr = rsqrtf(((sa[0] + sa[1]) + (sa[2] + sa[3])) * (ISQ ? (1.f / 256.f) : (1.f / 128.f)) + EPS); if (ISQ) rr *= QSCALE;
; #pragma unroll
;                 for (int bj = 0; bj < 2; ++bj) { const int cg_ = u.pn * 256 + bj * 128 + wc * 32; const int h = cg_ / 192, d0 = cg_ - h * 192;
;                     f32x4 a = acc[ai][bj][m][0], b = acc[ai][bj][m][1];
;                     if (d0 < 128) { a = a * rr; b = b * rr; }
;                     else { if (ISQ) { a = a * rr; b = b * rr; }
;                         f32x4 pa, pb;
; #pragma unroll
;                         for (int i = 0; i < 4; ++i) { pa[i] = __shfl_xor(a[i], 32); pb[i] = __shfl_xor(b[i], 32); }
;                         if (row < TL) { const int ti = row * 32 + ((d0 - 128) >> 5) * 16 + 8 * (fq & 1); const float sg = fq < 2 ? -1.f : 1.f;
;                             const f32x4 c0 = *(const f32x4*)(cosT + ti), c1 = *(const f32x4*)(cosT + ti + 4), s0 = *(const f32x4*)(sinT + ti) * sg, s1 = *(const f32x4*)(sinT + ti + 4) * sg;
;                             a = a * c0 + pa * s0; b = b * c1 + pb * s1; } }
;                     bf16_t* dst = O + ((size_t)(u.pb * 4 + h) * NT + row) * pitch + d0 + 8 * fq;
;                     u32x4 w; w.x = cvt_pk(a[0], a[1]); w.y = cvt_pk(a[2], a[3]); w.z = cvt_pk(b[0], b[1]); w.w = cvt_pk(b[2], b[3]); *(u32x4*)dst = w; } }
.LBB0_1502:
	s_waitcnt lgkmcnt(4)
	v_lshl_add_u64 v[42:43], s[54:55], 0, v[50:51]
	s_waitcnt lgkmcnt(0)
	v_mov_b64_e32 v[44:45], s[20:21]
	v_mad_u64_u32 v[44:45], s[8:9], v42, s86, v[44:45]
	v_mov_b32_e32 v42, v45
	v_mad_u64_u32 v[42:43], s[8:9], v43, s86, v[42:43]
	v_cvt_pk_bf16_f32 v38, v38, v39
	v_cvt_pk_bf16_f32 v39, v40, v41
	v_cvt_pk_bf16_f32 v40, v34, v35
	v_add_u32_e32 v34, 0xa0, v146
	v_mov_b32_e32 v45, v42
	v_ashrrev_i32_e32 v35, 31, v34
	v_lshl_add_u64 v[42:43], s[46:47], 1, v[44:45]
	v_cvt_pk_bf16_f32 v41, v36, v37
	v_lshl_add_u64 v[36:37], s[48:49], 0, v[34:35]
	v_lshl_add_u64 v[42:43], v[142:143], 1, v[42:43]
	v_lshlrev_b64 v[36:37], 5, v[36:37]
	global_store_dwordx4 v[42:43], v[38:41], off
	v_lshl_add_u64 v[36:37], s[12:13], 0, v[36:37]
	v_mov_b64_e32 v[36:37], v[208:209]
	v_mov_b64_e32 v[38:39], v[210:211]
	s_and_b64 vcc, exec, s[4:5]
	v_cmp_gt_i32_e64 s[8:9], s85, v34
	v_lshl_or_b32 v46, v34, 5, v166
	s_waitcnt vmcnt(0)
	v_mov_b32_e32 v40, v37
	v_mov_b32_e32 v41, v38
	v_mov_b32_e32 v37, v39
	v_pk_add_f32 v[36:37], v[40:41], v[36:37]
	s_nop 0
	v_add_f32_e32 v36, v36, v37
	v_fmamk_f32 v36, v36, 0x3b800000, v163
	v_mul_f32_e32 v37, 0x4b800000, v36
	v_cmp_gt_f32_e64 s[10:11], s84, v36
	s_nop 1
	v_cndmask_b32_e64 v36, v36, v37, s[10:11]
	v_rsq_f32_e32 v36, v36
	s_nop 0
	v_mul_f32_e32 v37, 0x45800000, v36
	v_cndmask_b32_e64 v36, v36, v37, s[10:11]
	v_mul_f32_e32 v36, 0x3dd53b94, v36
	v_pk_mul_f32 v[32:33], v[32:33], v[36:37] op_sel_hi:[1,0]
	v_pk_mul_f32 v[30:31], v[30:31], v[36:37] op_sel_hi:[1,0]
	v_pk_mul_f32 v[28:29], v[28:29], v[36:37] op_sel_hi:[1,0]
	v_pk_mul_f32 v[26:27], v[26:27], v[36:37] op_sel_hi:[1,0]
	s_cbranch_vccnz .LBB0_1506
	v_and_b32_e32 v38, 64, v165
	v_xor_b32_e32 v37, 32, v165
	v_add_u32_e32 v38, 64, v38
	v_cmp_lt_i32_e32 vcc, v37, v38
	s_nop 1
	v_cndmask_b32_e32 v37, v165, v37, vcc
	v_lshlrev_b32_e32 v37, 2, v37
	ds_bpermute_b32 v42, v37, v30
	ds_bpermute_b32 v38, v37, v26
	ds_bpermute_b32 v43, v37, v31
	ds_bpermute_b32 v39, v37, v27
	ds_bpermute_b32 v44, v37, v32
	ds_bpermute_b32 v40, v37, v28
	ds_bpermute_b32 v45, v37, v33
	ds_bpermute_b32 v41, v37, v29
	s_and_saveexec_b64 s[10:11], s[8:9]
	s_cbranch_execz .LBB0_1505
	s_add_i32 s33, s44, 0xffffff80
	s_lshr_b32 s33, s33, 1
	v_add_u32_e32 v48, s33, v46
	v_ashrrev_i32_e32 v49, 31, v48
	v_lshlrev_b64 v[56:57], 2, v[48:49]
	v_lshl_add_u64 v[52:53], s[16:17], 0, v[56:57]
	global_load_dwordx4 v[48:51], v[52:53], off
	s_nop 0
	global_load_dwordx4 v[52:55], v[52:53], off offset:16
	v_lshl_add_u64 v[60:61], s[14:15], 0, v[56:57]
	global_load_dwordx4 v[56:59], v[60:61], off
	s_nop 0
	global_load_dwordx4 v[60:63], v[60:61], off offset:16
	v_mov_b32_e32 v64, v144
	v_mov_b32_e32 v65, v144
	s_waitcnt vmcnt(3)
	v_pk_mul_f32 v[50:51], v[64:65], v[50:51]
	v_pk_mul_f32 v[48:49], v[144:145], v[48:49]
	s_waitcnt vmcnt(2)
	v_pk_mul_f32 v[54:55], v[64:65], v[54:55]
	v_pk_mul_f32 v[52:53], v[144:145], v[52:53]
	s_waitcnt lgkmcnt(1)
	v_pk_mul_f32 v[44:45], v[50:51], v[44:45]
	v_pk_mul_f32 v[42:43], v[48:49], v[42:43]
	s_waitcnt lgkmcnt(0)
	v_pk_mul_f32 v[40:41], v[54:55], v[40:41]
	v_pk_mul_f32 v[38:39], v[52:53], v[38:39]
	s_waitcnt vmcnt(1)
	v_pk_fma_f32 v[32:33], v[32:33], v[58:59], v[44:45]
	v_pk_fma_f32 v[30:31], v[30:31], v[56:57], v[42:43]
	s_waitcnt vmcnt(0)
	v_pk_fma_f32 v[28:29], v[28:29], v[62:63], v[40:41]
	v_pk_fma_f32 v[26:27], v[26:27], v[60:61], v[38:39]

; __device__ __forceinline__ unsigned cvt_pk(float lo, float hi) { unsigned r; asm volatile("v_cvt_pk_bf16_f32 %0, %1, %2" : "=v"(r) : "v"(lo), "v"(hi)); return r; }
;     __device__ __forceinline__ void operator()(const Acc& acc, const Unit& u, int wr, int wc, int fr, int fq) const {
;     ...
;             for (int m = 0; m < 4; ++m) { const int row = u.pm * 256 + ai * 128 + wr * 64 + m * 16 + fr; const size_t R = (size_t)u.pb * NT + row;
;                 const f32x4 sa = *(const f32x4*)(stats + R * 8 + (ISQ ? 0 : 4));
;                 float rr = rsqrtf(((sa[0] + sa[1]) + (sa[2] + sa[3])) * (ISQ ? (1.f / 256.f) : (1.f / 128.f)) + EPS); if (ISQ) rr *= QSCALE;
; #pragma unroll
;                 for (int bj = 0; bj < 2; ++bj) { const int cg_ = u.pn * 256 + bj * 128 + wc * 32; const int h = cg_ / 192, d0 = cg_ - h * 192;
;                     f32x4 a = acc[ai][bj][m][0], b = acc[ai][bj][m][1];
;                     if (d0 < 128) { a = a * rr; b = b * rr; }
;                     else { if (ISQ) { a = a * rr; b = b * rr; }
;                         f32x4 pa, pb;
; #pragma unroll
;                         for (int i = 0; i < 4; ++i) { pa[i] = __shfl_xor(a[i], 32); pb[i] = __shfl_xor(b[i], 32); }
;                         if (row < TL) { const int ti = row * 32 + ((d0 - 128) >> 5) * 16 + 8 * (fq & 1); const float sg = fq < 2 ? -1.f : 1.f;
;                             const f32x4 c0 = *(const f32x4*)(cosT + ti), c1 = *(const f32x4*)(cosT + ti + 4), s0 = *(const f32x4*)(sinT + ti) * sg, s1 = *(const f32x4*)(sinT + ti + 4) * sg;
;                             a = a * c0 + pa * s0; b = b * c1 + pb * s1; } }
;                     bf16_t* dst = O + ((size_t)(u.pb * 4 + h) * NT + row) * pitch + d0 + 8 * fq;
;                     u32x4 w; w.x = cvt_pk(a[0], a[1]); w.y = cvt_pk(a[2], a[3]); w.z = cvt_pk(b[0], b[1]); w.w = cvt_pk(b[2], b[3]); *(u32x4*)dst = w; } }
.LBB0_1510:
	s_waitcnt lgkmcnt(4)
	v_lshl_add_u64 v[26:27], s[54:55], 0, v[34:35]
	s_waitcnt lgkmcnt(0)
	v_mov_b64_e32 v[28:29], s[20:21]
	v_mad_u64_u32 v[28:29], s[8:9], v26, s86, v[28:29]
	v_mov_b32_e32 v26, v29
	v_mad_u64_u32 v[26:27], s[8:9], v27, s86, v[26:27]
	v_cvt_pk_bf16_f32 v22, v22, v23
	v_cvt_pk_bf16_f32 v23, v24, v25
	v_cvt_pk_bf16_f32 v24, v18, v19
	v_add_u32_e32 v18, 0xb0, v146
	v_mov_b32_e32 v29, v26
	v_ashrrev_i32_e32 v19, 31, v18
	v_lshl_add_u64 v[26:27], s[46:47], 1, v[28:29]
	v_cvt_pk_bf16_f32 v25, v20, v21
	v_lshl_add_u64 v[20:21], s[48:49], 0, v[18:19]
	v_lshl_add_u64 v[26:27], v[142:143], 1, v[26:27]
	v_lshlrev_b64 v[20:21], 5, v[20:21]
	global_store_dwordx4 v[26:27], v[22:25], off
	v_lshl_add_u64 v[20:21], s[12:13], 0, v[20:21]
	v_mov_b64_e32 v[20:21], v[212:213]
	v_mov_b64_e32 v[22:23], v[214:215]
	s_and_b64 vcc, exec, s[4:5]
	v_cmp_gt_i32_e64 s[4:5], s85, v18
	v_lshl_or_b32 v30, v18, 5, v166
	s_waitcnt vmcnt(0)
	v_mov_b32_e32 v24, v21
	v_mov_b32_e32 v25, v22
	v_mov_b32_e32 v21, v23
	v_pk_add_f32 v[20:21], v[24:25], v[20:21]
	s_nop 0
	v_add_f32_e32 v20, v20, v21
	v_fmamk_f32 v20, v20, 0x3b800000, v163
	v_mul_f32_e32 v21, 0x4b800000, v20
	v_cmp_gt_f32_e64 s[8:9], s84, v20
	s_nop 1
	v_cndmask_b32_e64 v20, v20, v21, s[8:9]
	v_rsq_f32_e32 v20, v20
	s_nop 0
	v_mul_f32_e32 v21, 0x45800000, v20
	v_cndmask_b32_e64 v20, v20, v21, s[8:9]
	v_mul_f32_e32 v20, 0x3dd53b94, v20
	v_pk_mul_f32 v[16:17], v[16:17], v[20:21] op_sel_hi:[1,0]
	v_pk_mul_f32 v[14:15], v[14:15], v[20:21] op_sel_hi:[1,0]
	v_pk_mul_f32 v[12:13], v[12:13], v[20:21] op_sel_hi:[1,0]
	v_pk_mul_f32 v[10:11], v[10:11], v[20:21] op_sel_hi:[1,0]
	s_cbranch_vccnz .LBB0_1514
	v_and_b32_e32 v22, 64, v165
	v_xor_b32_e32 v21, 32, v165
	v_add_u32_e32 v22, 64, v22
	v_cmp_lt_i32_e32 vcc, v21, v22
	s_nop 1
	v_cndmask_b32_e32 v21, v165, v21, vcc
	v_lshlrev_b32_e32 v21, 2, v21
	ds_bpermute_b32 v26, v21, v14
	ds_bpermute_b32 v22, v21, v10
	ds_bpermute_b32 v27, v21, v15
	ds_bpermute_b32 v23, v21, v11
	ds_bpermute_b32 v28, v21, v16
	ds_bpermute_b32 v24, v21, v12
	ds_bpermute_b32 v29, v21, v17
	ds_bpermute_b32 v25, v21, v13
	s_and_saveexec_b64 s[8:9], s[4:5]
	s_cbranch_execz .LBB0_1513
	s_add_i32 s10, s44, 0xffffff80
	s_lshr_b32 s10, s10, 1
	v_add_u32_e32 v32, s10, v30
	v_ashrrev_i32_e32 v33, 31, v32
	v_lshlrev_b64 v[40:41], 2, v[32:33]
	v_lshl_add_u64 v[36:37], s[16:17], 0, v[40:41]
	global_load_dwordx4 v[32:35], v[36:37], off
	s_nop 0
	global_load_dwordx4 v[36:39], v[36:37], off offset:16
	v_lshl_add_u64 v[44:45], s[14:15], 0, v[40:41]
	global_load_dwordx4 v[40:43], v[44:45], off
	s_nop 0
	global_load_dwordx4 v[44:47], v[44:45], off offset:16
	v_mov_b32_e32 v48, v144
	v_mov_b32_e32 v49, v144
	s_waitcnt vmcnt(3)
	v_pk_mul_f32 v[34:35], v[48:49], v[34:35]
	v_pk_mul_f32 v[32:33], v[144:145], v[32:33]
	s_waitcnt vmcnt(2)
	v_pk_mul_f32 v[38:39], v[48:49], v[38:39]
	v_pk_mul_f32 v[36:37], v[144:145], v[36:37]
	s_waitcnt lgkmcnt(1)
	v_pk_mul_f32 v[28:29], v[34:35], v[28:29]
	v_pk_mul_f32 v[26:27], v[32:33], v[26:27]
	s_waitcnt lgkmcnt(0)
	v_pk_mul_f32 v[24:25], v[38:39], v[24:25]
	v_pk_mul_f32 v[22:23], v[36:37], v[22:23]
	s_waitcnt vmcnt(1)
	v_pk_fma_f32 v[16:17], v[16:17], v[42:43], v[28:29]
	v_pk_fma_f32 v[14:15], v[14:15], v[40:41], v[26:27]
	s_waitcnt vmcnt(0)
	v_pk_fma_f32 v[12:13], v[12:13], v[46:47], v[24:25]
	v_pk_fma_f32 v[10:11], v[10:11], v[44:45], v[22:23]

; __device__ __forceinline__ unsigned cvt_pk(float lo, float hi) { unsigned r; asm volatile("v_cvt_pk_bf16_f32 %0, %1, %2" : "=v"(r) : "v"(lo), "v"(hi)); return r; }
;     __device__ __forceinline__ void operator()(const Acc& acc, const Unit& u, int wr, int wc, int fr, int fq) const {
;     ...
;             for (int m = 0; m < 4; ++m) { const int row = u.pm * 256 + ai * 128 + wr * 64 + m * 16 + fr; const size_t R = (size_t)u.pb * NT + row;
;                 const f32x4 sa = *(const f32x4*)(stats + R * 8 + (ISQ ? 0 : 4));
;                 float rr = rsqrtf(((sa[0] + sa[1]) + (sa[2] + sa[3])) * (ISQ ? (1.f / 256.f) : (1.f / 128.f)) + EPS); if (ISQ) rr *= QSCALE;
; #pragma unroll
;                 for (int bj = 0; bj < 2; ++bj) { const int cg_ = u.pn * 256 + bj * 128 + wc * 32; const int h = cg_ / 192, d0 = cg_ - h * 192;
;                     f32x4 a = acc[ai][bj][m][0], b = acc[ai][bj][m][1];
;                     if (d0 < 128) { a = a * rr; b = b * rr; }
;                     else { if (ISQ) { a = a * rr; b = b * rr; }
;                         f32x4 pa, pb;
; #pragma unroll
;                         for (int i = 0; i < 4; ++i) { pa[i] = __shfl_xor(a[i], 32); pb[i] = __shfl_xor(b[i], 32); }
;                         if (row < TL) { const int ti = row * 32 + ((d0 - 128) >> 5) * 16 + 8 * (fq & 1); const float sg = fq < 2 ? -1.f : 1.f;
;                             const f32x4 c0 = *(const f32x4*)(cosT + ti), c1 = *(const f32x4*)(cosT + ti + 4), s0 = *(const f32x4*)(sinT + ti) * sg, s1 = *(const f32x4*)(sinT + ti + 4) * sg;
;                             a = a * c0 + pa * s0; b = b * c1 + pb * s1; } }
;                     bf16_t* dst = O + ((size_t)(u.pb * 4 + h) * NT + row) * pitch + d0 + 8 * fq;
;                     u32x4 w; w.x = cvt_pk(a[0], a[1]); w.y = cvt_pk(a[2], a[3]); w.z = cvt_pk(b[0], b[1]); w.w = cvt_pk(b[2], b[3]); *(u32x4*)dst = w; } }
.LBB0_1540:
	v_mov_b32_e32 v134, v164
	s_lshl_b32 s92, s92, 8
	v_and_or_b32 v173, v134, 15, s83
	v_add_u32_e32 v154, s92, v173
	v_ashrrev_i32_e32 v155, 31, v154
	v_mad_i64_i32 v[130:131], s[4:5], s56, v170, v[154:155]
	v_lshlrev_b64 v[130:131], 5, v[130:131]
	v_lshl_add_u64 v[130:131], s[12:13], 0, v[130:131]
	v_mov_b64_e32 v[218:219], v[130:131]
	global_load_dwordx4 v[130:133], v[130:131], off offset:16
	s_mov_b32 s98, 0x1000
	s_mov_b32 s99, 0
	global_load_dwordx4 v[188:191], v[218:219], off offset:528
	global_load_dwordx4 v[192:195], v[218:219], off offset:1040
	global_load_dwordx4 v[196:199], v[218:219], off offset:1552
	v_lshl_add_u64 v[216:217], v[218:219], 0, s[98:99]
	global_load_dwordx4 v[200:203], v[216:217], off offset:16
	global_load_dwordx4 v[204:207], v[216:217], off offset:528
	global_load_dwordx4 v[208:211], v[216:217], off offset:1040
	global_load_dwordx4 v[212:215], v[216:217], off offset:1552
	s_lshl_b32 s4, s57, 8
	s_or_b32 s8, s4, s84
	s_mul_hi_i32 s4, s8, 0x2aaaaaab
	v_ashrrev_i32_e32 v134, 4, v134
	s_lshr_b32 s6, s4, 31
	s_ashr_i32 s33, s4, 5
	v_lshlrev_b32_e32 v150, 3, v134
	v_cmp_gt_i32_e32 vcc, 2, v134
	s_add_i32 s33, s33, s6
	s_mul_i32 s6, s33, 0xffffff40
	s_add_i32 s44, s6, s8
	v_cndmask_b32_e64 v152, 1.0, -1.0, vcc
	v_and_b32_e32 v172, 8, v150
	s_cmpk_gt_i32 s44, 0x7f
	v_mov_b32_e32 v153, v152
	v_cmp_gt_i32_e64 s[4:5], s78, v154
	v_lshl_or_b32 v174, v154, 5, v172
	s_cselect_b64 s[10:11], -1, 0
	s_cmpk_lt_i32 s44, 0x80
	s_mov_b64 s[6:7], -1
	s_waitcnt vmcnt(0)
	v_mov_b32_e32 v134, v131
	v_mov_b32_e32 v135, v132
	v_mov_b32_e32 v131, v133
	v_pk_add_f32 v[130:131], v[134:135], v[130:131]
	s_nop 0
	v_add_f32_e32 v130, v130, v131
	v_fmamk_f32 v151, v130, 0x3c000000, v169
	v_cmp_gt_f32_e32 vcc, s89, v151
	s_cbranch_scc1 .LBB0_1544
	v_and_b32_e32 v131, 64, v171
	v_xor_b32_e32 v130, 32, v171
	v_add_u32_e32 v131, 64, v131
	v_cmp_lt_i32_e64 s[6:7], v130, v131
	v_mov_b64_e32 v[136:137], v[124:125]
	v_mov_b64_e32 v[134:135], v[122:123]
	v_cndmask_b32_e64 v130, v171, v130, s[6:7]
	v_lshlrev_b32_e32 v130, 2, v130
	ds_bpermute_b32 v160, v130, v126
	ds_bpermute_b32 v156, v130, v122
	ds_bpermute_b32 v161, v130, v127
	ds_bpermute_b32 v157, v130, v123
	ds_bpermute_b32 v162, v130, v128
	ds_bpermute_b32 v158, v130, v124
	ds_bpermute_b32 v163, v130, v129
	ds_bpermute_b32 v159, v130, v125
	v_mov_b64_e32 v[132:133], v[128:129]
	v_mov_b64_e32 v[130:131], v[126:127]
	s_and_saveexec_b64 s[6:7], s[4:5]
	s_cbranch_execz .LBB0_1543
	s_add_i32 s9, s44, 0xffffff80
	s_lshr_b32 s9, s9, 1
	v_add_u32_e32 v130, s9, v174
	v_ashrrev_i32_e32 v131, 31, v130
	v_lshlrev_b64 v[176:177], 2, v[130:131]
	v_lshl_add_u64 v[134:135], s[16:17], 0, v[176:177]
	global_load_dwordx4 v[130:133], v[134:135], off
	s_nop 0
	global_load_dwordx4 v[134:137], v[134:135], off offset:16
	v_lshl_add_u64 v[180:181], s[14:15], 0, v[176:177]
	global_load_dwordx4 v[176:179], v[180:181], off
	s_nop 0
	global_load_dwordx4 v[180:183], v[180:181], off offset:16
	v_mov_b32_e32 v184, v152
	v_mov_b32_e32 v185, v152
	s_waitcnt vmcnt(3)
	v_pk_mul_f32 v[132:133], v[184:185], v[132:133]
	v_pk_mul_f32 v[130:131], v[152:153], v[130:131]
	s_waitcnt vmcnt(2)
	v_pk_mul_f32 v[136:137], v[184:185], v[136:137]
	v_pk_mul_f32 v[134:135], v[152:153], v[134:135]
	s_waitcnt lgkmcnt(1)
	v_pk_mul_f32 v[132:133], v[132:133], v[162:163]
	v_pk_mul_f32 v[130:131], v[130:131], v[160:161]
	s_waitcnt lgkmcnt(0)
	v_pk_mul_f32 v[136:137], v[136:137], v[158:159]
	v_pk_mul_f32 v[134:135], v[134:135], v[156:157]
	s_waitcnt vmcnt(1)
	v_pk_fma_f32 v[132:133], v[128:129], v[178:179], v[132:133]
	v_pk_fma_f32 v[130:131], v[126:127], v[176:177], v[130:131]
	s_waitcnt vmcnt(0)
	v_pk_fma_f32 v[136:137], v[124:125], v[182:183], v[136:137]
	v_pk_fma_f32 v[134:135], v[122:123], v[180:181], v[134:135]

; __device__ __forceinline__ unsigned cvt_pk(float lo, float hi) { unsigned r; asm volatile("v_cvt_pk_bf16_f32 %0, %1, %2" : "=v"(r) : "v"(lo), "v"(hi)); return r; }
;     __device__ __forceinline__ void operator()(const Acc& acc, const Unit& u, int wr, int wc, int fr, int fq) const {
;     ...
;             for (int m = 0; m < 4; ++m) { const int row = u.pm * 256 + ai * 128 + wr * 64 + m * 16 + fr; const size_t R = (size_t)u.pb * NT + row;
;                 const f32x4 sa = *(const f32x4*)(stats + R * 8 + (ISQ ? 0 : 4));
;                 float rr = rsqrtf(((sa[0] + sa[1]) + (sa[2] + sa[3])) * (ISQ ? (1.f / 256.f) : (1.f / 128.f)) + EPS); if (ISQ) rr *= QSCALE;
; #pragma unroll
;                 for (int bj = 0; bj < 2; ++bj) { const int cg_ = u.pn * 256 + bj * 128 + wc * 32; const int h = cg_ / 192, d0 = cg_ - h * 192;
;                     f32x4 a = acc[ai][bj][m][0], b = acc[ai][bj][m][1];
;                     if (d0 < 128) { a = a * rr; b = b * rr; }
;                     else { if (ISQ) { a = a * rr; b = b * rr; }
;                         f32x4 pa, pb;
; #pragma unroll
;                         for (int i = 0; i < 4; ++i) { pa[i] = __shfl_xor(a[i], 32); pb[i] = __shfl_xor(b[i], 32); }
;                         if (row < TL) { const int ti = row * 32 + ((d0 - 128) >> 5) * 16 + 8 * (fq & 1); const float sg = fq < 2 ? -1.f : 1.f;
;                             const f32x4 c0 = *(const f32x4*)(cosT + ti), c1 = *(const f32x4*)(cosT + ti + 4), s0 = *(const f32x4*)(sinT + ti) * sg, s1 = *(const f32x4*)(sinT + ti + 4) * sg;
;                             a = a * c0 + pa * s0; b = b * c1 + pb * s1; } }
;                     bf16_t* dst = O + ((size_t)(u.pb * 4 + h) * NT + row) * pitch + d0 + 8 * fq;
;                     u32x4 w; w.x = cvt_pk(a[0], a[1]); w.y = cvt_pk(a[2], a[3]); w.z = cvt_pk(b[0], b[1]); w.w = cvt_pk(b[2], b[3]); *(u32x4*)dst = w; } }
.LBB0_1552:
	s_mul_hi_i32 s49, s56, 0x900
	s_mul_i32 s48, s56, 0x900
	s_add_i32 s56, s8, s9
	v_mad_i64_i32 v[114:115], s[4:5], s56, v170, v[154:155]
	v_mov_b64_e32 v[116:117], s[20:21]
	v_mad_u64_u32 v[116:117], s[4:5], v114, s34, v[116:117]
	v_mad_i32_i24 v117, v115, s34, v117
	s_ashr_i32 s47, s46, 31
	v_lshl_add_u64 v[114:115], s[46:47], 1, v[116:117]
	v_lshl_add_u64 v[118:119], v[150:151], 1, v[114:115]
	v_cvt_pk_bf16_f32 v114, v122, v123
	v_add3_u32 v122, s92, v173, 16
	v_cvt_pk_bf16_f32 v115, v124, v125
	v_ashrrev_i32_e32 v123, 31, v122
	v_cvt_pk_bf16_f32 v116, v126, v127
	v_cvt_pk_bf16_f32 v117, v128, v129
	global_store_dwordx4 v[118:119], v[114:117], off
	v_cndmask_b32_e64 v118, 0, 1, s[10:11]
	v_cmp_ne_u32_e64 s[4:5], 1, v118
	v_lshl_add_u64 v[114:115], s[48:49], 0, v[122:123]
	v_lshlrev_b64 v[114:115], 5, v[114:115]
	v_lshl_add_u64 v[114:115], s[12:13], 0, v[114:115]
	v_mov_b64_e32 v[114:115], v[188:189]
	v_mov_b64_e32 v[116:117], v[190:191]
	v_cmp_gt_i32_e64 s[8:9], s78, v122
	s_waitcnt lgkmcnt(2)
	v_lshl_or_b32 v132, v122, 5, v172
	s_andn2_b64 vcc, exec, s[10:11]
	s_mov_b64 s[10:11], -1
	s_waitcnt vmcnt(0)
	v_mov_b32_e32 v118, v115
	v_mov_b32_e32 v119, v116
	v_mov_b32_e32 v115, v117
	v_pk_add_f32 v[114:115], v[118:119], v[114:115]
	s_nop 0
	v_add_f32_e32 v114, v114, v115
	s_waitcnt lgkmcnt(0)
	v_fmamk_f32 v133, v114, 0x3c000000, v169
	v_cmp_gt_f32_e64 s[6:7], s89, v133
	s_cbranch_vccnz .LBB0_1556
	v_and_b32_e32 v115, 64, v171
	v_xor_b32_e32 v114, 32, v171
	v_add_u32_e32 v115, 64, v115
	v_cmp_lt_i32_e32 vcc, v114, v115
	v_mov_b64_e32 v[120:121], v[108:109]
	v_mov_b64_e32 v[118:119], v[106:107]
	v_cndmask_b32_e32 v114, v171, v114, vcc
	v_lshlrev_b32_e32 v114, 2, v114
	ds_bpermute_b32 v128, v114, v110
	ds_bpermute_b32 v124, v114, v106
	ds_bpermute_b32 v129, v114, v111
	ds_bpermute_b32 v125, v114, v107
	ds_bpermute_b32 v130, v114, v112
	ds_bpermute_b32 v126, v114, v108
	ds_bpermute_b32 v131, v114, v113
	ds_bpermute_b32 v127, v114, v109
	v_mov_b64_e32 v[116:117], v[112:113]
	v_mov_b64_e32 v[114:115], v[110:111]
	s_and_saveexec_b64 s[10:11], s[8:9]
	s_cbranch_execz .LBB0_1555
	s_add_i32 s33, s44, 0xffffff80
	s_lshr_b32 s33, s33, 1
	v_add_u32_e32 v114, s33, v132
	v_ashrrev_i32_e32 v115, 31, v114
	v_lshlrev_b64 v[134:135], 2, v[114:115]
	v_lshl_add_u64 v[118:119], s[16:17], 0, v[134:135]
	global_load_dwordx4 v[114:117], v[118:119], off
	s_nop 0
	global_load_dwordx4 v[118:121], v[118:119], off offset:16
	v_lshl_add_u64 v[156:157], s[14:15], 0, v[134:135]
	global_load_dwordx4 v[134:137], v[156:157], off
	s_nop 0
	global_load_dwordx4 v[156:159], v[156:157], off offset:16
	v_mov_b32_e32 v160, v152
	v_mov_b32_e32 v161, v152
	s_waitcnt vmcnt(3)
	v_pk_mul_f32 v[116:117], v[160:161], v[116:117]
	v_pk_mul_f32 v[114:115], v[152:153], v[114:115]
	s_waitcnt vmcnt(2)
	v_pk_mul_f32 v[120:121], v[160:161], v[120:121]
	v_pk_mul_f32 v[118:119], v[152:153], v[118:119]
	s_waitcnt lgkmcnt(1)
	v_pk_mul_f32 v[116:117], v[116:117], v[130:131]
	v_pk_mul_f32 v[114:115], v[114:115], v[128:129]
	s_waitcnt lgkmcnt(0)
	v_pk_mul_f32 v[120:121], v[120:121], v[126:127]
	v_pk_mul_f32 v[118:119], v[118:119], v[124:125]
	s_waitcnt vmcnt(1)
	v_pk_fma_f32 v[116:117], v[112:113], v[136:137], v[116:117]
	v_pk_fma_f32 v[114:115], v[110:111], v[134:135], v[114:115]
	s_waitcnt vmcnt(0)
	v_pk_fma_f32 v[120:121], v[108:109], v[158:159], v[120:121]
	v_pk_fma_f32 v[118:119], v[106:107], v[156:157], v[118:119]

; __device__ __forceinline__ unsigned cvt_pk(float lo, float hi) { unsigned r; asm volatile("v_cvt_pk_bf16_f32 %0, %1, %2" : "=v"(r) : "v"(lo), "v"(hi)); return r; }
;     __device__ __forceinline__ void operator()(const Acc& acc, const Unit& u, int wr, int wc, int fr, int fq) const {
;     ...
;             for (int m = 0; m < 4; ++m) { const int row = u.pm * 256 + ai * 128 + wr * 64 + m * 16 + fr; const size_t R = (size_t)u.pb * NT + row;
;                 const f32x4 sa = *(const f32x4*)(stats + R * 8 + (ISQ ? 0 : 4));
;                 float rr = rsqrtf(((sa[0] + sa[1]) + (sa[2] + sa[3])) * (ISQ ? (1.f / 256.f) : (1.f / 128.f)) + EPS); if (ISQ) rr *= QSCALE;
; #pragma unroll
;                 for (int bj = 0; bj < 2; ++bj) { const int cg_ = u.pn * 256 + bj * 128 + wc * 32; const int h = cg_ / 192, d0 = cg_ - h * 192;
;                     f32x4 a = acc[ai][bj][m][0], b = acc[ai][bj][m][1];
;                     if (d0 < 128) { a = a * rr; b = b * rr; }
;                     else { if (ISQ) { a = a * rr; b = b * rr; }
;                         f32x4 pa, pb;
; #pragma unroll
;                         for (int i = 0; i < 4; ++i) { pa[i] = __shfl_xor(a[i], 32); pb[i] = __shfl_xor(b[i], 32); }
;                         if (row < TL) { const int ti = row * 32 + ((d0 - 128) >> 5) * 16 + 8 * (fq & 1); const float sg = fq < 2 ? -1.f : 1.f;
;                             const f32x4 c0 = *(const f32x4*)(cosT + ti), c1 = *(const f32x4*)(cosT + ti + 4), s0 = *(const f32x4*)(sinT + ti) * sg, s1 = *(const f32x4*)(sinT + ti + 4) * sg;
;                             a = a * c0 + pa * s0; b = b * c1 + pb * s1; } }
;                     bf16_t* dst = O + ((size_t)(u.pb * 4 + h) * NT + row) * pitch + d0 + 8 * fq;
;                     u32x4 w; w.x = cvt_pk(a[0], a[1]); w.y = cvt_pk(a[2], a[3]); w.z = cvt_pk(b[0], b[1]); w.w = cvt_pk(b[2], b[3]); *(u32x4*)dst = w; } }
.LBB0_1564:
	s_mul_hi_i32 s55, s56, 0x900
	s_mul_i32 s54, s56, 0x900
	v_lshl_add_u64 v[98:99], s[54:55], 0, v[122:123]
	v_mov_b64_e32 v[100:101], s[20:21]
	v_mad_u64_u32 v[100:101], s[8:9], v98, s34, v[100:101]
	v_mov_b32_e32 v98, v101
	v_mad_u64_u32 v[98:99], s[8:9], v99, s34, v[98:99]
	v_mov_b32_e32 v101, v98
	v_lshl_add_u64 v[98:99], s[46:47], 1, v[100:101]
	v_lshl_add_u64 v[102:103], v[150:151], 1, v[98:99]
	v_cvt_pk_bf16_f32 v98, v106, v107
	v_add3_u32 v106, s92, v173, 32
	v_cvt_pk_bf16_f32 v99, v108, v109
	v_ashrrev_i32_e32 v107, 31, v106
	v_cvt_pk_bf16_f32 v100, v110, v111
	v_cvt_pk_bf16_f32 v101, v112, v113
	global_store_dwordx4 v[102:103], v[98:101], off
	s_and_b64 vcc, exec, s[4:5]
	v_cmp_gt_i32_e64 s[8:9], s78, v106
	v_lshl_add_u64 v[98:99], s[48:49], 0, v[106:107]
	v_lshlrev_b64 v[98:99], 5, v[98:99]
	v_lshl_add_u64 v[98:99], s[12:13], 0, v[98:99]
	v_mov_b64_e32 v[98:99], v[192:193]
	v_mov_b64_e32 v[100:101], v[194:195]
	s_waitcnt lgkmcnt(2)
	v_lshl_or_b32 v116, v106, 5, v172
	s_mov_b64 s[56:57], -1
	s_waitcnt vmcnt(0)
	v_mov_b32_e32 v102, v99
	v_mov_b32_e32 v103, v100
	v_mov_b32_e32 v99, v101
	v_pk_add_f32 v[98:99], v[102:103], v[98:99]
	s_nop 0
	v_add_f32_e32 v98, v98, v99
	s_waitcnt lgkmcnt(0)
	v_fmamk_f32 v117, v98, 0x3c000000, v169
	v_cmp_gt_f32_e64 s[10:11], s89, v117
	s_cbranch_vccnz .LBB0_1568
	v_and_b32_e32 v99, 64, v171
	v_xor_b32_e32 v98, 32, v171
	v_add_u32_e32 v99, 64, v99
	v_cmp_lt_i32_e32 vcc, v98, v99
	v_mov_b64_e32 v[104:105], v[92:93]
	v_mov_b64_e32 v[102:103], v[90:91]
	v_cndmask_b32_e32 v98, v171, v98, vcc
	v_lshlrev_b32_e32 v98, 2, v98
	ds_bpermute_b32 v112, v98, v94
	ds_bpermute_b32 v108, v98, v90
	ds_bpermute_b32 v113, v98, v95
	ds_bpermute_b32 v109, v98, v91
	ds_bpermute_b32 v114, v98, v96
	ds_bpermute_b32 v110, v98, v92
	ds_bpermute_b32 v115, v98, v97
	ds_bpermute_b32 v111, v98, v93
	v_mov_b64_e32 v[100:101], v[96:97]
	v_mov_b64_e32 v[98:99], v[94:95]
	s_and_saveexec_b64 s[56:57], s[8:9]
	s_cbranch_execz .LBB0_1567
	s_add_i32 s33, s44, 0xffffff80
	s_lshr_b32 s33, s33, 1
	v_add_u32_e32 v98, s33, v116
	v_ashrrev_i32_e32 v99, 31, v98
	v_lshlrev_b64 v[118:119], 2, v[98:99]
	v_lshl_add_u64 v[102:103], s[16:17], 0, v[118:119]
	global_load_dwordx4 v[98:101], v[102:103], off
	s_nop 0
	global_load_dwordx4 v[102:105], v[102:103], off offset:16
	v_lshl_add_u64 v[122:123], s[14:15], 0, v[118:119]
	global_load_dwordx4 v[118:121], v[122:123], off
	s_nop 0
	global_load_dwordx4 v[122:125], v[122:123], off offset:16
	v_mov_b32_e32 v126, v152
	v_mov_b32_e32 v127, v152
	s_waitcnt vmcnt(3)
	v_pk_mul_f32 v[100:101], v[126:127], v[100:101]
	v_pk_mul_f32 v[98:99], v[152:153], v[98:99]
	s_waitcnt vmcnt(2)
	v_pk_mul_f32 v[104:105], v[126:127], v[104:105]
	v_pk_mul_f32 v[102:103], v[152:153], v[102:103]
	s_waitcnt lgkmcnt(1)
	v_pk_mul_f32 v[100:101], v[100:101], v[114:115]
	v_pk_mul_f32 v[98:99], v[98:99], v[112:113]
	s_waitcnt lgkmcnt(0)
	v_pk_mul_f32 v[104:105], v[104:105], v[110:111]
	v_pk_mul_f32 v[102:103], v[102:103], v[108:109]
	s_waitcnt vmcnt(1)
	v_pk_fma_f32 v[100:101], v[96:97], v[120:121], v[100:101]
	v_pk_fma_f32 v[98:99], v[94:95], v[118:119], v[98:99]
	s_waitcnt vmcnt(0)
	v_pk_fma_f32 v[104:105], v[92:93], v[124:125], v[104:105]
	v_pk_fma_f32 v[102:103], v[90:91], v[122:123], v[102:103]

; __device__ __forceinline__ unsigned cvt_pk(float lo, float hi) { unsigned r; asm volatile("v_cvt_pk_bf16_f32 %0, %1, %2" : "=v"(r) : "v"(lo), "v"(hi)); return r; }
;     __device__ __forceinline__ void operator()(const Acc& acc, const Unit& u, int wr, int wc, int fr, int fq) const {
;     ...
;             for (int m = 0; m < 4; ++m) { const int row = u.pm * 256 + ai * 128 + wr * 64 + m * 16 + fr; const size_t R = (size_t)u.pb * NT + row;
;                 const f32x4 sa = *(const f32x4*)(stats + R * 8 + (ISQ ? 0 : 4));
;                 float rr = rsqrtf(((sa[0] + sa[1]) + (sa[2] + sa[3])) * (ISQ ? (1.f / 256.f) : (1.f / 128.f)) + EPS); if (ISQ) rr *= QSCALE;
; #pragma unroll
;                 for (int bj = 0; bj < 2; ++bj) { const int cg_ = u.pn * 256 + bj * 128 + wc * 32; const int h = cg_ / 192, d0 = cg_ - h * 192;
;                     f32x4 a = acc[ai][bj][m][0], b = acc[ai][bj][m][1];
;                     if (d0 < 128) { a = a * rr; b = b * rr; }
;                     else { if (ISQ) { a = a * rr; b = b * rr; }
;                         f32x4 pa, pb;
; #pragma unroll
;                         for (int i = 0; i < 4; ++i) { pa[i] = __shfl_xor(a[i], 32); pb[i] = __shfl_xor(b[i], 32); }
;                         if (row < TL) { const int ti = row * 32 + ((d0 - 128) >> 5) * 16 + 8 * (fq & 1); const float sg = fq < 2 ? -1.f : 1.f;
;                             const f32x4 c0 = *(const f32x4*)(cosT + ti), c1 = *(const f32x4*)(cosT + ti + 4), s0 = *(const f32x4*)(sinT + ti) * sg, s1 = *(const f32x4*)(sinT + ti + 4) * sg;
;                             a = a * c0 + pa * s0; b = b * c1 + pb * s1; } }
;                     bf16_t* dst = O + ((size_t)(u.pb * 4 + h) * NT + row) * pitch + d0 + 8 * fq;
;                     u32x4 w; w.x = cvt_pk(a[0], a[1]); w.y = cvt_pk(a[2], a[3]); w.z = cvt_pk(b[0], b[1]); w.w = cvt_pk(b[2], b[3]); *(u32x4*)dst = w; } }
.LBB0_1576:
	v_lshl_add_u64 v[82:83], s[54:55], 0, v[106:107]
	v_mov_b64_e32 v[84:85], s[20:21]
	v_mad_u64_u32 v[84:85], s[8:9], v82, s34, v[84:85]
	v_mov_b32_e32 v82, v85
	v_mad_u64_u32 v[82:83], s[8:9], v83, s34, v[82:83]
	v_mov_b32_e32 v85, v82
	v_lshl_add_u64 v[82:83], s[46:47], 1, v[84:85]
	v_lshl_add_u64 v[86:87], v[150:151], 1, v[82:83]
	v_cvt_pk_bf16_f32 v82, v90, v91
	v_add3_u32 v90, s92, v173, 48
	v_cvt_pk_bf16_f32 v83, v92, v93
	v_ashrrev_i32_e32 v91, 31, v90
	v_cvt_pk_bf16_f32 v84, v94, v95
	v_cvt_pk_bf16_f32 v85, v96, v97
	global_store_dwordx4 v[86:87], v[82:85], off
	s_and_b64 vcc, exec, s[4:5]
	v_cmp_gt_i32_e64 s[8:9], s78, v90
	v_lshl_add_u64 v[82:83], s[48:49], 0, v[90:91]
	v_lshlrev_b64 v[82:83], 5, v[82:83]
	v_lshl_add_u64 v[82:83], s[12:13], 0, v[82:83]
	v_mov_b64_e32 v[82:83], v[196:197]
	v_mov_b64_e32 v[84:85], v[198:199]
	s_waitcnt lgkmcnt(2)
	v_lshl_or_b32 v100, v90, 5, v172
	s_mov_b64 s[56:57], -1
	s_waitcnt vmcnt(0)
	v_mov_b32_e32 v86, v83
	v_mov_b32_e32 v87, v84
	v_mov_b32_e32 v83, v85
	v_pk_add_f32 v[82:83], v[86:87], v[82:83]
	s_nop 0
	v_add_f32_e32 v82, v82, v83
	s_waitcnt lgkmcnt(0)
	v_fmamk_f32 v101, v82, 0x3c000000, v169
	v_cmp_gt_f32_e64 s[10:11], s89, v101
	s_cbranch_vccnz .LBB0_1580
	v_and_b32_e32 v83, 64, v171
	v_xor_b32_e32 v82, 32, v171
	v_add_u32_e32 v83, 64, v83
	v_cmp_lt_i32_e32 vcc, v82, v83
	v_mov_b64_e32 v[88:89], v[76:77]
	v_mov_b64_e32 v[86:87], v[74:75]
	v_cndmask_b32_e32 v82, v171, v82, vcc
	v_lshlrev_b32_e32 v82, 2, v82
	ds_bpermute_b32 v96, v82, v78
	ds_bpermute_b32 v92, v82, v74
	ds_bpermute_b32 v97, v82, v79
	ds_bpermute_b32 v93, v82, v75
	ds_bpermute_b32 v98, v82, v80
	ds_bpermute_b32 v94, v82, v76
	ds_bpermute_b32 v99, v82, v81
	ds_bpermute_b32 v95, v82, v77
	v_mov_b64_e32 v[84:85], v[80:81]
	v_mov_b64_e32 v[82:83], v[78:79]
	s_and_saveexec_b64 s[56:57], s[8:9]
	s_cbranch_execz .LBB0_1579
	s_add_i32 s33, s44, 0xffffff80
	s_lshr_b32 s33, s33, 1
	v_add_u32_e32 v82, s33, v100
	v_ashrrev_i32_e32 v83, 31, v82
	v_lshlrev_b64 v[102:103], 2, v[82:83]
	v_lshl_add_u64 v[86:87], s[16:17], 0, v[102:103]
	global_load_dwordx4 v[82:85], v[86:87], off
	s_nop 0
	global_load_dwordx4 v[86:89], v[86:87], off offset:16
	v_lshl_add_u64 v[106:107], s[14:15], 0, v[102:103]
	global_load_dwordx4 v[102:105], v[106:107], off
	s_nop 0
	global_load_dwordx4 v[106:109], v[106:107], off offset:16
	v_mov_b32_e32 v110, v152
	v_mov_b32_e32 v111, v152
	s_waitcnt vmcnt(3)
	v_pk_mul_f32 v[84:85], v[110:111], v[84:85]
	v_pk_mul_f32 v[82:83], v[152:153], v[82:83]
	s_waitcnt vmcnt(2)
	v_pk_mul_f32 v[88:89], v[110:111], v[88:89]
	v_pk_mul_f32 v[86:87], v[152:153], v[86:87]
	s_waitcnt lgkmcnt(1)
	v_pk_mul_f32 v[84:85], v[84:85], v[98:99]
	v_pk_mul_f32 v[82:83], v[82:83], v[96:97]
	s_waitcnt lgkmcnt(0)
	v_pk_mul_f32 v[88:89], v[88:89], v[94:95]
	v_pk_mul_f32 v[86:87], v[86:87], v[92:93]
	s_waitcnt vmcnt(1)
	v_pk_fma_f32 v[84:85], v[80:81], v[104:105], v[84:85]
	v_pk_fma_f32 v[82:83], v[78:79], v[102:103], v[82:83]
	s_waitcnt vmcnt(0)
	v_pk_fma_f32 v[88:89], v[76:77], v[108:109], v[88:89]
	v_pk_fma_f32 v[86:87], v[74:75], v[106:107], v[86:87]

; __device__ __forceinline__ unsigned cvt_pk(float lo, float hi) { unsigned r; asm volatile("v_cvt_pk_bf16_f32 %0, %1, %2" : "=v"(r) : "v"(lo), "v"(hi)); return r; }
;     __device__ __forceinline__ void operator()(const Acc& acc, const Unit& u, int wr, int wc, int fr, int fq) const {
;     ...
;             for (int m = 0; m < 4; ++m) { const int row = u.pm * 256 + ai * 128 + wr * 64 + m * 16 + fr; const size_t R = (size_t)u.pb * NT + row;
;                 const f32x4 sa = *(const f32x4*)(stats + R * 8 + (ISQ ? 0 : 4));
;                 float rr = rsqrtf(((sa[0] + sa[1]) + (sa[2] + sa[3])) * (ISQ ? (1.f / 256.f) : (1.f / 128.f)) + EPS); if (ISQ) rr *= QSCALE;
; #pragma unroll
;                 for (int bj = 0; bj < 2; ++bj) { const int cg_ = u.pn * 256 + bj * 128 + wc * 32; const int h = cg_ / 192, d0 = cg_ - h * 192;
;                     f32x4 a = acc[ai][bj][m][0], b = acc[ai][bj][m][1];
;                     if (d0 < 128) { a = a * rr; b = b * rr; }
;                     else { if (ISQ) { a = a * rr; b = b * rr; }
;                         f32x4 pa, pb;
; #pragma unroll
;                         for (int i = 0; i < 4; ++i) { pa[i] = __shfl_xor(a[i], 32); pb[i] = __shfl_xor(b[i], 32); }
;                         if (row < TL) { const int ti = row * 32 + ((d0 - 128) >> 5) * 16 + 8 * (fq & 1); const float sg = fq < 2 ? -1.f : 1.f;
;                             const f32x4 c0 = *(const f32x4*)(cosT + ti), c1 = *(const f32x4*)(cosT + ti + 4), s0 = *(const f32x4*)(sinT + ti) * sg, s1 = *(const f32x4*)(sinT + ti + 4) * sg;
;                             a = a * c0 + pa * s0; b = b * c1 + pb * s1; } }
;                     bf16_t* dst = O + ((size_t)(u.pb * 4 + h) * NT + row) * pitch + d0 + 8 * fq;
;                     u32x4 w; w.x = cvt_pk(a[0], a[1]); w.y = cvt_pk(a[2], a[3]); w.z = cvt_pk(b[0], b[1]); w.w = cvt_pk(b[2], b[3]); *(u32x4*)dst = w; } }
.LBB0_1588:
	v_lshl_add_u64 v[66:67], s[54:55], 0, v[90:91]
	v_mov_b64_e32 v[68:69], s[20:21]
	v_mad_u64_u32 v[68:69], s[8:9], v66, s34, v[68:69]
	v_mov_b32_e32 v66, v69
	v_mad_u64_u32 v[66:67], s[8:9], v67, s34, v[66:67]
	v_mov_b32_e32 v69, v66
	v_lshl_add_u64 v[66:67], s[46:47], 1, v[68:69]
	v_lshl_add_u64 v[70:71], v[150:151], 1, v[66:67]
	v_cvt_pk_bf16_f32 v66, v74, v75
	v_add_u32_e32 v74, 0x80, v154
	v_cvt_pk_bf16_f32 v67, v76, v77
	v_ashrrev_i32_e32 v75, 31, v74
	v_cvt_pk_bf16_f32 v68, v78, v79
	v_cvt_pk_bf16_f32 v69, v80, v81
	global_store_dwordx4 v[70:71], v[66:69], off
	s_and_b64 vcc, exec, s[4:5]
	v_cmp_gt_i32_e64 s[8:9], s78, v74
	v_lshl_add_u64 v[66:67], s[48:49], 0, v[74:75]
	v_lshlrev_b64 v[66:67], 5, v[66:67]
	v_lshl_add_u64 v[66:67], s[12:13], 0, v[66:67]
	v_mov_b64_e32 v[66:67], v[200:201]
	v_mov_b64_e32 v[68:69], v[202:203]
	s_waitcnt lgkmcnt(2)
	v_lshl_or_b32 v84, v74, 5, v172
	s_mov_b64 s[56:57], -1
	s_waitcnt vmcnt(0)
	v_mov_b32_e32 v70, v67
	v_mov_b32_e32 v71, v68
	v_mov_b32_e32 v67, v69
	v_pk_add_f32 v[66:67], v[70:71], v[66:67]
	s_nop 0
	v_add_f32_e32 v66, v66, v67
	s_waitcnt lgkmcnt(0)
	v_fmamk_f32 v85, v66, 0x3c000000, v169
	v_cmp_gt_f32_e64 s[10:11], s89, v85
	s_cbranch_vccnz .LBB0_1592
	v_and_b32_e32 v67, 64, v171
	v_xor_b32_e32 v66, 32, v171
	v_add_u32_e32 v67, 64, v67
	v_cmp_lt_i32_e32 vcc, v66, v67
	v_mov_b64_e32 v[72:73], v[60:61]
	v_mov_b64_e32 v[70:71], v[58:59]
	v_cndmask_b32_e32 v66, v171, v66, vcc
	v_lshlrev_b32_e32 v66, 2, v66
	ds_bpermute_b32 v80, v66, v62
	ds_bpermute_b32 v76, v66, v58
	ds_bpermute_b32 v81, v66, v63
	ds_bpermute_b32 v77, v66, v59
	ds_bpermute_b32 v82, v66, v64
	ds_bpermute_b32 v78, v66, v60
	ds_bpermute_b32 v83, v66, v65
	ds_bpermute_b32 v79, v66, v61
	v_mov_b64_e32 v[68:69], v[64:65]
	v_mov_b64_e32 v[66:67], v[62:63]
	s_and_saveexec_b64 s[56:57], s[8:9]
	s_cbranch_execz .LBB0_1591
	s_add_i32 s33, s44, 0xffffff80
	s_lshr_b32 s33, s33, 1
	v_add_u32_e32 v66, s33, v84
	v_ashrrev_i32_e32 v67, 31, v66
	v_lshlrev_b64 v[86:87], 2, v[66:67]
	v_lshl_add_u64 v[70:71], s[16:17], 0, v[86:87]
	global_load_dwordx4 v[66:69], v[70:71], off
	s_nop 0
	global_load_dwordx4 v[70:73], v[70:71], off offset:16
	v_lshl_add_u64 v[90:91], s[14:15], 0, v[86:87]
	global_load_dwordx4 v[86:89], v[90:91], off
	s_nop 0
	global_load_dwordx4 v[90:93], v[90:91], off offset:16
	v_mov_b32_e32 v94, v152
	v_mov_b32_e32 v95, v152
	s_waitcnt vmcnt(3)
	v_pk_mul_f32 v[68:69], v[94:95], v[68:69]
	v_pk_mul_f32 v[66:67], v[152:153], v[66:67]
	s_waitcnt vmcnt(2)
	v_pk_mul_f32 v[72:73], v[94:95], v[72:73]
	v_pk_mul_f32 v[70:71], v[152:153], v[70:71]
	s_waitcnt lgkmcnt(1)
	v_pk_mul_f32 v[68:69], v[68:69], v[82:83]
	v_pk_mul_f32 v[66:67], v[66:67], v[80:81]
	s_waitcnt lgkmcnt(0)
	v_pk_mul_f32 v[72:73], v[72:73], v[78:79]
	v_pk_mul_f32 v[70:71], v[70:71], v[76:77]
	s_waitcnt vmcnt(1)
	v_pk_fma_f32 v[68:69], v[64:65], v[88:89], v[68:69]
	v_pk_fma_f32 v[66:67], v[62:63], v[86:87], v[66:67]
	s_waitcnt vmcnt(0)
	v_pk_fma_f32 v[72:73], v[60:61], v[92:93], v[72:73]
	v_pk_fma_f32 v[70:71], v[58:59], v[90:91], v[70:71]

; __device__ __forceinline__ unsigned cvt_pk(float lo, float hi) { unsigned r; asm volatile("v_cvt_pk_bf16_f32 %0, %1, %2" : "=v"(r) : "v"(lo), "v"(hi)); return r; }
;     __device__ __forceinline__ void operator()(const Acc& acc, const Unit& u, int wr, int wc, int fr, int fq) const {
;     ...
;             for (int m = 0; m < 4; ++m) { const int row = u.pm * 256 + ai * 128 + wr * 64 + m * 16 + fr; const size_t R = (size_t)u.pb * NT + row;
;                 const f32x4 sa = *(const f32x4*)(stats + R * 8 + (ISQ ? 0 : 4));
;                 float rr = rsqrtf(((sa[0] + sa[1]) + (sa[2] + sa[3])) * (ISQ ? (1.f / 256.f) : (1.f / 128.f)) + EPS); if (ISQ) rr *= QSCALE;
; #pragma unroll
;                 for (int bj = 0; bj < 2; ++bj) { const int cg_ = u.pn * 256 + bj * 128 + wc * 32; const int h = cg_ / 192, d0 = cg_ - h * 192;
;                     f32x4 a = acc[ai][bj][m][0], b = acc[ai][bj][m][1];
;                     if (d0 < 128) { a = a * rr; b = b * rr; }
;                     else { if (ISQ) { a = a * rr; b = b * rr; }
;                         f32x4 pa, pb;
; #pragma unroll
;                         for (int i = 0; i < 4; ++i) { pa[i] = __shfl_xor(a[i], 32); pb[i] = __shfl_xor(b[i], 32); }
;                         if (row < TL) { const int ti = row * 32 + ((d0 - 128) >> 5) * 16 + 8 * (fq & 1); const float sg = fq < 2 ? -1.f : 1.f;
;                             const f32x4 c0 = *(const f32x4*)(cosT + ti), c1 = *(const f32x4*)(cosT + ti + 4), s0 = *(const f32x4*)(sinT + ti) * sg, s1 = *(const f32x4*)(sinT + ti + 4) * sg;
;                             a = a * c0 + pa * s0; b = b * c1 + pb * s1; } }
;                     bf16_t* dst = O + ((size_t)(u.pb * 4 + h) * NT + row) * pitch + d0 + 8 * fq;
;                     u32x4 w; w.x = cvt_pk(a[0], a[1]); w.y = cvt_pk(a[2], a[3]); w.z = cvt_pk(b[0], b[1]); w.w = cvt_pk(b[2], b[3]); *(u32x4*)dst = w; } }
.LBB0_1600:
	v_lshl_add_u64 v[50:51], s[54:55], 0, v[74:75]
	v_mov_b64_e32 v[52:53], s[20:21]
	v_mad_u64_u32 v[52:53], s[8:9], v50, s34, v[52:53]
	v_mov_b32_e32 v50, v53
	v_mad_u64_u32 v[50:51], s[8:9], v51, s34, v[50:51]
	v_mov_b32_e32 v53, v50
	v_lshl_add_u64 v[50:51], s[46:47], 1, v[52:53]
	v_lshl_add_u64 v[54:55], v[150:151], 1, v[50:51]
	v_cvt_pk_bf16_f32 v50, v58, v59
	v_add_u32_e32 v58, 0x90, v154
	v_cvt_pk_bf16_f32 v51, v60, v61
	v_ashrrev_i32_e32 v59, 31, v58
	v_cvt_pk_bf16_f32 v52, v62, v63
	v_cvt_pk_bf16_f32 v53, v64, v65
	global_store_dwordx4 v[54:55], v[50:53], off
	s_and_b64 vcc, exec, s[4:5]
	v_cmp_gt_i32_e64 s[8:9], s78, v58
	v_lshl_add_u64 v[50:51], s[48:49], 0, v[58:59]
	v_lshlrev_b64 v[50:51], 5, v[50:51]
	v_lshl_add_u64 v[50:51], s[12:13], 0, v[50:51]
	v_mov_b64_e32 v[50:51], v[204:205]
	v_mov_b64_e32 v[52:53], v[206:207]
	s_waitcnt lgkmcnt(2)
	v_lshl_or_b32 v68, v58, 5, v172
	s_mov_b64 s[56:57], -1
	s_waitcnt vmcnt(0)
	v_mov_b32_e32 v54, v51
	v_mov_b32_e32 v55, v52
	v_mov_b32_e32 v51, v53
	v_pk_add_f32 v[50:51], v[54:55], v[50:51]
	s_nop 0
	v_add_f32_e32 v50, v50, v51
	s_waitcnt lgkmcnt(0)
	v_fmamk_f32 v69, v50, 0x3c000000, v169
	v_cmp_gt_f32_e64 s[10:11], s89, v69
	s_cbranch_vccnz .LBB0_1604
	v_and_b32_e32 v51, 64, v171
	v_xor_b32_e32 v50, 32, v171
	v_add_u32_e32 v51, 64, v51
	v_cmp_lt_i32_e32 vcc, v50, v51
	v_mov_b64_e32 v[56:57], v[44:45]
	v_mov_b64_e32 v[54:55], v[42:43]
	v_cndmask_b32_e32 v50, v171, v50, vcc
	v_lshlrev_b32_e32 v50, 2, v50
	ds_bpermute_b32 v64, v50, v46
	ds_bpermute_b32 v60, v50, v42
	ds_bpermute_b32 v65, v50, v47
	ds_bpermute_b32 v61, v50, v43
	ds_bpermute_b32 v66, v50, v48
	ds_bpermute_b32 v62, v50, v44
	ds_bpermute_b32 v67, v50, v49
	ds_bpermute_b32 v63, v50, v45
	v_mov_b64_e32 v[52:53], v[48:49]
	v_mov_b64_e32 v[50:51], v[46:47]
	s_and_saveexec_b64 s[56:57], s[8:9]
	s_cbranch_execz .LBB0_1603
	s_add_i32 s33, s44, 0xffffff80
	s_lshr_b32 s33, s33, 1
	v_add_u32_e32 v50, s33, v68
	v_ashrrev_i32_e32 v51, 31, v50
	v_lshlrev_b64 v[70:71], 2, v[50:51]
	v_lshl_add_u64 v[54:55], s[16:17], 0, v[70:71]
	global_load_dwordx4 v[50:53], v[54:55], off
	s_nop 0
	global_load_dwordx4 v[54:57], v[54:55], off offset:16
	v_lshl_add_u64 v[74:75], s[14:15], 0, v[70:71]
	global_load_dwordx4 v[70:73], v[74:75], off
	s_nop 0
	global_load_dwordx4 v[74:77], v[74:75], off offset:16
	v_mov_b32_e32 v78, v152
	v_mov_b32_e32 v79, v152
	s_waitcnt vmcnt(3)
	v_pk_mul_f32 v[52:53], v[78:79], v[52:53]
	v_pk_mul_f32 v[50:51], v[152:153], v[50:51]
	s_waitcnt vmcnt(2)
	v_pk_mul_f32 v[56:57], v[78:79], v[56:57]
	v_pk_mul_f32 v[54:55], v[152:153], v[54:55]
	s_waitcnt lgkmcnt(1)
	v_pk_mul_f32 v[52:53], v[52:53], v[66:67]
	v_pk_mul_f32 v[50:51], v[50:51], v[64:65]
	s_waitcnt lgkmcnt(0)
	v_pk_mul_f32 v[56:57], v[56:57], v[62:63]
	v_pk_mul_f32 v[54:55], v[54:55], v[60:61]
	s_waitcnt vmcnt(1)
	v_pk_fma_f32 v[52:53], v[48:49], v[72:73], v[52:53]
	v_pk_fma_f32 v[50:51], v[46:47], v[70:71], v[50:51]
	s_waitcnt vmcnt(0)
	v_pk_fma_f32 v[56:57], v[44:45], v[76:77], v[56:57]
	v_pk_fma_f32 v[54:55], v[42:43], v[74:75], v[54:55]

; __device__ __forceinline__ unsigned cvt_pk(float lo, float hi) { unsigned r; asm volatile("v_cvt_pk_bf16_f32 %0, %1, %2" : "=v"(r) : "v"(lo), "v"(hi)); return r; }
;     __device__ __forceinline__ void operator()(const Acc& acc, const Unit& u, int wr, int wc, int fr, int fq) const {
;     ...
;             for (int m = 0; m < 4; ++m) { const int row = u.pm * 256 + ai * 128 + wr * 64 + m * 16 + fr; const size_t R = (size_t)u.pb * NT + row;
;                 const f32x4 sa = *(const f32x4*)(stats + R * 8 + (ISQ ? 0 : 4));
;                 float rr = rsqrtf(((sa[0] + sa[1]) + (sa[2] + sa[3])) * (ISQ ? (1.f / 256.f) : (1.f / 128.f)) + EPS); if (ISQ) rr *= QSCALE;
; #pragma unroll
;                 for (int bj = 0; bj < 2; ++bj) { const int cg_ = u.pn * 256 + bj * 128 + wc * 32; const int h = cg_ / 192, d0 = cg_ - h * 192;
;                     f32x4 a = acc[ai][bj][m][0], b = acc[ai][bj][m][1];
;                     if (d0 < 128) { a = a * rr; b = b * rr; }
;                     else { if (ISQ) { a = a * rr; b = b * rr; }
;                         f32x4 pa, pb;
; #pragma unroll
;                         for (int i = 0; i < 4; ++i) { pa[i] = __shfl_xor(a[i], 32); pb[i] = __shfl_xor(b[i], 32); }
;                         if (row < TL) { const int ti = row * 32 + ((d0 - 128) >> 5) * 16 + 8 * (fq & 1); const float sg = fq < 2 ? -1.f : 1.f;
;                             const f32x4 c0 = *(const f32x4*)(cosT + ti), c1 = *(const f32x4*)(cosT + ti + 4), s0 = *(const f32x4*)(sinT + ti) * sg, s1 = *(const f32x4*)(sinT + ti + 4) * sg;
;                             a = a * c0 + pa * s0; b = b * c1 + pb * s1; } }
;                     bf16_t* dst = O + ((size_t)(u.pb * 4 + h) * NT + row) * pitch + d0 + 8 * fq;
;                     u32x4 w; w.x = cvt_pk(a[0], a[1]); w.y = cvt_pk(a[2], a[3]); w.z = cvt_pk(b[0], b[1]); w.w = cvt_pk(b[2], b[3]); *(u32x4*)dst = w; } }
.LBB0_1612:
	v_lshl_add_u64 v[34:35], s[54:55], 0, v[58:59]
	v_mov_b64_e32 v[36:37], s[20:21]
	v_mad_u64_u32 v[36:37], s[8:9], v34, s34, v[36:37]
	v_mov_b32_e32 v34, v37
	v_mad_u64_u32 v[34:35], s[8:9], v35, s34, v[34:35]
	v_mov_b32_e32 v37, v34
	v_lshl_add_u64 v[34:35], s[46:47], 1, v[36:37]
	v_lshl_add_u64 v[38:39], v[150:151], 1, v[34:35]
	v_cvt_pk_bf16_f32 v34, v42, v43
	v_add_u32_e32 v42, 0xa0, v154
	v_cvt_pk_bf16_f32 v35, v44, v45
	v_ashrrev_i32_e32 v43, 31, v42
	v_cvt_pk_bf16_f32 v36, v46, v47
	v_cvt_pk_bf16_f32 v37, v48, v49
	global_store_dwordx4 v[38:39], v[34:37], off
	s_and_b64 vcc, exec, s[4:5]
	v_cmp_gt_i32_e64 s[8:9], s78, v42
	v_lshl_add_u64 v[34:35], s[48:49], 0, v[42:43]
	v_lshlrev_b64 v[34:35], 5, v[34:35]
	v_lshl_add_u64 v[34:35], s[12:13], 0, v[34:35]
	v_mov_b64_e32 v[34:35], v[208:209]
	v_mov_b64_e32 v[36:37], v[210:211]
	s_waitcnt lgkmcnt(2)
	v_lshl_or_b32 v52, v42, 5, v172
	s_mov_b64 s[56:57], -1
	s_waitcnt vmcnt(0)
	v_mov_b32_e32 v38, v35
	v_mov_b32_e32 v39, v36
	v_mov_b32_e32 v35, v37
	v_pk_add_f32 v[34:35], v[38:39], v[34:35]
	s_nop 0
	v_add_f32_e32 v34, v34, v35
	s_waitcnt lgkmcnt(0)
	v_fmamk_f32 v53, v34, 0x3c000000, v169
	v_cmp_gt_f32_e64 s[10:11], s89, v53
	s_cbranch_vccnz .LBB0_1616
	v_and_b32_e32 v35, 64, v171
	v_xor_b32_e32 v34, 32, v171
	v_add_u32_e32 v35, 64, v35
	v_cmp_lt_i32_e32 vcc, v34, v35
	v_mov_b64_e32 v[40:41], v[28:29]
	v_mov_b64_e32 v[38:39], v[26:27]
	v_cndmask_b32_e32 v34, v171, v34, vcc
	v_lshlrev_b32_e32 v34, 2, v34
	ds_bpermute_b32 v48, v34, v30
	ds_bpermute_b32 v44, v34, v26
	ds_bpermute_b32 v49, v34, v31
	ds_bpermute_b32 v45, v34, v27
	ds_bpermute_b32 v50, v34, v32
	ds_bpermute_b32 v46, v34, v28
	ds_bpermute_b32 v51, v34, v33
	ds_bpermute_b32 v47, v34, v29
	v_mov_b64_e32 v[36:37], v[32:33]
	v_mov_b64_e32 v[34:35], v[30:31]
	s_and_saveexec_b64 s[56:57], s[8:9]
	s_cbranch_execz .LBB0_1615
	s_add_i32 s33, s44, 0xffffff80
	s_lshr_b32 s33, s33, 1
	v_add_u32_e32 v34, s33, v52
	v_ashrrev_i32_e32 v35, 31, v34
	v_lshlrev_b64 v[54:55], 2, v[34:35]
	v_lshl_add_u64 v[38:39], s[16:17], 0, v[54:55]
	global_load_dwordx4 v[34:37], v[38:39], off
	s_nop 0
	global_load_dwordx4 v[38:41], v[38:39], off offset:16
	v_lshl_add_u64 v[58:59], s[14:15], 0, v[54:55]
	global_load_dwordx4 v[54:57], v[58:59], off
	s_nop 0
	global_load_dwordx4 v[58:61], v[58:59], off offset:16
	v_mov_b32_e32 v62, v152
	v_mov_b32_e32 v63, v152
	s_waitcnt vmcnt(3)
	v_pk_mul_f32 v[36:37], v[62:63], v[36:37]
	v_pk_mul_f32 v[34:35], v[152:153], v[34:35]
	s_waitcnt vmcnt(2)
	v_pk_mul_f32 v[40:41], v[62:63], v[40:41]
	v_pk_mul_f32 v[38:39], v[152:153], v[38:39]
	s_waitcnt lgkmcnt(1)
	v_pk_mul_f32 v[36:37], v[36:37], v[50:51]
	v_pk_mul_f32 v[34:35], v[34:35], v[48:49]
	s_waitcnt lgkmcnt(0)
	v_pk_mul_f32 v[40:41], v[40:41], v[46:47]
	v_pk_mul_f32 v[38:39], v[38:39], v[44:45]
	s_waitcnt vmcnt(1)
	v_pk_fma_f32 v[36:37], v[32:33], v[56:57], v[36:37]
	v_pk_fma_f32 v[34:35], v[30:31], v[54:55], v[34:35]
	s_waitcnt vmcnt(0)
	v_pk_fma_f32 v[40:41], v[28:29], v[60:61], v[40:41]
	v_pk_fma_f32 v[38:39], v[26:27], v[58:59], v[38:39]

; __device__ __forceinline__ unsigned cvt_pk(float lo, float hi) { unsigned r; asm volatile("v_cvt_pk_bf16_f32 %0, %1, %2" : "=v"(r) : "v"(lo), "v"(hi)); return r; }
;     __device__ __forceinline__ void operator()(const Acc& acc, const Unit& u, int wr, int wc, int fr, int fq) const {
;     ...
;             for (int m = 0; m < 4; ++m) { const int row = u.pm * 256 + ai * 128 + wr * 64 + m * 16 + fr; const size_t R = (size_t)u.pb * NT + row;
;                 const f32x4 sa = *(const f32x4*)(stats + R * 8 + (ISQ ? 0 : 4));
;                 float rr = rsqrtf(((sa[0] + sa[1]) + (sa[2] + sa[3])) * (ISQ ? (1.f / 256.f) : (1.f / 128.f)) + EPS); if (ISQ) rr *= QSCALE;
; #pragma unroll
;                 for (int bj = 0; bj < 2; ++bj) { const int cg_ = u.pn * 256 + bj * 128 + wc * 32; const int h = cg_ / 192, d0 = cg_ - h * 192;
;                     f32x4 a = acc[ai][bj][m][0], b = acc[ai][bj][m][1];
;                     if (d0 < 128) { a = a * rr; b = b * rr; }
;                     else { if (ISQ) { a = a * rr; b = b * rr; }
;                         f32x4 pa, pb;
; #pragma unroll
;                         for (int i = 0; i < 4; ++i) { pa[i] = __shfl_xor(a[i], 32); pb[i] = __shfl_xor(b[i], 32); }
;                         if (row < TL) { const int ti = row * 32 + ((d0 - 128) >> 5) * 16 + 8 * (fq & 1); const float sg = fq < 2 ? -1.f : 1.f;
;                             const f32x4 c0 = *(const f32x4*)(cosT + ti), c1 = *(const f32x4*)(cosT + ti + 4), s0 = *(const f32x4*)(sinT + ti) * sg, s1 = *(const f32x4*)(sinT + ti + 4) * sg;
;                             a = a * c0 + pa * s0; b = b * c1 + pb * s1; } }
;                     bf16_t* dst = O + ((size_t)(u.pb * 4 + h) * NT + row) * pitch + d0 + 8 * fq;
;                     u32x4 w; w.x = cvt_pk(a[0], a[1]); w.y = cvt_pk(a[2], a[3]); w.z = cvt_pk(b[0], b[1]); w.w = cvt_pk(b[2], b[3]); *(u32x4*)dst = w; } }
.LBB0_1624:
	v_lshl_add_u64 v[18:19], s[54:55], 0, v[42:43]
	v_mov_b64_e32 v[20:21], s[20:21]
	v_mad_u64_u32 v[20:21], s[8:9], v18, s34, v[20:21]
	v_mov_b32_e32 v18, v21
	v_mad_u64_u32 v[18:19], s[8:9], v19, s34, v[18:19]
	v_mov_b32_e32 v21, v18
	v_lshl_add_u64 v[18:19], s[46:47], 1, v[20:21]
	v_lshl_add_u64 v[22:23], v[150:151], 1, v[18:19]
	v_cvt_pk_bf16_f32 v18, v26, v27
	v_add_u32_e32 v26, 0xb0, v154
	v_cvt_pk_bf16_f32 v19, v28, v29
	v_ashrrev_i32_e32 v27, 31, v26
	v_cvt_pk_bf16_f32 v20, v30, v31
	v_cvt_pk_bf16_f32 v21, v32, v33
	global_store_dwordx4 v[22:23], v[18:21], off
	s_and_b64 vcc, exec, s[4:5]
	v_cmp_gt_i32_e64 s[4:5], s78, v26
	v_lshl_add_u64 v[18:19], s[48:49], 0, v[26:27]
	v_lshlrev_b64 v[18:19], 5, v[18:19]
	v_lshl_add_u64 v[18:19], s[12:13], 0, v[18:19]
	v_mov_b64_e32 v[18:19], v[212:213]
	v_mov_b64_e32 v[20:21], v[214:215]
	s_waitcnt lgkmcnt(2)
	v_lshl_or_b32 v36, v26, 5, v172
	s_mov_b64 s[10:11], -1
	s_waitcnt vmcnt(0)
	v_mov_b32_e32 v22, v19
	v_mov_b32_e32 v23, v20
	v_mov_b32_e32 v19, v21
	v_pk_add_f32 v[18:19], v[22:23], v[18:19]
	s_nop 0
	v_add_f32_e32 v18, v18, v19
	s_waitcnt lgkmcnt(0)
	v_fmamk_f32 v37, v18, 0x3c000000, v169
	v_cmp_gt_f32_e64 s[8:9], s89, v37
	s_cbranch_vccnz .LBB0_1628
	v_and_b32_e32 v19, 64, v171
	v_xor_b32_e32 v18, 32, v171
	v_add_u32_e32 v19, 64, v19
	v_cmp_lt_i32_e32 vcc, v18, v19
	v_mov_b64_e32 v[24:25], v[12:13]
	v_mov_b64_e32 v[22:23], v[10:11]
	v_cndmask_b32_e32 v18, v171, v18, vcc
	v_lshlrev_b32_e32 v18, 2, v18
	ds_bpermute_b32 v32, v18, v14
	ds_bpermute_b32 v28, v18, v10
	ds_bpermute_b32 v33, v18, v15
	ds_bpermute_b32 v29, v18, v11
	ds_bpermute_b32 v34, v18, v16
	ds_bpermute_b32 v30, v18, v12
	ds_bpermute_b32 v35, v18, v17
	ds_bpermute_b32 v31, v18, v13
	v_mov_b64_e32 v[20:21], v[16:17]
	v_mov_b64_e32 v[18:19], v[14:15]
	s_and_saveexec_b64 s[10:11], s[4:5]
	s_cbranch_execz .LBB0_1627
	s_add_i32 s33, s44, 0xffffff80
	s_lshr_b32 s33, s33, 1
	v_add_u32_e32 v18, s33, v36
	v_ashrrev_i32_e32 v19, 31, v18
	v_lshlrev_b64 v[38:39], 2, v[18:19]
	v_lshl_add_u64 v[22:23], s[16:17], 0, v[38:39]
	global_load_dwordx4 v[18:21], v[22:23], off
	s_nop 0
	global_load_dwordx4 v[22:25], v[22:23], off offset:16
	v_lshl_add_u64 v[42:43], s[14:15], 0, v[38:39]
	global_load_dwordx4 v[38:41], v[42:43], off
	s_nop 0
	global_load_dwordx4 v[42:45], v[42:43], off offset:16
	v_mov_b32_e32 v46, v152
	v_mov_b32_e32 v47, v152
	s_waitcnt vmcnt(3)
	v_pk_mul_f32 v[20:21], v[46:47], v[20:21]
	v_pk_mul_f32 v[18:19], v[152:153], v[18:19]
	s_waitcnt vmcnt(2)
	v_pk_mul_f32 v[24:25], v[46:47], v[24:25]
	v_pk_mul_f32 v[22:23], v[152:153], v[22:23]
	s_waitcnt lgkmcnt(1)
	v_pk_mul_f32 v[20:21], v[20:21], v[34:35]
	v_pk_mul_f32 v[18:19], v[18:19], v[32:33]
	s_waitcnt lgkmcnt(0)
	v_pk_mul_f32 v[24:25], v[24:25], v[30:31]
	v_pk_mul_f32 v[22:23], v[22:23], v[28:29]
	s_waitcnt vmcnt(1)
	v_pk_fma_f32 v[20:21], v[16:17], v[40:41], v[20:21]
	v_pk_fma_f32 v[18:19], v[14:15], v[38:39], v[18:19]
	s_waitcnt vmcnt(0)
	v_pk_fma_f32 v[24:25], v[12:13], v[44:45], v[24:25]
	v_pk_fma_f32 v[22:23], v[10:11], v[42:43], v[22:23]

; #define LAS __attribute__((address_space(3)))
; __device__ __forceinline__ void attn_unit(LAS unsigned char* lds, int b, int h, int q0, int kbeg, int ntiles, const bf16_t* Q, const bf16_t* K, const bf16_t* Vt, bf16_t* cat) {
;     ...
;     f32x16 o[4];
; #pragma unroll
;     for (int d = 0; d < 4; ++d)
; #pragma unroll
;         for (int r = 0; r < 16; ++r) o[d][r] = 0.f;
;     float mrun = -1e30f, lrun = 0.f;
;     ...
;     asm volatile("s_waitcnt vmcnt(0)" ::: "memory");
;     __syncthreads();
;     f32x16 pc0, pc1;
;     { const LAS unsigned char* kb = lds + r32 * (KP * 2) + hi * 16;
; #pragma unroll
;       for (int r = 0; r < 16; ++r) { pc0[r] = 0.f; pc1[r] = 0.f; }
; #pragma unroll
;       for (int ds = 0; ds < 12; ++ds) {
;           const bf16x8 k0 = *(const LAS bf16x8*)(kb + ds * 32), k1 = *(const LAS bf16x8*)(kb + 32 * (KP * 2) + ds * 32);
;           pc0 = __builtin_amdgcn_mfma_f32_32x32x16_bf16(k0, qf[ds], pc0, 0, 0, 0);
;           pc1 = __builtin_amdgcn_mfma_f32_32x32x16_bf16(k1, qf[ds], pc1, 0, 0, 0); } }
;     float mxc;
;     { float mx = fmaxf(pc0[0], pc1[0]);
; #pragma unroll
;       for (int r = 1; r < 16; ++r) mx = fmaxf(mx, fmaxf(pc0[r], pc1[r]));
;       mxc = fmaxf(mx, __shfl_xor(mx, 32)); }
;     __syncthreads();
.LBB0_1839:
	v_mad_u32_u24 v22, v19, s59, 0
	v_lshl_add_u32 v229, v4, 4, v22
	s_waitcnt lgkmcnt(0)
	s_waitcnt lgkmcnt(0)
	s_barrier
	ds_read_b128 v[6:9], v229
	ds_read_b128 v[10:13], v229 offset:32
	s_waitcnt lgkmcnt(1)
	v_mfma_f32_32x32x16_bf16 v[82:97], v[6:9], v[174:177], 0
	ds_read_b128 v[6:9], v229 offset:12800
	ds_read_b128 v[14:17], v229 offset:12832
	v_lshlrev_b32_e32 v208, 3, v4
	v_mad_i64_i32 v[20:21], s[4:5], v5, s56, 0
	s_mov_b32 s4, 0
	s_lshr_b32 s6, s48, 3
	s_mov_b32 s5, s4
	s_waitcnt lgkmcnt(2)
	v_mfma_f32_32x32x16_bf16 v[82:97], v[10:13], v[170:173], v[82:97]
	s_and_b32 s33, s6, 3
	s_mov_b32 s6, s4
	s_mov_b32 s7, s4
	s_mov_b32 s8, s4
	s_mov_b32 s9, s4
	s_mov_b32 s10, s4
	s_mov_b32 s11, s4
	s_waitcnt lgkmcnt(1)
	v_mfma_f32_32x32x16_bf16 v[66:81], v[6:9], v[174:177], 0
	ds_read_b128 v[6:9], v229 offset:64
	ds_read_b128 v[10:13], v229 offset:96
	s_mov_b32 s12, s4
	s_mov_b32 s13, s4
	s_mov_b32 s14, s4
	s_mov_b32 s15, s4
	s_mov_b32 s16, s4
	s_mov_b32 s17, s4
	s_waitcnt lgkmcnt(1)
	v_mfma_f32_32x32x16_bf16 v[82:97], v[6:9], v[166:169], v[82:97]
	s_mov_b32 s18, s4
	s_mov_b32 s19, s4
	v_mul_i32_i24_e32 v19, 0xfffffef8, v19
	v_and_b32_e32 v18, 7, v18
	v_add3_u32 v230, v22, v19, v208
	v_mov_b32_e32 v231, 0xf149f2ca
	v_mfma_f32_32x32x16_bf16 v[66:81], v[14:17], v[170:173], v[66:81]
	ds_read_b128 v[6:9], v229 offset:12864
	ds_read_b128 v[14:17], v229 offset:12896
	s_waitcnt lgkmcnt(2)
	v_mfma_f32_32x32x16_bf16 v[82:97], v[10:13], v[162:165], v[82:97]
	s_waitcnt lgkmcnt(1)
	v_mfma_f32_32x32x16_bf16 v[66:81], v[6:9], v[166:169], v[66:81]
	ds_read_b128 v[6:9], v229 offset:128
	ds_read_b128 v[10:13], v229 offset:160
	s_waitcnt lgkmcnt(1)
	v_mfma_f32_32x32x16_bf16 v[82:97], v[6:9], v[158:161], v[82:97]
	v_mfma_f32_32x32x16_bf16 v[66:81], v[14:17], v[162:165], v[66:81]
	ds_read_b128 v[6:9], v229 offset:12928
	ds_read_b128 v[14:17], v229 offset:12960
	s_waitcnt lgkmcnt(2)
	v_mfma_f32_32x32x16_bf16 v[82:97], v[10:13], v[154:157], v[82:97]
	s_waitcnt lgkmcnt(1)
	v_mfma_f32_32x32x16_bf16 v[66:81], v[6:9], v[158:161], v[66:81]
	ds_read_b128 v[6:9], v229 offset:192
	ds_read_b128 v[10:13], v229 offset:224
	s_waitcnt lgkmcnt(1)
	v_mfma_f32_32x32x16_bf16 v[82:97], v[6:9], v[150:153], v[82:97]
	v_mfma_f32_32x32x16_bf16 v[66:81], v[14:17], v[154:157], v[66:81]
	ds_read_b128 v[6:9], v229 offset:12992
	ds_read_b128 v[14:17], v229 offset:13024
	s_waitcnt lgkmcnt(2)
	v_mfma_f32_32x32x16_bf16 v[82:97], v[10:13], v[146:149], v[82:97]
	s_waitcnt lgkmcnt(1)
	v_mfma_f32_32x32x16_bf16 v[66:81], v[6:9], v[150:153], v[66:81]
	ds_read_b128 v[6:9], v229 offset:256
	ds_read_b128 v[10:13], v229 offset:288
	s_waitcnt lgkmcnt(1)
	v_mfma_f32_32x32x16_bf16 v[82:97], v[6:9], v[142:145], v[82:97]
	v_mfma_f32_32x32x16_bf16 v[66:81], v[14:17], v[146:149], v[66:81]
	ds_read_b128 v[6:9], v229 offset:13056
	ds_read_b128 v[14:17], v229 offset:13088
	s_waitcnt lgkmcnt(2)
	v_mfma_f32_32x32x16_bf16 v[82:97], v[10:13], v[138:141], v[82:97]
	s_waitcnt lgkmcnt(1)
	v_mfma_f32_32x32x16_bf16 v[66:81], v[6:9], v[142:145], v[66:81]
	ds_read_b128 v[6:9], v229 offset:320
	ds_read_b128 v[10:13], v229 offset:352
	ds_read_b128 v[2:5], v229 offset:13152
	s_waitcnt lgkmcnt(2)
	v_mfma_f32_32x32x16_bf16 v[82:97], v[6:9], v[134:137], v[82:97]
	ds_read_b128 v[6:9], v229 offset:13120
	s_waitcnt vmcnt(0) lgkmcnt(0)
	s_barrier
	v_mfma_f32_32x32x16_bf16 v[66:81], v[14:17], v[138:141], v[66:81]
	v_mfma_f32_32x32x16_bf16 v[66:81], v[6:9], v[134:137], v[66:81]
	v_mfma_f32_32x32x16_bf16 v[66:81], v[2:5], v[130:133], v[66:81]
	v_mfma_f32_32x32x16_bf16 v[82:97], v[10:13], v[130:133], v[82:97]
	s_nop 10
	v_max_f32_e32 v2, v67, v67
	v_max_f32_e32 v3, v83, v83
	v_max_f32_e32 v2, v3, v2
	v_max_f32_e32 v3, v68, v68
	v_max_f32_e32 v4, v84, v84
	v_max_f32_e32 v3, v4, v3
	v_max_f32_e32 v4, v69, v69
	v_max_f32_e32 v5, v85, v85
	v_max3_f32 v2, v82, v66, v2
	v_max_f32_e32 v4, v5, v4
	v_max3_f32 v2, v2, v3, v4
	v_max_f32_e32 v3, v70, v70
	v_max_f32_e32 v4, v86, v86
	v_max_f32_e32 v3, v4, v3
	v_max_f32_e32 v4, v71, v71
	v_max_f32_e32 v5, v87, v87
	v_max_f32_e32 v4, v5, v4
	v_max3_f32 v2, v2, v3, v4
	v_max_f32_e32 v3, v72, v72
	v_max_f32_e32 v4, v88, v88
	v_max_f32_e32 v3, v4, v3
	v_max_f32_e32 v4, v73, v73
	v_max_f32_e32 v5, v89, v89
	v_max_f32_e32 v4, v5, v4
	v_max3_f32 v2, v2, v3, v4
	v_max_f32_e32 v3, v74, v74
	v_max_f32_e32 v4, v90, v90
	v_max_f32_e32 v3, v4, v3
	v_max_f32_e32 v4, v75, v75
	v_max_f32_e32 v5, v91, v91
	v_max_f32_e32 v4, v5, v4
	v_max3_f32 v2, v2, v3, v4
	v_max_f32_e32 v3, v76, v76
	v_max_f32_e32 v4, v92, v92
	v_max_f32_e32 v3, v4, v3
	v_max_f32_e32 v4, v77, v77
	v_max_f32_e32 v5, v93, v93
	v_max_f32_e32 v4, v5, v4
	v_max3_f32 v2, v2, v3, v4
	v_max_f32_e32 v3, v78, v78
	v_max_f32_e32 v4, v94, v94
	v_max_f32_e32 v3, v4, v3
	v_max_f32_e32 v4, v79, v79
	v_max_f32_e32 v5, v95, v95
	v_max_f32_e32 v4, v5, v4
	v_max3_f32 v2, v2, v3, v4
	v_max_f32_e32 v3, v80, v80
	v_max_f32_e32 v4, v96, v96
	v_max_f32_e32 v3, v4, v3
	v_max_f32_e32 v4, v81, v81
	v_max_f32_e32 v5, v97, v97
	v_max_f32_e32 v4, v5, v4
	v_max3_f32 v23, v2, v3, v4
	v_and_b32_e32 v3, 64, v226
	v_xor_b32_e32 v2, 32, v226
	v_add_u32_e32 v3, 64, v3
	v_cmp_lt_i32_e32 vcc, v2, v3
	s_nop 1
	v_cndmask_b32_e32 v2, v226, v2, vcc
	v_lshlrev_b32_e32 v209, 2, v2
	v_mov_b64_e32 v[2:3], s[4:5]
	ds_bpermute_b32 v24, v209, v23
	v_mov_b64_e32 v[4:5], s[6:7]
	v_mov_b64_e32 v[6:7], s[8:9]
	v_mov_b64_e32 v[8:9], s[10:11]
	v_mov_b64_e32 v[10:11], s[12:13]
	v_mov_b64_e32 v[12:13], s[14:15]
	v_mov_b64_e32 v[14:15], s[16:17]
	v_mov_b64_e32 v[16:17], s[18:19]
	s_add_i32 s5, s61, s33
	s_mul_i32 s7, s5, 0xe1000
	s_mul_hi_i32 s6, s5, 0xe1000
	s_add_u32 s8, s7, 0xfcb8800
	s_addc_u32 s9, s6, 0
	s_add_u32 s7, s7, 0xfcbe800
	s_waitcnt lgkmcnt(0)
	v_max_f32_e32 v24, v24, v24
	s_addc_u32 s6, s6, 0
	v_max_f32_e32 v98, v23, v24
	v_mov_b32_e32 v23, s9
	v_or_b32_e32 v22, s8, v202
	v_mov_b32_e32 v221, s6
	v_or_b32_e32 v220, s7, v202
	v_mad_i64_i32 v[20:21], s[6:7], s5, v227, v[20:21]
	v_lshlrev_b32_e32 v202, 4, v18
	v_lshl_add_u64 v[214:215], v[22:23], 0, s[42:43]
	v_lshl_add_u64 v[216:217], v[22:23], 0, s[44:45]
	v_lshl_add_u64 v[218:219], v[22:23], 0, s[46:47]
	v_lshl_add_u64 v[222:223], v[20:21], 0, v[202:203]
	v_mov_b64_e32 v[32:33], v[16:17]
	v_mov_b64_e32 v[48:49], v[16:17]
	v_mov_b64_e32 v[64:65], v[16:17]
	v_mov_b32_e32 v202, 0
	v_mov_b64_e32 v[30:31], v[14:15]
	v_mov_b64_e32 v[28:29], v[12:13]
	v_mov_b64_e32 v[26:27], v[10:11]
	v_mov_b64_e32 v[24:25], v[8:9]
	v_mov_b64_e32 v[22:23], v[6:7]
	v_mov_b64_e32 v[20:21], v[4:5]
	v_mov_b64_e32 v[18:19], v[2:3]
	v_mov_b64_e32 v[46:47], v[14:15]
	v_mov_b64_e32 v[44:45], v[12:13]
	v_mov_b64_e32 v[42:43], v[10:11]
	v_mov_b64_e32 v[40:41], v[8:9]
	v_mov_b64_e32 v[38:39], v[6:7]
	v_mov_b64_e32 v[36:37], v[4:5]
	v_mov_b64_e32 v[34:35], v[2:3]
	v_mov_b64_e32 v[62:63], v[14:15]
	v_mov_b64_e32 v[60:61], v[12:13]
	v_mov_b64_e32 v[58:59], v[10:11]
	v_mov_b64_e32 v[56:57], v[8:9]
	v_mov_b64_e32 v[54:55], v[6:7]
	v_mov_b64_e32 v[52:53], v[4:5]
	v_mov_b64_e32 v[50:51], v[2:3]
	s_branch .LBB0_1841
